# v3 + GEMM K-loops: the barrier ahead of each MFMA segment moved behind its 8th MFMA (pipe fed across the hand-off)
# speedup vs baseline: 1.0062x; 1.0050x over previous
; #define PG8_STAGE(bufoff, gbase, voff) do { _Pragma("unroll") for (int _i = 0; _i < 2; ++_i) \
;         __builtin_amdgcn_global_load_lds((const unsigned*)((const char*)(gbase) + (voff)[_i]), (LAS unsigned*)(lds + (bufoff) + ldsw + _i * 8192), 16, 0, 0); } while (0)
; #define PG8_LDA(dst, b, h) do { _Pragma("unroll") for (int m = 0; m < 4; ++m) _Pragma("unroll") for (int k = 0; k < 2; ++k) dst[m][k] = *(const LAS bf16x8*)(lds + PG8_SA(b, h) + aoff + m * 2048 + k * 1024); } while (0)
; #define PG8_LDB(dst, b, h) do { _Pragma("unroll") for (int n = 0; n < 2; ++n) _Pragma("unroll") for (int k = 0; k < 2; ++k) dst[n][k] = *(const LAS bf16x8*)(lds + PG8_SB(b, h) + boff + n * 2048 + k * 1024); } while (0)
; #define PG8_MMA(ai, bj, At, Bt) do { __builtin_amdgcn_s_setprio(1); _Pragma("unroll") for (int m = 0; m < 4; ++m) _Pragma("unroll") for (int n = 0; n < 2; ++n) _Pragma("unroll") for (int k = 0; k < 2; ++k) \
;         acc[ai][bj][m][n] = __builtin_amdgcn_mfma_f32_16x16x32_bf16(Bt[n][k], At[m][k], acc[ai][bj][m][n], 0, 0, 0); __builtin_amdgcn_s_setprio(0); } while (0)
; #define PG8_WAIT_V(n) asm volatile("s_waitcnt vmcnt(" #n ")" ::: "memory")
; #define PG8_WAIT_L(n) asm volatile("s_waitcnt lgkmcnt(" #n ")" ::: "memory")
; #define PG8_BAR __builtin_amdgcn_s_barrier()
; #define PG8_SCHED __builtin_amdgcn_sched_barrier(0)
; template <class Epi, class Sched>
; __device__ __forceinline__ void gemm_phase(int wv, LAS unsigned char* lds, const Gemm g, const Sched& S, const Epi& E) {
;     ...
;         for (int t = 0; t < nt; t += 2) {
;             const bool last = (t == nt - 2);
;             const char* a1 = cA + (size_t)(t + 1) * kstep;
;             const char* a2 = last ? nA : cA + (size_t)(t + 2) * kstep; const char* b2 = last ? nB : cB + (size_t)(t + 2) * kstep;
;             const char* a3 = a2 + kstep; const char* b3 = b2 + kstep;
;             PG8_LDB(B0, 0, 0); PG8_LDB(B1, 0, 1); PG8_SCHED; PG8_LDA(At, 0, 0); PG8_STAGE(PG8_SA(1, 1), a1 + hstep, voffA);
;             PG8_WAIT_V(8); PG8_WAIT_L(0); PG8_BAR; PG8_MMA(0, 0, At, B0); PG8_MMA(0, 1, At, B1); PG8_BAR; PG8_SCHED;
;             PG8_LDA(At, 0, 1); PG8_STAGE(PG8_SB(0, 0), b2, voffB); PG8_STAGE(PG8_SB(0, 1), b2 + hstepB, voffB); PG8_STAGE(PG8_SA(0, 0), a2, voffA);
;             PG8_WAIT_V(8); PG8_WAIT_L(0); PG8_BAR; PG8_MMA(1, 0, At, B0); PG8_MMA(1, 1, At, B1); PG8_BAR; PG8_SCHED;
.LBB0_178:
	s_add_u32 s20, s18, 0xfffc0080
	s_addc_u32 s21, s19, -1
	s_add_i32 s47, 0, 0x10000
	s_cmp_eq_u32 s46, 12
	s_cselect_b32 s23, s11, s21
	s_cselect_b32 s22, s41, s20
	s_cselect_b32 s21, s13, s45
	s_cselect_b32 s20, s42, s43
	s_add_i32 s50, 0, 0x14000
	v_add_u32_e32 v154, s47, v143
	v_add_u32_e32 v170, s50, v143
	ds_read_b128 v[138:141], v154
	ds_read_b128 v[146:149], v154 offset:1024
	ds_read_b128 v[150:153], v154 offset:2048
	ds_read_b128 v[154:157], v154 offset:3072
	ds_read_b128 v[158:161], v170
	ds_read_b128 v[162:165], v170 offset:1024
	ds_read_b128 v[166:169], v170 offset:2048
	ds_read_b128 v[170:173], v170 offset:3072
	v_lshl_add_u64 v[186:187], s[18:19], 0, v[134:135]
	s_add_i32 m0, s29, 0xc000
	ds_read_b128 v[174:177], v145
	ds_read_b128 v[178:181], v145 offset:1024
	ds_read_b128 v[182:185], v145 offset:2048
	ds_read_b128 v[198:201], v145 offset:3072
	ds_read_b128 v[202:205], v145 offset:4096
	ds_read_b128 v[206:209], v145 offset:5120
	ds_read_b128 v[210:213], v145 offset:6144
	ds_read_b128 v[214:217], v145 offset:7168
	global_load_lds_dwordx4 v[186:187], off
	v_lshl_add_u64 v[186:187], s[18:19], 0, v[136:137]
	s_add_i32 m0, s29, 0xe000
	s_nop 0
	global_load_lds_dwordx4 v[186:187], off
	s_waitcnt vmcnt(8)
	s_waitcnt lgkmcnt(0)
	s_setprio 1
	s_waitcnt lgkmcnt(0)
	v_mfma_f32_16x16x32_bf16 v[124:127], v[138:141], v[174:177], v[124:127]
	v_mfma_f32_16x16x32_bf16 v[120:123], v[150:153], v[174:177], v[120:123]
	v_mfma_f32_16x16x32_bf16 v[108:111], v[138:141], v[182:185], v[108:111]
	v_mfma_f32_16x16x32_bf16 v[100:103], v[150:153], v[182:185], v[100:103]
	v_mfma_f32_16x16x32_bf16 v[92:95], v[138:141], v[202:205], v[92:95]
	v_mfma_f32_16x16x32_bf16 v[84:87], v[150:153], v[202:205], v[84:87]
	v_mfma_f32_16x16x32_bf16 v[76:79], v[138:141], v[210:213], v[76:79]
	v_mfma_f32_16x16x32_bf16 v[68:71], v[150:153], v[210:213], v[68:71]
	s_barrier
	v_mfma_f32_16x16x32_bf16 v[124:127], v[146:149], v[178:181], v[124:127]
	v_mfma_f32_16x16x32_bf16 v[120:123], v[154:157], v[178:181], v[120:123]
	v_mfma_f32_16x16x32_bf16 v[108:111], v[146:149], v[198:201], v[108:111]
	v_mfma_f32_16x16x32_bf16 v[100:103], v[154:157], v[198:201], v[100:103]
	v_mfma_f32_16x16x32_bf16 v[92:95], v[146:149], v[206:209], v[92:95]
	v_mfma_f32_16x16x32_bf16 v[84:87], v[154:157], v[206:209], v[84:87]
	v_mfma_f32_16x16x32_bf16 v[76:79], v[146:149], v[214:217], v[76:79]
	v_mfma_f32_16x16x32_bf16 v[68:71], v[154:157], v[214:217], v[68:71]
	s_setprio 0
	s_setprio 1
	v_mfma_f32_16x16x32_bf16 v[116:119], v[158:161], v[174:177], v[116:119]
	v_mfma_f32_16x16x32_bf16 v[112:115], v[166:169], v[174:177], v[112:115]
	v_mfma_f32_16x16x32_bf16 v[104:107], v[158:161], v[182:185], v[104:107]
	v_mfma_f32_16x16x32_bf16 v[96:99], v[166:169], v[182:185], v[96:99]
	v_mfma_f32_16x16x32_bf16 v[88:91], v[158:161], v[202:205], v[88:91]
	v_mfma_f32_16x16x32_bf16 v[80:83], v[166:169], v[202:205], v[80:83]
	v_mfma_f32_16x16x32_bf16 v[72:75], v[158:161], v[210:213], v[72:75]
	v_mfma_f32_16x16x32_bf16 v[64:67], v[166:169], v[210:213], v[64:67]
	v_mfma_f32_16x16x32_bf16 v[116:119], v[162:165], v[178:181], v[116:119]
	v_mfma_f32_16x16x32_bf16 v[112:115], v[170:173], v[178:181], v[112:115]
	v_mfma_f32_16x16x32_bf16 v[104:107], v[162:165], v[198:201], v[104:107]
	v_mfma_f32_16x16x32_bf16 v[96:99], v[170:173], v[198:201], v[96:99]
	v_mfma_f32_16x16x32_bf16 v[88:91], v[162:165], v[206:209], v[88:91]
	v_mfma_f32_16x16x32_bf16 v[80:83], v[170:173], v[206:209], v[80:83]
	v_mfma_f32_16x16x32_bf16 v[72:75], v[162:165], v[214:217], v[72:75]
	v_mfma_f32_16x16x32_bf16 v[64:67], v[170:173], v[214:217], v[64:67]
	s_setprio 0
	s_barrier
	s_add_i32 s47, s47, s28
	v_lshl_add_u64 v[186:187], s[20:21], 0, v[188:189]
	s_mov_b32 m0, s47
	ds_read_b128 v[174:177], v145 offset:16384
	ds_read_b128 v[178:181], v145 offset:17408
	ds_read_b128 v[182:185], v145 offset:18432
	ds_read_b128 v[198:201], v145 offset:19456
	ds_read_b128 v[202:205], v145 offset:20480
	ds_read_b128 v[206:209], v145 offset:21504
	ds_read_b128 v[210:213], v145 offset:22528
	ds_read_b128 v[214:217], v145 offset:23552
	global_load_lds_dwordx4 v[186:187], off
	s_add_i32 m0, s47, 0x2000
	s_add_u32 s48, s20, 0x40000
	v_lshl_add_u64 v[218:219], s[20:21], 0, v[128:129]
	s_addc_u32 s49, s21, 0
	s_add_i32 s47, s50, s28
	global_load_lds_dwordx4 v[218:219], off
	v_lshl_add_u64 v[220:221], s[48:49], 0, v[188:189]
	s_mov_b32 m0, s47
	v_lshl_add_u64 v[222:223], s[22:23], 0, v[130:131]
	global_load_lds_dwordx4 v[220:221], off
	v_lshl_add_u64 v[220:221], s[48:49], 0, v[128:129]
	s_add_i32 m0, s47, 0x2000
	s_nop 0
	global_load_lds_dwordx4 v[220:221], off
	v_lshl_add_u64 v[220:221], s[22:23], 0, v[132:133]
	s_mov_b32 m0, s29
	s_nop 0
	global_load_lds_dwordx4 v[220:221], off
	s_mov_b32 m0, s30
	s_nop 0
	global_load_lds_dwordx4 v[222:223], off
	s_waitcnt vmcnt(8)
	s_waitcnt lgkmcnt(0)
	s_setprio 1
	s_waitcnt lgkmcnt(0)
	v_mfma_f32_16x16x32_bf16 v[60:63], v[138:141], v[174:177], v[60:63]
	v_mfma_f32_16x16x32_bf16 v[52:55], v[150:153], v[174:177], v[52:55]
	v_mfma_f32_16x16x32_bf16 v[44:47], v[138:141], v[182:185], v[44:47]
	v_mfma_f32_16x16x32_bf16 v[36:39], v[150:153], v[182:185], v[36:39]
	v_mfma_f32_16x16x32_bf16 v[28:31], v[138:141], v[202:205], v[28:31]
	v_mfma_f32_16x16x32_bf16 v[20:23], v[150:153], v[202:205], v[20:23]
	v_mfma_f32_16x16x32_bf16 v[12:15], v[138:141], v[210:213], v[12:15]
	v_mfma_f32_16x16x32_bf16 v[4:7], v[150:153], v[210:213], v[4:7]
	s_barrier
; #define PG8_STAGE(bufoff, gbase, voff) do { _Pragma("unroll") for (int _i = 0; _i < 2; ++_i) \
;         __builtin_amdgcn_global_load_lds((const unsigned*)((const char*)(gbase) + (voff)[_i]), (LAS unsigned*)(lds + (bufoff) + ldsw + _i * 8192), 16, 0, 0); } while (0)
; #define PG8_LDA(dst, b, h) do { _Pragma("unroll") for (int m = 0; m < 4; ++m) _Pragma("unroll") for (int k = 0; k < 2; ++k) dst[m][k] = *(const LAS bf16x8*)(lds + PG8_SA(b, h) + aoff + m * 2048 + k * 1024); } while (0)
; #define PG8_LDB(dst, b, h) do { _Pragma("unroll") for (int n = 0; n < 2; ++n) _Pragma("unroll") for (int k = 0; k < 2; ++k) dst[n][k] = *(const LAS bf16x8*)(lds + PG8_SB(b, h) + boff + n * 2048 + k * 1024); } while (0)
; #define PG8_MMA(ai, bj, At, Bt) do { __builtin_amdgcn_s_setprio(1); _Pragma("unroll") for (int m = 0; m < 4; ++m) _Pragma("unroll") for (int n = 0; n < 2; ++n) _Pragma("unroll") for (int k = 0; k < 2; ++k) \
;         acc[ai][bj][m][n] = __builtin_amdgcn_mfma_f32_16x16x32_bf16(Bt[n][k], At[m][k], acc[ai][bj][m][n], 0, 0, 0); __builtin_amdgcn_s_setprio(0); } while (0)
; #define PG8_WAIT_V(n) asm volatile("s_waitcnt vmcnt(" #n ")" ::: "memory")
; #define PG8_WAIT_L(n) asm volatile("s_waitcnt lgkmcnt(" #n ")" ::: "memory")
; #define PG8_BAR __builtin_amdgcn_s_barrier()
; #define PG8_SCHED __builtin_amdgcn_sched_barrier(0)
; template <class Epi, class Sched>
; __device__ __forceinline__ void gemm_phase(int wv, LAS unsigned char* lds, const Gemm g, const Sched& S, const Epi& E) {
;     ...
;             PG8_WAIT_V(8); PG8_WAIT_L(0); PG8_BAR; PG8_MMA(1, 0, At, B0); PG8_MMA(1, 1, At, B1); PG8_BAR; PG8_SCHED;
;             PG8_LDB(B0, 1, 0); PG8_LDB(B1, 1, 1); PG8_SCHED; PG8_LDA(At, 1, 0); PG8_STAGE(PG8_SA(0, 1), a2 + hstep, voffA);
;             PG8_WAIT_V(8); PG8_WAIT_L(0); PG8_BAR; PG8_MMA(0, 0, At, B0); PG8_MMA(0, 1, At, B1); PG8_BAR; PG8_SCHED;
	v_mfma_f32_16x16x32_bf16 v[60:63], v[146:149], v[178:181], v[60:63]
	v_mfma_f32_16x16x32_bf16 v[52:55], v[154:157], v[178:181], v[52:55]
	v_mfma_f32_16x16x32_bf16 v[44:47], v[146:149], v[198:201], v[44:47]
	v_mfma_f32_16x16x32_bf16 v[36:39], v[154:157], v[198:201], v[36:39]
	v_mfma_f32_16x16x32_bf16 v[28:31], v[146:149], v[206:209], v[28:31]
	v_mfma_f32_16x16x32_bf16 v[20:23], v[154:157], v[206:209], v[20:23]
	v_mfma_f32_16x16x32_bf16 v[12:15], v[146:149], v[214:217], v[12:15]
	v_mfma_f32_16x16x32_bf16 v[4:7], v[154:157], v[214:217], v[4:7]
	s_setprio 0
	s_setprio 1
	v_mfma_f32_16x16x32_bf16 v[56:59], v[158:161], v[174:177], v[56:59]
	v_mfma_f32_16x16x32_bf16 v[48:51], v[166:169], v[174:177], v[48:51]
	v_mfma_f32_16x16x32_bf16 v[40:43], v[158:161], v[182:185], v[40:43]
	v_mfma_f32_16x16x32_bf16 v[32:35], v[166:169], v[182:185], v[32:35]
	v_mfma_f32_16x16x32_bf16 v[24:27], v[158:161], v[202:205], v[24:27]
	v_mfma_f32_16x16x32_bf16 v[16:19], v[166:169], v[202:205], v[16:19]
	v_mfma_f32_16x16x32_bf16 v[8:11], v[158:161], v[210:213], v[8:11]
	v_mfma_f32_16x16x32_bf16 v[0:3], v[166:169], v[210:213], v[0:3]
	v_mfma_f32_16x16x32_bf16 v[56:59], v[162:165], v[178:181], v[56:59]
	v_mfma_f32_16x16x32_bf16 v[48:51], v[170:173], v[178:181], v[48:51]
	v_mfma_f32_16x16x32_bf16 v[40:43], v[162:165], v[198:201], v[40:43]
	v_mfma_f32_16x16x32_bf16 v[32:35], v[170:173], v[198:201], v[32:35]
	v_mfma_f32_16x16x32_bf16 v[24:27], v[162:165], v[206:209], v[24:27]
	v_mfma_f32_16x16x32_bf16 v[16:19], v[170:173], v[206:209], v[16:19]
	v_mfma_f32_16x16x32_bf16 v[8:11], v[162:165], v[214:217], v[8:11]
	v_mfma_f32_16x16x32_bf16 v[0:3], v[170:173], v[214:217], v[0:3]
	s_setprio 0
	s_barrier
	s_add_i32 s47, 0, 0x18000
	s_add_i32 s48, 0, 0x1c000
	v_add_u32_e32 v154, s47, v143
	v_add_u32_e32 v170, s48, v143
	ds_read_b128 v[138:141], v154
	ds_read_b128 v[146:149], v154 offset:1024
	ds_read_b128 v[150:153], v154 offset:2048
	ds_read_b128 v[154:157], v154 offset:3072
	ds_read_b128 v[158:161], v170
	ds_read_b128 v[162:165], v170 offset:1024
	ds_read_b128 v[166:169], v170 offset:2048
	ds_read_b128 v[170:173], v170 offset:3072
	s_add_u32 s22, s22, 0x40000
	s_addc_u32 s23, s23, 0
	s_mov_b32 m0, s31
	v_lshl_add_u64 v[228:229], s[22:23], 0, v[132:133]
	ds_read_b128 v[174:177], v145 offset:32768
	ds_read_b128 v[178:181], v145 offset:33792
	ds_read_b128 v[182:185], v145 offset:34816
	ds_read_b128 v[198:201], v145 offset:35840
	ds_read_b128 v[202:205], v145 offset:36864
	ds_read_b128 v[206:209], v145 offset:37888
	ds_read_b128 v[210:213], v145 offset:38912
	ds_read_b128 v[214:217], v145 offset:39936
	global_load_lds_dwordx4 v[228:229], off
	v_lshl_add_u64 v[228:229], s[22:23], 0, v[130:131]
	s_mov_b32 m0, s36
	s_nop 0
	global_load_lds_dwordx4 v[228:229], off
	s_waitcnt vmcnt(8)
	s_waitcnt lgkmcnt(0)
	s_setprio 1
	s_waitcnt lgkmcnt(0)
	v_mfma_f32_16x16x32_bf16 v[124:127], v[138:141], v[174:177], v[124:127]
	v_mfma_f32_16x16x32_bf16 v[120:123], v[150:153], v[174:177], v[120:123]
	v_mfma_f32_16x16x32_bf16 v[108:111], v[138:141], v[182:185], v[108:111]
	v_mfma_f32_16x16x32_bf16 v[100:103], v[150:153], v[182:185], v[100:103]
	v_mfma_f32_16x16x32_bf16 v[92:95], v[138:141], v[202:205], v[92:95]
	v_mfma_f32_16x16x32_bf16 v[84:87], v[150:153], v[202:205], v[84:87]
	v_mfma_f32_16x16x32_bf16 v[76:79], v[138:141], v[210:213], v[76:79]
	v_mfma_f32_16x16x32_bf16 v[68:71], v[150:153], v[210:213], v[68:71]
	s_barrier
	v_mfma_f32_16x16x32_bf16 v[124:127], v[146:149], v[178:181], v[124:127]
	v_mfma_f32_16x16x32_bf16 v[120:123], v[154:157], v[178:181], v[120:123]
	v_mfma_f32_16x16x32_bf16 v[108:111], v[146:149], v[198:201], v[108:111]
	v_mfma_f32_16x16x32_bf16 v[100:103], v[154:157], v[198:201], v[100:103]
	v_mfma_f32_16x16x32_bf16 v[92:95], v[146:149], v[206:209], v[92:95]
	v_mfma_f32_16x16x32_bf16 v[84:87], v[154:157], v[206:209], v[84:87]
	v_mfma_f32_16x16x32_bf16 v[76:79], v[146:149], v[214:217], v[76:79]
	v_mfma_f32_16x16x32_bf16 v[68:71], v[154:157], v[214:217], v[68:71]
	s_setprio 0
	s_setprio 1
	v_mfma_f32_16x16x32_bf16 v[116:119], v[158:161], v[174:177], v[116:119]
	v_mfma_f32_16x16x32_bf16 v[112:115], v[166:169], v[174:177], v[112:115]
	v_mfma_f32_16x16x32_bf16 v[104:107], v[158:161], v[182:185], v[104:107]
	v_mfma_f32_16x16x32_bf16 v[96:99], v[166:169], v[182:185], v[96:99]
	v_mfma_f32_16x16x32_bf16 v[88:91], v[158:161], v[202:205], v[88:91]
	v_mfma_f32_16x16x32_bf16 v[80:83], v[166:169], v[202:205], v[80:83]
	v_mfma_f32_16x16x32_bf16 v[72:75], v[158:161], v[210:213], v[72:75]
	v_mfma_f32_16x16x32_bf16 v[64:67], v[166:169], v[210:213], v[64:67]
	v_mfma_f32_16x16x32_bf16 v[116:119], v[162:165], v[178:181], v[116:119]
	v_mfma_f32_16x16x32_bf16 v[112:115], v[170:173], v[178:181], v[112:115]
	v_mfma_f32_16x16x32_bf16 v[104:107], v[162:165], v[198:201], v[104:107]
	v_mfma_f32_16x16x32_bf16 v[96:99], v[170:173], v[198:201], v[96:99]
	v_mfma_f32_16x16x32_bf16 v[88:91], v[162:165], v[206:209], v[88:91]
	v_mfma_f32_16x16x32_bf16 v[80:83], v[170:173], v[206:209], v[80:83]
	v_mfma_f32_16x16x32_bf16 v[72:75], v[162:165], v[214:217], v[72:75]
	v_mfma_f32_16x16x32_bf16 v[64:67], v[170:173], v[214:217], v[64:67]
	s_setprio 0
	s_barrier
; #define PG8_STAGE(bufoff, gbase, voff) do { _Pragma("unroll") for (int _i = 0; _i < 2; ++_i) \
;         __builtin_amdgcn_global_load_lds((const unsigned*)((const char*)(gbase) + (voff)[_i]), (LAS unsigned*)(lds + (bufoff) + ldsw + _i * 8192), 16, 0, 0); } while (0)
; #define PG8_LDA(dst, b, h) do { _Pragma("unroll") for (int m = 0; m < 4; ++m) _Pragma("unroll") for (int k = 0; k < 2; ++k) dst[m][k] = *(const LAS bf16x8*)(lds + PG8_SA(b, h) + aoff + m * 2048 + k * 1024); } while (0)
; #define PG8_MMA(ai, bj, At, Bt) do { __builtin_amdgcn_s_setprio(1); _Pragma("unroll") for (int m = 0; m < 4; ++m) _Pragma("unroll") for (int n = 0; n < 2; ++n) _Pragma("unroll") for (int k = 0; k < 2; ++k) \
;         acc[ai][bj][m][n] = __builtin_amdgcn_mfma_f32_16x16x32_bf16(Bt[n][k], At[m][k], acc[ai][bj][m][n], 0, 0, 0); __builtin_amdgcn_s_setprio(0); } while (0)
; #define PG8_WAIT_V(n) asm volatile("s_waitcnt vmcnt(" #n ")" ::: "memory")
; #define PG8_WAIT_L(n) asm volatile("s_waitcnt lgkmcnt(" #n ")" ::: "memory")
; #define PG8_BAR __builtin_amdgcn_s_barrier()
; #define PG8_SCHED __builtin_amdgcn_sched_barrier(0)
; template <class Epi, class Sched>
; __device__ __forceinline__ void gemm_phase(int wv, LAS unsigned char* lds, const Gemm g, const Sched& S, const Epi& E) {
;     ...
;             PG8_LDA(At, 1, 1); PG8_STAGE(PG8_SB(1, 0), b3, voffB); PG8_STAGE(PG8_SB(1, 1), b3 + hstepB, voffB); PG8_STAGE(PG8_SA(1, 0), a3, voffA);
;             PG8_WAIT_V(8); PG8_WAIT_L(0); PG8_BAR; PG8_MMA(1, 0, At, B0); PG8_MMA(1, 1, At, B1); PG8_BAR; PG8_SCHED;
;         }
;         if (wr == 0) PG8_BAR;
	s_add_i32 s22, s47, s28
	v_lshl_add_u64 v[186:187], v[186:187], 0, s[74:75]
	s_mov_b32 m0, s22
	ds_read_b128 v[174:177], v145 offset:49152
	ds_read_b128 v[178:181], v145 offset:50176
	ds_read_b128 v[182:185], v145 offset:51200
	ds_read_b128 v[198:201], v145 offset:52224
	ds_read_b128 v[202:205], v145 offset:53248
	ds_read_b128 v[206:209], v145 offset:54272
	ds_read_b128 v[210:213], v145 offset:55296
	ds_read_b128 v[214:217], v145 offset:56320
	global_load_lds_dwordx4 v[186:187], off
	s_add_i32 m0, s22, 0x2000
	s_add_u32 s20, s20, 0x40080
	v_lshl_add_u64 v[186:187], v[218:219], 0, s[74:75]
	s_addc_u32 s21, s21, 0
	s_add_i32 s22, s48, s28
	global_load_lds_dwordx4 v[186:187], off
	v_lshl_add_u64 v[186:187], s[20:21], 0, v[188:189]
	s_mov_b32 m0, s22
	s_nop 0
	global_load_lds_dwordx4 v[186:187], off
	v_lshl_add_u64 v[186:187], s[20:21], 0, v[128:129]
	s_add_i32 m0, s22, 0x2000
	s_nop 0
	global_load_lds_dwordx4 v[186:187], off
	v_lshl_add_u64 v[186:187], v[220:221], 0, s[74:75]
	s_mov_b32 m0, s37
	s_nop 0
	global_load_lds_dwordx4 v[186:187], off
	v_lshl_add_u64 v[186:187], v[222:223], 0, s[74:75]
	s_mov_b32 m0, s38
	s_nop 0
	global_load_lds_dwordx4 v[186:187], off
	s_waitcnt vmcnt(8)
	s_waitcnt lgkmcnt(0)
	s_setprio 1
	s_waitcnt lgkmcnt(0)
	v_mfma_f32_16x16x32_bf16 v[60:63], v[138:141], v[174:177], v[60:63]
	v_mfma_f32_16x16x32_bf16 v[52:55], v[150:153], v[174:177], v[52:55]
	v_mfma_f32_16x16x32_bf16 v[44:47], v[138:141], v[182:185], v[44:47]
	v_mfma_f32_16x16x32_bf16 v[36:39], v[150:153], v[182:185], v[36:39]
	v_mfma_f32_16x16x32_bf16 v[28:31], v[138:141], v[202:205], v[28:31]
	v_mfma_f32_16x16x32_bf16 v[20:23], v[150:153], v[202:205], v[20:23]
	v_mfma_f32_16x16x32_bf16 v[12:15], v[138:141], v[210:213], v[12:15]
	v_mfma_f32_16x16x32_bf16 v[4:7], v[150:153], v[210:213], v[4:7]
	s_barrier
	v_mfma_f32_16x16x32_bf16 v[60:63], v[146:149], v[178:181], v[60:63]
	v_mfma_f32_16x16x32_bf16 v[52:55], v[154:157], v[178:181], v[52:55]
	v_mfma_f32_16x16x32_bf16 v[44:47], v[146:149], v[198:201], v[44:47]
	v_mfma_f32_16x16x32_bf16 v[36:39], v[154:157], v[198:201], v[36:39]
	v_mfma_f32_16x16x32_bf16 v[28:31], v[146:149], v[206:209], v[28:31]
	v_mfma_f32_16x16x32_bf16 v[20:23], v[154:157], v[206:209], v[20:23]
	v_mfma_f32_16x16x32_bf16 v[12:15], v[146:149], v[214:217], v[12:15]
	v_mfma_f32_16x16x32_bf16 v[4:7], v[154:157], v[214:217], v[4:7]
	s_setprio 0
	s_setprio 1
	v_mfma_f32_16x16x32_bf16 v[56:59], v[158:161], v[174:177], v[56:59]
	v_mfma_f32_16x16x32_bf16 v[48:51], v[166:169], v[174:177], v[48:51]
	v_mfma_f32_16x16x32_bf16 v[40:43], v[158:161], v[182:185], v[40:43]
	v_mfma_f32_16x16x32_bf16 v[32:35], v[166:169], v[182:185], v[32:35]
	v_mfma_f32_16x16x32_bf16 v[24:27], v[158:161], v[202:205], v[24:27]
	v_mfma_f32_16x16x32_bf16 v[16:19], v[166:169], v[202:205], v[16:19]
	v_mfma_f32_16x16x32_bf16 v[8:11], v[158:161], v[210:213], v[8:11]
	v_mfma_f32_16x16x32_bf16 v[0:3], v[166:169], v[210:213], v[0:3]
	v_mfma_f32_16x16x32_bf16 v[56:59], v[162:165], v[178:181], v[56:59]
	v_mfma_f32_16x16x32_bf16 v[48:51], v[170:173], v[178:181], v[48:51]
	v_mfma_f32_16x16x32_bf16 v[40:43], v[162:165], v[198:201], v[40:43]
	v_mfma_f32_16x16x32_bf16 v[32:35], v[170:173], v[198:201], v[32:35]
	v_mfma_f32_16x16x32_bf16 v[24:27], v[162:165], v[206:209], v[24:27]
	v_mfma_f32_16x16x32_bf16 v[16:19], v[170:173], v[206:209], v[16:19]
	v_mfma_f32_16x16x32_bf16 v[8:11], v[162:165], v[214:217], v[8:11]
	v_mfma_f32_16x16x32_bf16 v[0:3], v[170:173], v[214:217], v[0:3]
	s_setprio 0
	s_barrier
	s_add_i32 s46, s46, 2
	s_add_u32 s18, s18, 0x100
	s_addc_u32 s19, s19, 0
	s_add_u32 s43, s43, 0x100
	s_addc_u32 s45, s45, 0
	s_cmp_gt_u32 s46, 13
	s_cbranch_scc0 .LBB0_178
	s_and_b64 vcc, exec, s[8:9]
	s_cbranch_vccz .LBB0_181
	s_barrier

; #define PG8_STAGE(bufoff, gbase, voff) do { _Pragma("unroll") for (int _i = 0; _i < 2; ++_i) \
;         __builtin_amdgcn_global_load_lds((const unsigned*)((const char*)(gbase) + (voff)[_i]), (LAS unsigned*)(lds + (bufoff) + ldsw + _i * 8192), 16, 0, 0); } while (0)
; #define PG8_LDA(dst, b, h) do { _Pragma("unroll") for (int m = 0; m < 4; ++m) _Pragma("unroll") for (int k = 0; k < 2; ++k) dst[m][k] = *(const LAS bf16x8*)(lds + PG8_SA(b, h) + aoff + m * 2048 + k * 1024); } while (0)
; #define PG8_LDB(dst, b, h) do { _Pragma("unroll") for (int n = 0; n < 2; ++n) _Pragma("unroll") for (int k = 0; k < 2; ++k) dst[n][k] = *(const LAS bf16x8*)(lds + PG8_SB(b, h) + boff + n * 2048 + k * 1024); } while (0)
; #define PG8_MMA(ai, bj, At, Bt) do { __builtin_amdgcn_s_setprio(1); _Pragma("unroll") for (int m = 0; m < 4; ++m) _Pragma("unroll") for (int n = 0; n < 2; ++n) _Pragma("unroll") for (int k = 0; k < 2; ++k) \
;         acc[ai][bj][m][n] = __builtin_amdgcn_mfma_f32_16x16x32_bf16(Bt[n][k], At[m][k], acc[ai][bj][m][n], 0, 0, 0); __builtin_amdgcn_s_setprio(0); } while (0)
; #define PG8_WAIT_V(n) asm volatile("s_waitcnt vmcnt(" #n ")" ::: "memory")
; #define PG8_WAIT_L(n) asm volatile("s_waitcnt lgkmcnt(" #n ")" ::: "memory")
; #define PG8_BAR __builtin_amdgcn_s_barrier()
; #define PG8_SCHED __builtin_amdgcn_sched_barrier(0)
; template <class Epi, class Sched>
; __device__ __forceinline__ void gemm_phase(int wv, LAS unsigned char* lds, const Gemm g, const Sched& S, const Epi& E) {
;     ...
;         for (int t = 0; t < nt; t += 2) {
;             const bool last = (t == nt - 2);
;             const char* a1 = cA + (size_t)(t + 1) * kstep;
;             const char* a2 = last ? nA : cA + (size_t)(t + 2) * kstep; const char* b2 = last ? nB : cB + (size_t)(t + 2) * kstep;
;             const char* a3 = a2 + kstep; const char* b3 = b2 + kstep;
;             PG8_LDB(B0, 0, 0); PG8_LDB(B1, 0, 1); PG8_SCHED; PG8_LDA(At, 0, 0); PG8_STAGE(PG8_SA(1, 1), a1 + hstep, voffA);
;             PG8_WAIT_V(8); PG8_WAIT_L(0); PG8_BAR; PG8_MMA(0, 0, At, B0); PG8_MMA(0, 1, At, B1); PG8_BAR; PG8_SCHED;
;             PG8_LDA(At, 0, 1); PG8_STAGE(PG8_SB(0, 0), b2, voffB); PG8_STAGE(PG8_SB(0, 1), b2 + hstepB, voffB); PG8_STAGE(PG8_SA(0, 0), a2, voffA);
;             PG8_WAIT_V(8); PG8_WAIT_L(0); PG8_BAR; PG8_MMA(1, 0, At, B0); PG8_MMA(1, 1, At, B1); PG8_BAR; PG8_SCHED;
.LBB0_255:
	s_add_u32 s20, s18, 0x100
	s_addc_u32 s21, s19, 0
	s_add_i32 s49, 0, 0x10000
	s_cmp_eq_u32 s48, 40
	s_cselect_b32 s25, s5, s21
	s_cselect_b32 s24, s4, s20
	s_cselect_b32 s23, s17, s47
	s_cselect_b32 s22, s16, s46
	s_add_i32 s50, 0, 0x14000
	v_add_u32_e32 v124, s49, v240
	v_add_u32_e32 v156, s50, v240
	ds_read_b128 v[112:115], v124
	ds_read_b128 v[116:119], v124 offset:1024
	ds_read_b128 v[120:123], v124 offset:2048
	ds_read_b128 v[124:127], v124 offset:3072
	ds_read_b128 v[128:131], v156
	ds_read_b128 v[140:143], v156 offset:1024
	ds_read_b128 v[152:155], v156 offset:2048
	ds_read_b128 v[156:159], v156 offset:3072
	v_lshl_add_u64 v[212:213], s[18:19], 0, v[204:205]
	s_add_i32 m0, s31, 0xc000
	ds_read_b128 v[160:163], v244
	ds_read_b128 v[164:167], v244 offset:1024
	ds_read_b128 v[168:171], v244 offset:2048
	ds_read_b128 v[172:175], v244 offset:3072
	ds_read_b128 v[176:179], v244 offset:4096
	ds_read_b128 v[180:183], v244 offset:5120
	ds_read_b128 v[184:187], v244 offset:6144
	ds_read_b128 v[208:211], v244 offset:7168
	global_load_lds_dwordx4 v[212:213], off
	v_lshl_add_u64 v[212:213], s[18:19], 0, v[206:207]
	s_add_i32 m0, s31, 0xe000
	s_nop 0
	global_load_lds_dwordx4 v[212:213], off
	s_waitcnt vmcnt(8)
	s_waitcnt lgkmcnt(0)
	s_setprio 1
	s_waitcnt lgkmcnt(0)
	v_mfma_f32_16x16x32_bf16 v[148:151], v[112:115], v[160:163], v[148:151]
	v_mfma_f32_16x16x32_bf16 v[144:147], v[120:123], v[160:163], v[144:147]
	v_mfma_f32_16x16x32_bf16 v[108:111], v[112:115], v[168:171], v[108:111]
	v_mfma_f32_16x16x32_bf16 v[104:107], v[120:123], v[168:171], v[104:107]
	v_mfma_f32_16x16x32_bf16 v[92:95], v[112:115], v[176:179], v[92:95]
	v_mfma_f32_16x16x32_bf16 v[88:91], v[120:123], v[176:179], v[88:91]
	v_mfma_f32_16x16x32_bf16 v[76:79], v[112:115], v[184:187], v[76:79]
	v_mfma_f32_16x16x32_bf16 v[72:75], v[120:123], v[184:187], v[72:75]
	s_barrier
	v_mfma_f32_16x16x32_bf16 v[148:151], v[116:119], v[164:167], v[148:151]
	v_mfma_f32_16x16x32_bf16 v[144:147], v[124:127], v[164:167], v[144:147]
	v_mfma_f32_16x16x32_bf16 v[108:111], v[116:119], v[172:175], v[108:111]
	v_mfma_f32_16x16x32_bf16 v[104:107], v[124:127], v[172:175], v[104:107]
	v_mfma_f32_16x16x32_bf16 v[92:95], v[116:119], v[180:183], v[92:95]
	v_mfma_f32_16x16x32_bf16 v[88:91], v[124:127], v[180:183], v[88:91]
	v_mfma_f32_16x16x32_bf16 v[76:79], v[116:119], v[208:211], v[76:79]
	v_mfma_f32_16x16x32_bf16 v[72:75], v[124:127], v[208:211], v[72:75]
	s_setprio 0
	s_setprio 1
	v_mfma_f32_16x16x32_bf16 v[136:139], v[128:131], v[160:163], v[136:139]
	v_mfma_f32_16x16x32_bf16 v[132:135], v[152:155], v[160:163], v[132:135]
	v_mfma_f32_16x16x32_bf16 v[100:103], v[128:131], v[168:171], v[100:103]
	v_mfma_f32_16x16x32_bf16 v[96:99], v[152:155], v[168:171], v[96:99]
	v_mfma_f32_16x16x32_bf16 v[84:87], v[128:131], v[176:179], v[84:87]
	v_mfma_f32_16x16x32_bf16 v[80:83], v[152:155], v[176:179], v[80:83]
	v_mfma_f32_16x16x32_bf16 v[68:71], v[128:131], v[184:187], v[68:71]
	v_mfma_f32_16x16x32_bf16 v[64:67], v[152:155], v[184:187], v[64:67]
	v_mfma_f32_16x16x32_bf16 v[136:139], v[140:143], v[164:167], v[136:139]
	v_mfma_f32_16x16x32_bf16 v[132:135], v[156:159], v[164:167], v[132:135]
	v_mfma_f32_16x16x32_bf16 v[100:103], v[140:143], v[172:175], v[100:103]
	v_mfma_f32_16x16x32_bf16 v[96:99], v[156:159], v[172:175], v[96:99]
	v_mfma_f32_16x16x32_bf16 v[84:87], v[140:143], v[180:183], v[84:87]
	v_mfma_f32_16x16x32_bf16 v[80:83], v[156:159], v[180:183], v[80:83]
	v_mfma_f32_16x16x32_bf16 v[68:71], v[140:143], v[208:211], v[68:71]
	v_mfma_f32_16x16x32_bf16 v[64:67], v[156:159], v[208:211], v[64:67]
	s_setprio 0
	s_barrier
	s_add_i32 s18, s49, s30
	v_lshl_add_u64 v[212:213], s[22:23], 0, v[188:189]
	s_mov_b32 m0, s18
	ds_read_b128 v[160:163], v244 offset:16384
	ds_read_b128 v[164:167], v244 offset:17408
	ds_read_b128 v[168:171], v244 offset:18432
	ds_read_b128 v[172:175], v244 offset:19456
	ds_read_b128 v[176:179], v244 offset:20480
	ds_read_b128 v[180:183], v244 offset:21504
	ds_read_b128 v[184:187], v244 offset:22528
	ds_read_b128 v[208:211], v244 offset:23552
	global_load_lds_dwordx4 v[212:213], off
	s_add_i32 m0, s18, 0x2000
	s_add_u32 s18, s22, 0xb000
	v_lshl_add_u64 v[214:215], s[22:23], 0, v[198:199]
	s_addc_u32 s19, s23, 0
	s_add_i32 s49, s50, s30
	global_load_lds_dwordx4 v[214:215], off
	v_lshl_add_u64 v[216:217], s[18:19], 0, v[188:189]
	s_mov_b32 m0, s49
	v_lshl_add_u64 v[218:219], s[24:25], 0, v[200:201]
	global_load_lds_dwordx4 v[216:217], off
	v_lshl_add_u64 v[216:217], s[18:19], 0, v[198:199]
	s_add_i32 m0, s49, 0x2000
	s_nop 0
	global_load_lds_dwordx4 v[216:217], off
	v_lshl_add_u64 v[216:217], s[24:25], 0, v[202:203]
	s_mov_b32 m0, s31
	s_nop 0
	global_load_lds_dwordx4 v[216:217], off
	s_mov_b32 m0, s36
	s_nop 0
	global_load_lds_dwordx4 v[218:219], off
	s_waitcnt vmcnt(8)
	s_waitcnt lgkmcnt(0)
	s_setprio 1
	s_waitcnt lgkmcnt(0)
	v_mfma_f32_16x16x32_bf16 v[60:63], v[112:115], v[160:163], v[60:63]
	v_mfma_f32_16x16x32_bf16 v[56:59], v[120:123], v[160:163], v[56:59]
	v_mfma_f32_16x16x32_bf16 v[44:47], v[112:115], v[168:171], v[44:47]
	v_mfma_f32_16x16x32_bf16 v[40:43], v[120:123], v[168:171], v[40:43]
	v_mfma_f32_16x16x32_bf16 v[28:31], v[112:115], v[176:179], v[28:31]
	v_mfma_f32_16x16x32_bf16 v[24:27], v[120:123], v[176:179], v[24:27]
	v_mfma_f32_16x16x32_bf16 v[12:15], v[112:115], v[184:187], v[12:15]
	v_mfma_f32_16x16x32_bf16 v[8:11], v[120:123], v[184:187], v[8:11]
	s_barrier
; #define PG8_STAGE(bufoff, gbase, voff) do { _Pragma("unroll") for (int _i = 0; _i < 2; ++_i) \
;         __builtin_amdgcn_global_load_lds((const unsigned*)((const char*)(gbase) + (voff)[_i]), (LAS unsigned*)(lds + (bufoff) + ldsw + _i * 8192), 16, 0, 0); } while (0)
; #define PG8_LDA(dst, b, h) do { _Pragma("unroll") for (int m = 0; m < 4; ++m) _Pragma("unroll") for (int k = 0; k < 2; ++k) dst[m][k] = *(const LAS bf16x8*)(lds + PG8_SA(b, h) + aoff + m * 2048 + k * 1024); } while (0)
; #define PG8_LDB(dst, b, h) do { _Pragma("unroll") for (int n = 0; n < 2; ++n) _Pragma("unroll") for (int k = 0; k < 2; ++k) dst[n][k] = *(const LAS bf16x8*)(lds + PG8_SB(b, h) + boff + n * 2048 + k * 1024); } while (0)
; #define PG8_MMA(ai, bj, At, Bt) do { __builtin_amdgcn_s_setprio(1); _Pragma("unroll") for (int m = 0; m < 4; ++m) _Pragma("unroll") for (int n = 0; n < 2; ++n) _Pragma("unroll") for (int k = 0; k < 2; ++k) \
;         acc[ai][bj][m][n] = __builtin_amdgcn_mfma_f32_16x16x32_bf16(Bt[n][k], At[m][k], acc[ai][bj][m][n], 0, 0, 0); __builtin_amdgcn_s_setprio(0); } while (0)
; #define PG8_WAIT_V(n) asm volatile("s_waitcnt vmcnt(" #n ")" ::: "memory")
; #define PG8_WAIT_L(n) asm volatile("s_waitcnt lgkmcnt(" #n ")" ::: "memory")
; #define PG8_BAR __builtin_amdgcn_s_barrier()
; #define PG8_SCHED __builtin_amdgcn_sched_barrier(0)
; template <class Epi, class Sched>
; __device__ __forceinline__ void gemm_phase(int wv, LAS unsigned char* lds, const Gemm g, const Sched& S, const Epi& E) {
;     ...
;             PG8_WAIT_V(8); PG8_WAIT_L(0); PG8_BAR; PG8_MMA(1, 0, At, B0); PG8_MMA(1, 1, At, B1); PG8_BAR; PG8_SCHED;
;             PG8_LDB(B0, 1, 0); PG8_LDB(B1, 1, 1); PG8_SCHED; PG8_LDA(At, 1, 0); PG8_STAGE(PG8_SA(0, 1), a2 + hstep, voffA);
;             PG8_WAIT_V(8); PG8_WAIT_L(0); PG8_BAR; PG8_MMA(0, 0, At, B0); PG8_MMA(0, 1, At, B1); PG8_BAR; PG8_SCHED;
	v_mfma_f32_16x16x32_bf16 v[60:63], v[116:119], v[164:167], v[60:63]
	v_mfma_f32_16x16x32_bf16 v[56:59], v[124:127], v[164:167], v[56:59]
	v_mfma_f32_16x16x32_bf16 v[44:47], v[116:119], v[172:175], v[44:47]
	v_mfma_f32_16x16x32_bf16 v[40:43], v[124:127], v[172:175], v[40:43]
	v_mfma_f32_16x16x32_bf16 v[28:31], v[116:119], v[180:183], v[28:31]
	v_mfma_f32_16x16x32_bf16 v[24:27], v[124:127], v[180:183], v[24:27]
	v_mfma_f32_16x16x32_bf16 v[12:15], v[116:119], v[208:211], v[12:15]
	v_mfma_f32_16x16x32_bf16 v[8:11], v[124:127], v[208:211], v[8:11]
	s_setprio 0
	s_setprio 1
	v_mfma_f32_16x16x32_bf16 v[52:55], v[128:131], v[160:163], v[52:55]
	v_mfma_f32_16x16x32_bf16 v[48:51], v[152:155], v[160:163], v[48:51]
	v_mfma_f32_16x16x32_bf16 v[36:39], v[128:131], v[168:171], v[36:39]
	v_mfma_f32_16x16x32_bf16 v[32:35], v[152:155], v[168:171], v[32:35]
	v_mfma_f32_16x16x32_bf16 v[20:23], v[128:131], v[176:179], v[20:23]
	v_mfma_f32_16x16x32_bf16 v[16:19], v[152:155], v[176:179], v[16:19]
	v_mfma_f32_16x16x32_bf16 v[4:7], v[128:131], v[184:187], v[4:7]
	v_mfma_f32_16x16x32_bf16 v[0:3], v[152:155], v[184:187], v[0:3]
	v_mfma_f32_16x16x32_bf16 v[52:55], v[140:143], v[164:167], v[52:55]
	v_mfma_f32_16x16x32_bf16 v[48:51], v[156:159], v[164:167], v[48:51]
	v_mfma_f32_16x16x32_bf16 v[36:39], v[140:143], v[172:175], v[36:39]
	v_mfma_f32_16x16x32_bf16 v[32:35], v[156:159], v[172:175], v[32:35]
	v_mfma_f32_16x16x32_bf16 v[20:23], v[140:143], v[180:183], v[20:23]
	v_mfma_f32_16x16x32_bf16 v[16:19], v[156:159], v[180:183], v[16:19]
	v_mfma_f32_16x16x32_bf16 v[4:7], v[140:143], v[208:211], v[4:7]
	v_mfma_f32_16x16x32_bf16 v[0:3], v[156:159], v[208:211], v[0:3]
	s_setprio 0
	s_barrier
	s_add_i32 s49, 0, 0x18000
	s_add_i32 s50, 0, 0x1c000
	v_add_u32_e32 v124, s49, v240
	v_add_u32_e32 v156, s50, v240
	ds_read_b128 v[112:115], v124
	ds_read_b128 v[116:119], v124 offset:1024
	ds_read_b128 v[120:123], v124 offset:2048
	ds_read_b128 v[124:127], v124 offset:3072
	ds_read_b128 v[128:131], v156
	ds_read_b128 v[140:143], v156 offset:1024
	ds_read_b128 v[152:155], v156 offset:2048
	ds_read_b128 v[156:159], v156 offset:3072
	s_add_u32 s18, s24, 0xb0000
	s_addc_u32 s19, s25, 0
	s_mov_b32 m0, s37
	v_lshl_add_u64 v[220:221], s[18:19], 0, v[202:203]
	ds_read_b128 v[160:163], v244 offset:32768
	ds_read_b128 v[164:167], v244 offset:33792
	ds_read_b128 v[168:171], v244 offset:34816
	ds_read_b128 v[172:175], v244 offset:35840
	ds_read_b128 v[176:179], v244 offset:36864
	ds_read_b128 v[180:183], v244 offset:37888
	ds_read_b128 v[184:187], v244 offset:38912
	ds_read_b128 v[208:211], v244 offset:39936
	global_load_lds_dwordx4 v[220:221], off
	v_lshl_add_u64 v[220:221], s[18:19], 0, v[200:201]
	s_mov_b32 m0, s38
	s_nop 0
	global_load_lds_dwordx4 v[220:221], off
	s_waitcnt vmcnt(8)
	s_waitcnt lgkmcnt(0)
	s_setprio 1
	s_waitcnt lgkmcnt(0)
	v_mfma_f32_16x16x32_bf16 v[148:151], v[112:115], v[160:163], v[148:151]
	v_mfma_f32_16x16x32_bf16 v[144:147], v[120:123], v[160:163], v[144:147]
	v_mfma_f32_16x16x32_bf16 v[108:111], v[112:115], v[168:171], v[108:111]
	v_mfma_f32_16x16x32_bf16 v[104:107], v[120:123], v[168:171], v[104:107]
	v_mfma_f32_16x16x32_bf16 v[92:95], v[112:115], v[176:179], v[92:95]
	v_mfma_f32_16x16x32_bf16 v[88:91], v[120:123], v[176:179], v[88:91]
	v_mfma_f32_16x16x32_bf16 v[76:79], v[112:115], v[184:187], v[76:79]
	v_mfma_f32_16x16x32_bf16 v[72:75], v[120:123], v[184:187], v[72:75]
	s_barrier
	v_mfma_f32_16x16x32_bf16 v[148:151], v[116:119], v[164:167], v[148:151]
	v_mfma_f32_16x16x32_bf16 v[144:147], v[124:127], v[164:167], v[144:147]
	v_mfma_f32_16x16x32_bf16 v[108:111], v[116:119], v[172:175], v[108:111]
	v_mfma_f32_16x16x32_bf16 v[104:107], v[124:127], v[172:175], v[104:107]
	v_mfma_f32_16x16x32_bf16 v[92:95], v[116:119], v[180:183], v[92:95]
	v_mfma_f32_16x16x32_bf16 v[88:91], v[124:127], v[180:183], v[88:91]
	v_mfma_f32_16x16x32_bf16 v[76:79], v[116:119], v[208:211], v[76:79]
	v_mfma_f32_16x16x32_bf16 v[72:75], v[124:127], v[208:211], v[72:75]
	s_setprio 0
	s_setprio 1
	v_mfma_f32_16x16x32_bf16 v[136:139], v[128:131], v[160:163], v[136:139]
	v_mfma_f32_16x16x32_bf16 v[132:135], v[152:155], v[160:163], v[132:135]
	v_mfma_f32_16x16x32_bf16 v[100:103], v[128:131], v[168:171], v[100:103]
	v_mfma_f32_16x16x32_bf16 v[96:99], v[152:155], v[168:171], v[96:99]
	v_mfma_f32_16x16x32_bf16 v[84:87], v[128:131], v[176:179], v[84:87]
	v_mfma_f32_16x16x32_bf16 v[80:83], v[152:155], v[176:179], v[80:83]
	v_mfma_f32_16x16x32_bf16 v[68:71], v[128:131], v[184:187], v[68:71]
	v_mfma_f32_16x16x32_bf16 v[64:67], v[152:155], v[184:187], v[64:67]
	v_mfma_f32_16x16x32_bf16 v[136:139], v[140:143], v[164:167], v[136:139]
	v_mfma_f32_16x16x32_bf16 v[132:135], v[156:159], v[164:167], v[132:135]
	v_mfma_f32_16x16x32_bf16 v[100:103], v[140:143], v[172:175], v[100:103]
	v_mfma_f32_16x16x32_bf16 v[96:99], v[156:159], v[172:175], v[96:99]
	v_mfma_f32_16x16x32_bf16 v[84:87], v[140:143], v[180:183], v[84:87]
	v_mfma_f32_16x16x32_bf16 v[80:83], v[156:159], v[180:183], v[80:83]
	v_mfma_f32_16x16x32_bf16 v[68:71], v[140:143], v[208:211], v[68:71]
	v_mfma_f32_16x16x32_bf16 v[64:67], v[156:159], v[208:211], v[64:67]
	s_setprio 0
	s_barrier
; #define PG8_STAGE(bufoff, gbase, voff) do { _Pragma("unroll") for (int _i = 0; _i < 2; ++_i) \
;         __builtin_amdgcn_global_load_lds((const unsigned*)((const char*)(gbase) + (voff)[_i]), (LAS unsigned*)(lds + (bufoff) + ldsw + _i * 8192), 16, 0, 0); } while (0)
; #define PG8_LDA(dst, b, h) do { _Pragma("unroll") for (int m = 0; m < 4; ++m) _Pragma("unroll") for (int k = 0; k < 2; ++k) dst[m][k] = *(const LAS bf16x8*)(lds + PG8_SA(b, h) + aoff + m * 2048 + k * 1024); } while (0)
; #define PG8_MMA(ai, bj, At, Bt) do { __builtin_amdgcn_s_setprio(1); _Pragma("unroll") for (int m = 0; m < 4; ++m) _Pragma("unroll") for (int n = 0; n < 2; ++n) _Pragma("unroll") for (int k = 0; k < 2; ++k) \
;         acc[ai][bj][m][n] = __builtin_amdgcn_mfma_f32_16x16x32_bf16(Bt[n][k], At[m][k], acc[ai][bj][m][n], 0, 0, 0); __builtin_amdgcn_s_setprio(0); } while (0)
; #define PG8_WAIT_V(n) asm volatile("s_waitcnt vmcnt(" #n ")" ::: "memory")
; #define PG8_WAIT_L(n) asm volatile("s_waitcnt lgkmcnt(" #n ")" ::: "memory")
; #define PG8_BAR __builtin_amdgcn_s_barrier()
; #define PG8_SCHED __builtin_amdgcn_sched_barrier(0)
; template <class Epi, class Sched>
; __device__ __forceinline__ void gemm_phase(int wv, LAS unsigned char* lds, const Gemm g, const Sched& S, const Epi& E) {
;     ...
;             PG8_LDA(At, 1, 1); PG8_STAGE(PG8_SB(1, 0), b3, voffB); PG8_STAGE(PG8_SB(1, 1), b3 + hstepB, voffB); PG8_STAGE(PG8_SA(1, 0), a3, voffA);
;             PG8_WAIT_V(8); PG8_WAIT_L(0); PG8_BAR; PG8_MMA(1, 0, At, B0); PG8_MMA(1, 1, At, B1); PG8_BAR; PG8_SCHED;
;         }
;         if (wr == 0) PG8_BAR;
	s_add_i32 s18, s49, s30
	v_lshl_add_u64 v[212:213], v[212:213], 0, s[74:75]
	s_mov_b32 m0, s18
	ds_read_b128 v[160:163], v244 offset:49152
	ds_read_b128 v[164:167], v244 offset:50176
	ds_read_b128 v[168:171], v244 offset:51200
	ds_read_b128 v[172:175], v244 offset:52224
	ds_read_b128 v[176:179], v244 offset:53248
	ds_read_b128 v[180:183], v244 offset:54272
	ds_read_b128 v[184:187], v244 offset:55296
	ds_read_b128 v[208:211], v244 offset:56320
	global_load_lds_dwordx4 v[212:213], off
	s_add_i32 m0, s18, 0x2000
	s_add_u32 s18, s22, 0xb080
	v_lshl_add_u64 v[212:213], v[214:215], 0, s[74:75]
	s_addc_u32 s19, s23, 0
	s_add_i32 s22, s50, s30
	global_load_lds_dwordx4 v[212:213], off
	v_lshl_add_u64 v[212:213], s[18:19], 0, v[188:189]
	s_mov_b32 m0, s22
	s_nop 0
	global_load_lds_dwordx4 v[212:213], off
	v_lshl_add_u64 v[212:213], s[18:19], 0, v[198:199]
	s_add_i32 m0, s22, 0x2000
	s_nop 0
	global_load_lds_dwordx4 v[212:213], off
	v_lshl_add_u64 v[212:213], v[216:217], 0, s[74:75]
	s_mov_b32 m0, s39
	s_nop 0
	global_load_lds_dwordx4 v[212:213], off
	v_lshl_add_u64 v[212:213], v[218:219], 0, s[74:75]
	s_mov_b32 m0, s40
	s_nop 0
	global_load_lds_dwordx4 v[212:213], off
	s_waitcnt vmcnt(8)
	s_waitcnt lgkmcnt(0)
	s_setprio 1
	s_waitcnt lgkmcnt(0)
	v_mfma_f32_16x16x32_bf16 v[60:63], v[112:115], v[160:163], v[60:63]
	v_mfma_f32_16x16x32_bf16 v[56:59], v[120:123], v[160:163], v[56:59]
	v_mfma_f32_16x16x32_bf16 v[44:47], v[112:115], v[168:171], v[44:47]
	v_mfma_f32_16x16x32_bf16 v[40:43], v[120:123], v[168:171], v[40:43]
	v_mfma_f32_16x16x32_bf16 v[28:31], v[112:115], v[176:179], v[28:31]
	v_mfma_f32_16x16x32_bf16 v[24:27], v[120:123], v[176:179], v[24:27]
	v_mfma_f32_16x16x32_bf16 v[12:15], v[112:115], v[184:187], v[12:15]
	v_mfma_f32_16x16x32_bf16 v[8:11], v[120:123], v[184:187], v[8:11]
	s_barrier
	v_mfma_f32_16x16x32_bf16 v[60:63], v[116:119], v[164:167], v[60:63]
	v_mfma_f32_16x16x32_bf16 v[56:59], v[124:127], v[164:167], v[56:59]
	v_mfma_f32_16x16x32_bf16 v[44:47], v[116:119], v[172:175], v[44:47]
	v_mfma_f32_16x16x32_bf16 v[40:43], v[124:127], v[172:175], v[40:43]
	v_mfma_f32_16x16x32_bf16 v[28:31], v[116:119], v[180:183], v[28:31]
	v_mfma_f32_16x16x32_bf16 v[24:27], v[124:127], v[180:183], v[24:27]
	v_mfma_f32_16x16x32_bf16 v[12:15], v[116:119], v[208:211], v[12:15]
	v_mfma_f32_16x16x32_bf16 v[8:11], v[124:127], v[208:211], v[8:11]
	s_setprio 0
	s_setprio 1
	v_mfma_f32_16x16x32_bf16 v[52:55], v[128:131], v[160:163], v[52:55]
	v_mfma_f32_16x16x32_bf16 v[48:51], v[152:155], v[160:163], v[48:51]
	v_mfma_f32_16x16x32_bf16 v[36:39], v[128:131], v[168:171], v[36:39]
	v_mfma_f32_16x16x32_bf16 v[32:35], v[152:155], v[168:171], v[32:35]
	v_mfma_f32_16x16x32_bf16 v[20:23], v[128:131], v[176:179], v[20:23]
	v_mfma_f32_16x16x32_bf16 v[16:19], v[152:155], v[176:179], v[16:19]
	v_mfma_f32_16x16x32_bf16 v[4:7], v[128:131], v[184:187], v[4:7]
	v_mfma_f32_16x16x32_bf16 v[0:3], v[152:155], v[184:187], v[0:3]
	v_mfma_f32_16x16x32_bf16 v[52:55], v[140:143], v[164:167], v[52:55]
	v_mfma_f32_16x16x32_bf16 v[48:51], v[156:159], v[164:167], v[48:51]
	v_mfma_f32_16x16x32_bf16 v[36:39], v[140:143], v[172:175], v[36:39]
	v_mfma_f32_16x16x32_bf16 v[32:35], v[156:159], v[172:175], v[32:35]
	v_mfma_f32_16x16x32_bf16 v[20:23], v[140:143], v[180:183], v[20:23]
	v_mfma_f32_16x16x32_bf16 v[16:19], v[156:159], v[180:183], v[16:19]
	v_mfma_f32_16x16x32_bf16 v[4:7], v[140:143], v[208:211], v[4:7]
	v_mfma_f32_16x16x32_bf16 v[0:3], v[156:159], v[208:211], v[0:3]
	s_setprio 0
	s_barrier
	s_add_i32 s48, s48, 2
	s_add_u32 s46, s46, 0x100
	s_addc_u32 s47, s47, 0
	s_cmp_gt_u32 s48, 41
	s_mov_b64 s[18:19], s[20:21]
	s_cbranch_scc0 .LBB0_255
	s_and_b64 vcc, exec, s[14:15]
	s_cbranch_vccz .LBB0_258
	s_barrier

; #define PG8_STAGE(bufoff, gbase, voff) do { _Pragma("unroll") for (int _i = 0; _i < 2; ++_i) \
;         __builtin_amdgcn_global_load_lds((const unsigned*)((const char*)(gbase) + (voff)[_i]), (LAS unsigned*)(lds + (bufoff) + ldsw + _i * 8192), 16, 0, 0); } while (0)
; #define PG8_LDA(dst, b, h) do { _Pragma("unroll") for (int m = 0; m < 4; ++m) _Pragma("unroll") for (int k = 0; k < 2; ++k) dst[m][k] = *(const LAS bf16x8*)(lds + PG8_SA(b, h) + aoff + m * 2048 + k * 1024); } while (0)
; #define PG8_LDB(dst, b, h) do { _Pragma("unroll") for (int n = 0; n < 2; ++n) _Pragma("unroll") for (int k = 0; k < 2; ++k) dst[n][k] = *(const LAS bf16x8*)(lds + PG8_SB(b, h) + boff + n * 2048 + k * 1024); } while (0)
; #define PG8_MMA(ai, bj, At, Bt) do { __builtin_amdgcn_s_setprio(1); _Pragma("unroll") for (int m = 0; m < 4; ++m) _Pragma("unroll") for (int n = 0; n < 2; ++n) _Pragma("unroll") for (int k = 0; k < 2; ++k) \
;         acc[ai][bj][m][n] = __builtin_amdgcn_mfma_f32_16x16x32_bf16(Bt[n][k], At[m][k], acc[ai][bj][m][n], 0, 0, 0); __builtin_amdgcn_s_setprio(0); } while (0)
; #define PG8_WAIT_V(n) asm volatile("s_waitcnt vmcnt(" #n ")" ::: "memory")
; #define PG8_WAIT_L(n) asm volatile("s_waitcnt lgkmcnt(" #n ")" ::: "memory")
; #define PG8_BAR __builtin_amdgcn_s_barrier()
; #define PG8_SCHED __builtin_amdgcn_sched_barrier(0)
; template <class Epi, class Sched>
; __device__ __forceinline__ void gemm_phase(int wv, LAS unsigned char* lds, const Gemm g, const Sched& S, const Epi& E) {
;     ...
;         for (int t = 0; t < nt; t += 2) {
;             const bool last = (t == nt - 2);
;             const char* a1 = cA + (size_t)(t + 1) * kstep;
;             const char* a2 = last ? nA : cA + (size_t)(t + 2) * kstep; const char* b2 = last ? nB : cB + (size_t)(t + 2) * kstep;
;             const char* a3 = a2 + kstep; const char* b3 = b2 + kstep;
;             PG8_LDB(B0, 0, 0); PG8_LDB(B1, 0, 1); PG8_SCHED; PG8_LDA(At, 0, 0); PG8_STAGE(PG8_SA(1, 1), a1 + hstep, voffA);
;             PG8_WAIT_V(8); PG8_WAIT_L(0); PG8_BAR; PG8_MMA(0, 0, At, B0); PG8_MMA(0, 1, At, B1); PG8_BAR; PG8_SCHED;
;             PG8_LDA(At, 0, 1); PG8_STAGE(PG8_SB(0, 0), b2, voffB); PG8_STAGE(PG8_SB(0, 1), b2 + hstepB, voffB); PG8_STAGE(PG8_SA(0, 0), a2, voffA);
;             PG8_WAIT_V(8); PG8_WAIT_L(0); PG8_BAR; PG8_MMA(1, 0, At, B0); PG8_MMA(1, 1, At, B1); PG8_BAR; PG8_SCHED;
.LBB0_344:
	s_add_u32 s18, s2, 0xfffc0080
	s_addc_u32 s19, s3, -1
	s_add_i32 s47, 0, 0x10000
	s_cmp_eq_u32 s46, 12
	s_cselect_b32 s21, s11, s19
	s_cselect_b32 s20, s41, s18
	s_cselect_b32 s19, s13, s45
	s_cselect_b32 s18, s42, s43
	s_add_i32 s50, 0, 0x14000
	v_add_u32_e32 v156, s47, v145
	v_add_u32_e32 v172, s50, v145
	ds_read_b128 v[140:143], v156
	ds_read_b128 v[148:151], v156 offset:1024
	ds_read_b128 v[152:155], v156 offset:2048
	ds_read_b128 v[156:159], v156 offset:3072
	ds_read_b128 v[160:163], v172
	ds_read_b128 v[164:167], v172 offset:1024
	ds_read_b128 v[168:171], v172 offset:2048
	ds_read_b128 v[172:175], v172 offset:3072
	v_lshl_add_u64 v[218:219], s[2:3], 0, v[136:137]
	s_add_i32 m0, s27, 0xc000
	ds_read_b128 v[176:179], v147
	ds_read_b128 v[180:183], v147 offset:1024
	ds_read_b128 v[184:187], v147 offset:2048
	ds_read_b128 v[198:201], v147 offset:3072
	ds_read_b128 v[202:205], v147 offset:4096
	ds_read_b128 v[206:209], v147 offset:5120
	ds_read_b128 v[210:213], v147 offset:6144
	ds_read_b128 v[214:217], v147 offset:7168
	global_load_lds_dwordx4 v[218:219], off
	v_lshl_add_u64 v[218:219], s[2:3], 0, v[138:139]
	s_add_i32 m0, s27, 0xe000
	s_nop 0
	global_load_lds_dwordx4 v[218:219], off
	s_waitcnt vmcnt(8)
	s_waitcnt lgkmcnt(0)
	s_setprio 1
	s_waitcnt lgkmcnt(0)
	v_mfma_f32_16x16x32_bf16 v[124:127], v[140:143], v[176:179], v[124:127]
	v_mfma_f32_16x16x32_bf16 v[120:123], v[152:155], v[176:179], v[120:123]
	v_mfma_f32_16x16x32_bf16 v[108:111], v[140:143], v[184:187], v[108:111]
	v_mfma_f32_16x16x32_bf16 v[104:107], v[152:155], v[184:187], v[104:107]
	v_mfma_f32_16x16x32_bf16 v[92:95], v[140:143], v[202:205], v[92:95]
	v_mfma_f32_16x16x32_bf16 v[88:91], v[152:155], v[202:205], v[88:91]
	v_mfma_f32_16x16x32_bf16 v[76:79], v[140:143], v[210:213], v[76:79]
	v_mfma_f32_16x16x32_bf16 v[72:75], v[152:155], v[210:213], v[72:75]
	s_barrier
	v_mfma_f32_16x16x32_bf16 v[124:127], v[148:151], v[180:183], v[124:127]
	v_mfma_f32_16x16x32_bf16 v[120:123], v[156:159], v[180:183], v[120:123]
	v_mfma_f32_16x16x32_bf16 v[108:111], v[148:151], v[198:201], v[108:111]
	v_mfma_f32_16x16x32_bf16 v[104:107], v[156:159], v[198:201], v[104:107]
	v_mfma_f32_16x16x32_bf16 v[92:95], v[148:151], v[206:209], v[92:95]
	v_mfma_f32_16x16x32_bf16 v[88:91], v[156:159], v[206:209], v[88:91]
	v_mfma_f32_16x16x32_bf16 v[76:79], v[148:151], v[214:217], v[76:79]
	v_mfma_f32_16x16x32_bf16 v[72:75], v[156:159], v[214:217], v[72:75]
	s_setprio 0
	s_setprio 1
	v_mfma_f32_16x16x32_bf16 v[116:119], v[160:163], v[176:179], v[116:119]
	v_mfma_f32_16x16x32_bf16 v[112:115], v[168:171], v[176:179], v[112:115]
	v_mfma_f32_16x16x32_bf16 v[100:103], v[160:163], v[184:187], v[100:103]
	v_mfma_f32_16x16x32_bf16 v[96:99], v[168:171], v[184:187], v[96:99]
	v_mfma_f32_16x16x32_bf16 v[84:87], v[160:163], v[202:205], v[84:87]
	v_mfma_f32_16x16x32_bf16 v[80:83], v[168:171], v[202:205], v[80:83]
	v_mfma_f32_16x16x32_bf16 v[68:71], v[160:163], v[210:213], v[68:71]
	v_mfma_f32_16x16x32_bf16 v[64:67], v[168:171], v[210:213], v[64:67]
	v_mfma_f32_16x16x32_bf16 v[116:119], v[164:167], v[180:183], v[116:119]
	v_mfma_f32_16x16x32_bf16 v[112:115], v[172:175], v[180:183], v[112:115]
	v_mfma_f32_16x16x32_bf16 v[100:103], v[164:167], v[198:201], v[100:103]
	v_mfma_f32_16x16x32_bf16 v[96:99], v[172:175], v[198:201], v[96:99]
	v_mfma_f32_16x16x32_bf16 v[84:87], v[164:167], v[206:209], v[84:87]
	v_mfma_f32_16x16x32_bf16 v[80:83], v[172:175], v[206:209], v[80:83]
	v_mfma_f32_16x16x32_bf16 v[68:71], v[164:167], v[214:217], v[68:71]
	v_mfma_f32_16x16x32_bf16 v[64:67], v[172:175], v[214:217], v[64:67]
	s_setprio 0
	s_barrier
	s_add_i32 s47, s47, s26
	v_lshl_add_u64 v[218:219], s[18:19], 0, v[132:133]
	s_mov_b32 m0, s47
	ds_read_b128 v[176:179], v147 offset:16384
	ds_read_b128 v[180:183], v147 offset:17408
	ds_read_b128 v[184:187], v147 offset:18432
	ds_read_b128 v[198:201], v147 offset:19456
	ds_read_b128 v[202:205], v147 offset:20480
	ds_read_b128 v[206:209], v147 offset:21504
	ds_read_b128 v[210:213], v147 offset:22528
	ds_read_b128 v[214:217], v147 offset:23552
	global_load_lds_dwordx4 v[218:219], off
	s_add_i32 m0, s47, 0x2000
	s_add_u32 s48, s18, 0x4000
	v_lshl_add_u64 v[220:221], s[18:19], 0, v[128:129]
	s_addc_u32 s49, s19, 0
	s_add_i32 s47, s50, s26
	global_load_lds_dwordx4 v[220:221], off
	v_lshl_add_u64 v[222:223], s[48:49], 0, v[132:133]
	s_mov_b32 m0, s47
	v_lshl_add_u64 v[228:229], s[20:21], 0, v[130:131]
	global_load_lds_dwordx4 v[222:223], off
	v_lshl_add_u64 v[222:223], s[48:49], 0, v[128:129]
	s_add_i32 m0, s47, 0x2000
	s_nop 0
	global_load_lds_dwordx4 v[222:223], off
	v_lshl_add_u64 v[222:223], s[20:21], 0, v[134:135]
	s_mov_b32 m0, s27
	s_nop 0
	global_load_lds_dwordx4 v[222:223], off
	s_mov_b32 m0, s28
	s_nop 0
	global_load_lds_dwordx4 v[228:229], off
	s_waitcnt vmcnt(8)
	s_waitcnt lgkmcnt(0)
	s_setprio 1
	s_waitcnt lgkmcnt(0)
	v_mfma_f32_16x16x32_bf16 v[60:63], v[140:143], v[176:179], v[60:63]
	v_mfma_f32_16x16x32_bf16 v[56:59], v[152:155], v[176:179], v[56:59]
	v_mfma_f32_16x16x32_bf16 v[44:47], v[140:143], v[184:187], v[44:47]
	v_mfma_f32_16x16x32_bf16 v[40:43], v[152:155], v[184:187], v[40:43]
	v_mfma_f32_16x16x32_bf16 v[28:31], v[140:143], v[202:205], v[28:31]
	v_mfma_f32_16x16x32_bf16 v[24:27], v[152:155], v[202:205], v[24:27]
	v_mfma_f32_16x16x32_bf16 v[12:15], v[140:143], v[210:213], v[12:15]
	v_mfma_f32_16x16x32_bf16 v[8:11], v[152:155], v[210:213], v[8:11]
	s_barrier
; #define PG8_STAGE(bufoff, gbase, voff) do { _Pragma("unroll") for (int _i = 0; _i < 2; ++_i) \
;         __builtin_amdgcn_global_load_lds((const unsigned*)((const char*)(gbase) + (voff)[_i]), (LAS unsigned*)(lds + (bufoff) + ldsw + _i * 8192), 16, 0, 0); } while (0)
; #define PG8_LDA(dst, b, h) do { _Pragma("unroll") for (int m = 0; m < 4; ++m) _Pragma("unroll") for (int k = 0; k < 2; ++k) dst[m][k] = *(const LAS bf16x8*)(lds + PG8_SA(b, h) + aoff + m * 2048 + k * 1024); } while (0)
; #define PG8_LDB(dst, b, h) do { _Pragma("unroll") for (int n = 0; n < 2; ++n) _Pragma("unroll") for (int k = 0; k < 2; ++k) dst[n][k] = *(const LAS bf16x8*)(lds + PG8_SB(b, h) + boff + n * 2048 + k * 1024); } while (0)
; #define PG8_MMA(ai, bj, At, Bt) do { __builtin_amdgcn_s_setprio(1); _Pragma("unroll") for (int m = 0; m < 4; ++m) _Pragma("unroll") for (int n = 0; n < 2; ++n) _Pragma("unroll") for (int k = 0; k < 2; ++k) \
;         acc[ai][bj][m][n] = __builtin_amdgcn_mfma_f32_16x16x32_bf16(Bt[n][k], At[m][k], acc[ai][bj][m][n], 0, 0, 0); __builtin_amdgcn_s_setprio(0); } while (0)
; #define PG8_WAIT_V(n) asm volatile("s_waitcnt vmcnt(" #n ")" ::: "memory")
; #define PG8_WAIT_L(n) asm volatile("s_waitcnt lgkmcnt(" #n ")" ::: "memory")
; #define PG8_BAR __builtin_amdgcn_s_barrier()
; #define PG8_SCHED __builtin_amdgcn_sched_barrier(0)
; template <class Epi, class Sched>
; __device__ __forceinline__ void gemm_phase(int wv, LAS unsigned char* lds, const Gemm g, const Sched& S, const Epi& E) {
;     ...
;             PG8_WAIT_V(8); PG8_WAIT_L(0); PG8_BAR; PG8_MMA(1, 0, At, B0); PG8_MMA(1, 1, At, B1); PG8_BAR; PG8_SCHED;
;             PG8_LDB(B0, 1, 0); PG8_LDB(B1, 1, 1); PG8_SCHED; PG8_LDA(At, 1, 0); PG8_STAGE(PG8_SA(0, 1), a2 + hstep, voffA);
;             PG8_WAIT_V(8); PG8_WAIT_L(0); PG8_BAR; PG8_MMA(0, 0, At, B0); PG8_MMA(0, 1, At, B1); PG8_BAR; PG8_SCHED;
	v_mfma_f32_16x16x32_bf16 v[60:63], v[148:151], v[180:183], v[60:63]
	v_mfma_f32_16x16x32_bf16 v[56:59], v[156:159], v[180:183], v[56:59]
	v_mfma_f32_16x16x32_bf16 v[44:47], v[148:151], v[198:201], v[44:47]
	v_mfma_f32_16x16x32_bf16 v[40:43], v[156:159], v[198:201], v[40:43]
	v_mfma_f32_16x16x32_bf16 v[28:31], v[148:151], v[206:209], v[28:31]
	v_mfma_f32_16x16x32_bf16 v[24:27], v[156:159], v[206:209], v[24:27]
	v_mfma_f32_16x16x32_bf16 v[12:15], v[148:151], v[214:217], v[12:15]
	v_mfma_f32_16x16x32_bf16 v[8:11], v[156:159], v[214:217], v[8:11]
	s_setprio 0
	s_setprio 1
	v_mfma_f32_16x16x32_bf16 v[52:55], v[160:163], v[176:179], v[52:55]
	v_mfma_f32_16x16x32_bf16 v[48:51], v[168:171], v[176:179], v[48:51]
	v_mfma_f32_16x16x32_bf16 v[36:39], v[160:163], v[184:187], v[36:39]
	v_mfma_f32_16x16x32_bf16 v[32:35], v[168:171], v[184:187], v[32:35]
	v_mfma_f32_16x16x32_bf16 v[20:23], v[160:163], v[202:205], v[20:23]
	v_mfma_f32_16x16x32_bf16 v[16:19], v[168:171], v[202:205], v[16:19]
	v_mfma_f32_16x16x32_bf16 v[4:7], v[160:163], v[210:213], v[4:7]
	v_mfma_f32_16x16x32_bf16 v[0:3], v[168:171], v[210:213], v[0:3]
	v_mfma_f32_16x16x32_bf16 v[52:55], v[164:167], v[180:183], v[52:55]
	v_mfma_f32_16x16x32_bf16 v[48:51], v[172:175], v[180:183], v[48:51]
	v_mfma_f32_16x16x32_bf16 v[36:39], v[164:167], v[198:201], v[36:39]
	v_mfma_f32_16x16x32_bf16 v[32:35], v[172:175], v[198:201], v[32:35]
	v_mfma_f32_16x16x32_bf16 v[20:23], v[164:167], v[206:209], v[20:23]
	v_mfma_f32_16x16x32_bf16 v[16:19], v[172:175], v[206:209], v[16:19]
	v_mfma_f32_16x16x32_bf16 v[4:7], v[164:167], v[214:217], v[4:7]
	v_mfma_f32_16x16x32_bf16 v[0:3], v[172:175], v[214:217], v[0:3]
	s_setprio 0
	s_barrier
	s_add_i32 s47, 0, 0x18000
	s_add_i32 s48, 0, 0x1c000
	v_add_u32_e32 v156, s47, v145
	v_add_u32_e32 v172, s48, v145
	ds_read_b128 v[140:143], v156
	ds_read_b128 v[148:151], v156 offset:1024
	ds_read_b128 v[152:155], v156 offset:2048
	ds_read_b128 v[156:159], v156 offset:3072
	ds_read_b128 v[160:163], v172
	ds_read_b128 v[164:167], v172 offset:1024
	ds_read_b128 v[168:171], v172 offset:2048
	ds_read_b128 v[172:175], v172 offset:3072
	s_add_u32 s20, s20, 0x40000
	s_addc_u32 s21, s21, 0
	s_mov_b32 m0, s29
	v_lshl_add_u64 v[230:231], s[20:21], 0, v[134:135]
	ds_read_b128 v[176:179], v147 offset:32768
	ds_read_b128 v[180:183], v147 offset:33792
	ds_read_b128 v[184:187], v147 offset:34816
	ds_read_b128 v[198:201], v147 offset:35840
	ds_read_b128 v[202:205], v147 offset:36864
	ds_read_b128 v[206:209], v147 offset:37888
	ds_read_b128 v[210:213], v147 offset:38912
	ds_read_b128 v[214:217], v147 offset:39936
	global_load_lds_dwordx4 v[230:231], off
	v_lshl_add_u64 v[230:231], s[20:21], 0, v[130:131]
	s_mov_b32 m0, s30
	s_nop 0
	global_load_lds_dwordx4 v[230:231], off
	s_waitcnt vmcnt(8)
	s_waitcnt lgkmcnt(0)
	s_setprio 1
	s_waitcnt lgkmcnt(0)
	v_mfma_f32_16x16x32_bf16 v[124:127], v[140:143], v[176:179], v[124:127]
	v_mfma_f32_16x16x32_bf16 v[120:123], v[152:155], v[176:179], v[120:123]
	v_mfma_f32_16x16x32_bf16 v[108:111], v[140:143], v[184:187], v[108:111]
	v_mfma_f32_16x16x32_bf16 v[104:107], v[152:155], v[184:187], v[104:107]
	v_mfma_f32_16x16x32_bf16 v[92:95], v[140:143], v[202:205], v[92:95]
	v_mfma_f32_16x16x32_bf16 v[88:91], v[152:155], v[202:205], v[88:91]
	v_mfma_f32_16x16x32_bf16 v[76:79], v[140:143], v[210:213], v[76:79]
	v_mfma_f32_16x16x32_bf16 v[72:75], v[152:155], v[210:213], v[72:75]
	s_barrier
	v_mfma_f32_16x16x32_bf16 v[124:127], v[148:151], v[180:183], v[124:127]
	v_mfma_f32_16x16x32_bf16 v[120:123], v[156:159], v[180:183], v[120:123]
	v_mfma_f32_16x16x32_bf16 v[108:111], v[148:151], v[198:201], v[108:111]
	v_mfma_f32_16x16x32_bf16 v[104:107], v[156:159], v[198:201], v[104:107]
	v_mfma_f32_16x16x32_bf16 v[92:95], v[148:151], v[206:209], v[92:95]
	v_mfma_f32_16x16x32_bf16 v[88:91], v[156:159], v[206:209], v[88:91]
	v_mfma_f32_16x16x32_bf16 v[76:79], v[148:151], v[214:217], v[76:79]
	v_mfma_f32_16x16x32_bf16 v[72:75], v[156:159], v[214:217], v[72:75]
	s_setprio 0
	s_setprio 1
	v_mfma_f32_16x16x32_bf16 v[116:119], v[160:163], v[176:179], v[116:119]
	v_mfma_f32_16x16x32_bf16 v[112:115], v[168:171], v[176:179], v[112:115]
	v_mfma_f32_16x16x32_bf16 v[100:103], v[160:163], v[184:187], v[100:103]
	v_mfma_f32_16x16x32_bf16 v[96:99], v[168:171], v[184:187], v[96:99]
	v_mfma_f32_16x16x32_bf16 v[84:87], v[160:163], v[202:205], v[84:87]
	v_mfma_f32_16x16x32_bf16 v[80:83], v[168:171], v[202:205], v[80:83]
	v_mfma_f32_16x16x32_bf16 v[68:71], v[160:163], v[210:213], v[68:71]
	v_mfma_f32_16x16x32_bf16 v[64:67], v[168:171], v[210:213], v[64:67]
	v_mfma_f32_16x16x32_bf16 v[116:119], v[164:167], v[180:183], v[116:119]
	v_mfma_f32_16x16x32_bf16 v[112:115], v[172:175], v[180:183], v[112:115]
	v_mfma_f32_16x16x32_bf16 v[100:103], v[164:167], v[198:201], v[100:103]
	v_mfma_f32_16x16x32_bf16 v[96:99], v[172:175], v[198:201], v[96:99]
	v_mfma_f32_16x16x32_bf16 v[84:87], v[164:167], v[206:209], v[84:87]
	v_mfma_f32_16x16x32_bf16 v[80:83], v[172:175], v[206:209], v[80:83]
	v_mfma_f32_16x16x32_bf16 v[68:71], v[164:167], v[214:217], v[68:71]
	v_mfma_f32_16x16x32_bf16 v[64:67], v[172:175], v[214:217], v[64:67]
	s_setprio 0
	s_barrier
; #define PG8_STAGE(bufoff, gbase, voff) do { _Pragma("unroll") for (int _i = 0; _i < 2; ++_i) \
;         __builtin_amdgcn_global_load_lds((const unsigned*)((const char*)(gbase) + (voff)[_i]), (LAS unsigned*)(lds + (bufoff) + ldsw + _i * 8192), 16, 0, 0); } while (0)
; #define PG8_LDA(dst, b, h) do { _Pragma("unroll") for (int m = 0; m < 4; ++m) _Pragma("unroll") for (int k = 0; k < 2; ++k) dst[m][k] = *(const LAS bf16x8*)(lds + PG8_SA(b, h) + aoff + m * 2048 + k * 1024); } while (0)
; #define PG8_MMA(ai, bj, At, Bt) do { __builtin_amdgcn_s_setprio(1); _Pragma("unroll") for (int m = 0; m < 4; ++m) _Pragma("unroll") for (int n = 0; n < 2; ++n) _Pragma("unroll") for (int k = 0; k < 2; ++k) \
;         acc[ai][bj][m][n] = __builtin_amdgcn_mfma_f32_16x16x32_bf16(Bt[n][k], At[m][k], acc[ai][bj][m][n], 0, 0, 0); __builtin_amdgcn_s_setprio(0); } while (0)
; #define PG8_WAIT_V(n) asm volatile("s_waitcnt vmcnt(" #n ")" ::: "memory")
; #define PG8_WAIT_L(n) asm volatile("s_waitcnt lgkmcnt(" #n ")" ::: "memory")
; #define PG8_BAR __builtin_amdgcn_s_barrier()
; #define PG8_SCHED __builtin_amdgcn_sched_barrier(0)
; template <class Epi, class Sched>
; __device__ __forceinline__ void gemm_phase(int wv, LAS unsigned char* lds, const Gemm g, const Sched& S, const Epi& E) {
;     ...
;             PG8_LDA(At, 1, 1); PG8_STAGE(PG8_SB(1, 0), b3, voffB); PG8_STAGE(PG8_SB(1, 1), b3 + hstepB, voffB); PG8_STAGE(PG8_SA(1, 0), a3, voffA);
;             PG8_WAIT_V(8); PG8_WAIT_L(0); PG8_BAR; PG8_MMA(1, 0, At, B0); PG8_MMA(1, 1, At, B1); PG8_BAR; PG8_SCHED;
;         }
;         if (wr == 0) PG8_BAR;
	s_add_i32 s20, s47, s26
	v_lshl_add_u64 v[218:219], v[218:219], 0, s[74:75]
	s_mov_b32 m0, s20
	ds_read_b128 v[176:179], v147 offset:49152
	ds_read_b128 v[180:183], v147 offset:50176
	ds_read_b128 v[184:187], v147 offset:51200
	ds_read_b128 v[198:201], v147 offset:52224
	ds_read_b128 v[202:205], v147 offset:53248
	ds_read_b128 v[206:209], v147 offset:54272
	ds_read_b128 v[210:213], v147 offset:55296
	ds_read_b128 v[214:217], v147 offset:56320
	global_load_lds_dwordx4 v[218:219], off
	s_add_i32 m0, s20, 0x2000
	s_add_u32 s18, s18, 0x4080
	v_lshl_add_u64 v[218:219], v[220:221], 0, s[74:75]
	s_addc_u32 s19, s19, 0
	s_add_i32 s20, s48, s26
	global_load_lds_dwordx4 v[218:219], off
	v_lshl_add_u64 v[218:219], s[18:19], 0, v[132:133]
	s_mov_b32 m0, s20
	s_nop 0
	global_load_lds_dwordx4 v[218:219], off
	v_lshl_add_u64 v[218:219], s[18:19], 0, v[128:129]
	s_add_i32 m0, s20, 0x2000
	s_nop 0
	global_load_lds_dwordx4 v[218:219], off
	v_lshl_add_u64 v[218:219], v[222:223], 0, s[74:75]
	s_mov_b32 m0, s37
	s_nop 0
	global_load_lds_dwordx4 v[218:219], off
	v_lshl_add_u64 v[218:219], v[228:229], 0, s[74:75]
	s_mov_b32 m0, s38
	s_nop 0
	global_load_lds_dwordx4 v[218:219], off
	s_waitcnt vmcnt(8)
	s_waitcnt lgkmcnt(0)
	s_setprio 1
	s_waitcnt lgkmcnt(0)
	v_mfma_f32_16x16x32_bf16 v[60:63], v[140:143], v[176:179], v[60:63]
	v_mfma_f32_16x16x32_bf16 v[56:59], v[152:155], v[176:179], v[56:59]
	v_mfma_f32_16x16x32_bf16 v[44:47], v[140:143], v[184:187], v[44:47]
	v_mfma_f32_16x16x32_bf16 v[40:43], v[152:155], v[184:187], v[40:43]
	v_mfma_f32_16x16x32_bf16 v[28:31], v[140:143], v[202:205], v[28:31]
	v_mfma_f32_16x16x32_bf16 v[24:27], v[152:155], v[202:205], v[24:27]
	v_mfma_f32_16x16x32_bf16 v[12:15], v[140:143], v[210:213], v[12:15]
	v_mfma_f32_16x16x32_bf16 v[8:11], v[152:155], v[210:213], v[8:11]
	s_barrier
	v_mfma_f32_16x16x32_bf16 v[60:63], v[148:151], v[180:183], v[60:63]
	v_mfma_f32_16x16x32_bf16 v[56:59], v[156:159], v[180:183], v[56:59]
	v_mfma_f32_16x16x32_bf16 v[44:47], v[148:151], v[198:201], v[44:47]
	v_mfma_f32_16x16x32_bf16 v[40:43], v[156:159], v[198:201], v[40:43]
	v_mfma_f32_16x16x32_bf16 v[28:31], v[148:151], v[206:209], v[28:31]
	v_mfma_f32_16x16x32_bf16 v[24:27], v[156:159], v[206:209], v[24:27]
	v_mfma_f32_16x16x32_bf16 v[12:15], v[148:151], v[214:217], v[12:15]
	v_mfma_f32_16x16x32_bf16 v[8:11], v[156:159], v[214:217], v[8:11]
	s_setprio 0
	s_setprio 1
	v_mfma_f32_16x16x32_bf16 v[52:55], v[160:163], v[176:179], v[52:55]
	v_mfma_f32_16x16x32_bf16 v[48:51], v[168:171], v[176:179], v[48:51]
	v_mfma_f32_16x16x32_bf16 v[36:39], v[160:163], v[184:187], v[36:39]
	v_mfma_f32_16x16x32_bf16 v[32:35], v[168:171], v[184:187], v[32:35]
	v_mfma_f32_16x16x32_bf16 v[20:23], v[160:163], v[202:205], v[20:23]
	v_mfma_f32_16x16x32_bf16 v[16:19], v[168:171], v[202:205], v[16:19]
	v_mfma_f32_16x16x32_bf16 v[4:7], v[160:163], v[210:213], v[4:7]
	v_mfma_f32_16x16x32_bf16 v[0:3], v[168:171], v[210:213], v[0:3]
	v_mfma_f32_16x16x32_bf16 v[52:55], v[164:167], v[180:183], v[52:55]
	v_mfma_f32_16x16x32_bf16 v[48:51], v[172:175], v[180:183], v[48:51]
	v_mfma_f32_16x16x32_bf16 v[36:39], v[164:167], v[198:201], v[36:39]
	v_mfma_f32_16x16x32_bf16 v[32:35], v[172:175], v[198:201], v[32:35]
	v_mfma_f32_16x16x32_bf16 v[20:23], v[164:167], v[206:209], v[20:23]
	v_mfma_f32_16x16x32_bf16 v[16:19], v[172:175], v[206:209], v[16:19]
	v_mfma_f32_16x16x32_bf16 v[4:7], v[164:167], v[214:217], v[4:7]
	v_mfma_f32_16x16x32_bf16 v[0:3], v[172:175], v[214:217], v[0:3]
	s_setprio 0
	s_barrier
	s_add_i32 s46, s46, 2
	s_add_u32 s2, s2, 0x100
	s_addc_u32 s3, s3, 0
	s_add_u32 s43, s43, 0x100
	s_addc_u32 s45, s45, 0
	s_cmp_gt_u32 s46, 13
	s_cbranch_scc0 .LBB0_344
	s_and_b64 vcc, exec, s[8:9]
	s_cbranch_vccz .LBB0_347
	s_barrier

; #define PG8_STAGE(bufoff, gbase, voff) do { _Pragma("unroll") for (int _i = 0; _i < 2; ++_i) \
;         __builtin_amdgcn_global_load_lds((const unsigned*)((const char*)(gbase) + (voff)[_i]), (LAS unsigned*)(lds + (bufoff) + ldsw + _i * 8192), 16, 0, 0); } while (0)
; #define PG8_LDA(dst, b, h) do { _Pragma("unroll") for (int m = 0; m < 4; ++m) _Pragma("unroll") for (int k = 0; k < 2; ++k) dst[m][k] = *(const LAS bf16x8*)(lds + PG8_SA(b, h) + aoff + m * 2048 + k * 1024); } while (0)
; #define PG8_LDB(dst, b, h) do { _Pragma("unroll") for (int n = 0; n < 2; ++n) _Pragma("unroll") for (int k = 0; k < 2; ++k) dst[n][k] = *(const LAS bf16x8*)(lds + PG8_SB(b, h) + boff + n * 2048 + k * 1024); } while (0)
; #define PG8_MMA(ai, bj, At, Bt) do { __builtin_amdgcn_s_setprio(1); _Pragma("unroll") for (int m = 0; m < 4; ++m) _Pragma("unroll") for (int n = 0; n < 2; ++n) _Pragma("unroll") for (int k = 0; k < 2; ++k) \
;         acc[ai][bj][m][n] = __builtin_amdgcn_mfma_f32_16x16x32_bf16(Bt[n][k], At[m][k], acc[ai][bj][m][n], 0, 0, 0); __builtin_amdgcn_s_setprio(0); } while (0)
; #define PG8_WAIT_V(n) asm volatile("s_waitcnt vmcnt(" #n ")" ::: "memory")
; #define PG8_WAIT_L(n) asm volatile("s_waitcnt lgkmcnt(" #n ")" ::: "memory")
; #define PG8_BAR __builtin_amdgcn_s_barrier()
; #define PG8_SCHED __builtin_amdgcn_sched_barrier(0)
; template <class Epi, class Sched>
; __device__ __forceinline__ void gemm_phase(int wv, LAS unsigned char* lds, const Gemm g, const Sched& S, const Epi& E) {
;     ...
;         for (int t = 0; t < nt; t += 2) {
;             const bool last = (t == nt - 2);
;             const char* a1 = cA + (size_t)(t + 1) * kstep;
;             const char* a2 = last ? nA : cA + (size_t)(t + 2) * kstep; const char* b2 = last ? nB : cB + (size_t)(t + 2) * kstep;
;             const char* a3 = a2 + kstep; const char* b3 = b2 + kstep;
;             PG8_LDB(B0, 0, 0); PG8_LDB(B1, 0, 1); PG8_SCHED; PG8_LDA(At, 0, 0); PG8_STAGE(PG8_SA(1, 1), a1 + hstep, voffA);
;             PG8_WAIT_V(8); PG8_WAIT_L(0); PG8_BAR; PG8_MMA(0, 0, At, B0); PG8_MMA(0, 1, At, B1); PG8_BAR; PG8_SCHED;
;             PG8_LDA(At, 0, 1); PG8_STAGE(PG8_SB(0, 0), b2, voffB); PG8_STAGE(PG8_SB(0, 1), b2 + hstepB, voffB); PG8_STAGE(PG8_SA(0, 0), a2, voffA);
;             PG8_WAIT_V(8); PG8_WAIT_L(0); PG8_BAR; PG8_MMA(1, 0, At, B0); PG8_MMA(1, 1, At, B1); PG8_BAR; PG8_SCHED;
.LBB0_542:
	s_add_u32 s28, s4, 0xfffc0080
	s_addc_u32 s29, s5, -1
	s_add_i32 s55, 0, 0x10000
	s_cmp_eq_u32 s54, 12
	s_cselect_b32 s31, s21, s29
	s_cselect_b32 s30, s50, s28
	s_cselect_b32 s29, s23, s53
	s_cselect_b32 s28, s51, s52
	s_add_i32 s58, 0, 0x14000
	v_add_u32_e32 v60, s55, v206
	s_waitcnt vmcnt(0)
	v_add_u32_e32 v92, s58, v206
	ds_read_b128 v[48:51], v60
	ds_read_b128 v[52:55], v60 offset:1024
	ds_read_b128 v[56:59], v60 offset:2048
	ds_read_b128 v[60:63], v60 offset:3072
	ds_read_b128 v[64:67], v92
	ds_read_b128 v[68:71], v92 offset:1024
	ds_read_b128 v[88:91], v92 offset:2048
	ds_read_b128 v[92:95], v92 offset:3072
	v_lshl_add_u64 v[222:223], s[4:5], 0, v[174:175]
	s_add_i32 m0, s41, 0xc000
	ds_read_b128 v[180:183], v209
	ds_read_b128 v[184:187], v209 offset:1024
	ds_read_b128 v[198:201], v209 offset:2048
	ds_read_b128 v[202:205], v209 offset:3072
	ds_read_b128 v[210:213], v209 offset:4096
	ds_read_b128 v[214:217], v209 offset:5120
	ds_read_b128 v[218:221], v209 offset:6144
	ds_read_b128 v[228:231], v209 offset:7168
	global_load_lds_dwordx4 v[222:223], off
	v_lshl_add_u64 v[222:223], s[4:5], 0, v[176:177]
	s_add_i32 m0, s41, 0xe000
	s_nop 0
	global_load_lds_dwordx4 v[222:223], off
	s_waitcnt vmcnt(8)
	s_waitcnt lgkmcnt(0)
	s_setprio 1
	s_waitcnt lgkmcnt(0)
	v_mfma_f32_16x16x32_bf16 v[156:159], v[48:51], v[180:183], v[156:159]
	v_mfma_f32_16x16x32_bf16 v[152:155], v[56:59], v[180:183], v[152:155]
	v_mfma_f32_16x16x32_bf16 v[140:143], v[48:51], v[198:201], v[140:143]
	v_mfma_f32_16x16x32_bf16 v[136:139], v[56:59], v[198:201], v[136:139]
	v_mfma_f32_16x16x32_bf16 v[124:127], v[48:51], v[210:213], v[124:127]
	v_mfma_f32_16x16x32_bf16 v[120:123], v[56:59], v[210:213], v[120:123]
	v_mfma_f32_16x16x32_bf16 v[108:111], v[48:51], v[218:221], v[108:111]
	v_mfma_f32_16x16x32_bf16 v[104:107], v[56:59], v[218:221], v[104:107]
	s_barrier
	v_mfma_f32_16x16x32_bf16 v[156:159], v[52:55], v[184:187], v[156:159]
	v_mfma_f32_16x16x32_bf16 v[152:155], v[60:63], v[184:187], v[152:155]
	v_mfma_f32_16x16x32_bf16 v[140:143], v[52:55], v[202:205], v[140:143]
	v_mfma_f32_16x16x32_bf16 v[136:139], v[60:63], v[202:205], v[136:139]
	v_mfma_f32_16x16x32_bf16 v[124:127], v[52:55], v[214:217], v[124:127]
	v_mfma_f32_16x16x32_bf16 v[120:123], v[60:63], v[214:217], v[120:123]
	v_mfma_f32_16x16x32_bf16 v[108:111], v[52:55], v[228:231], v[108:111]
	v_mfma_f32_16x16x32_bf16 v[104:107], v[60:63], v[228:231], v[104:107]
	s_setprio 0
	s_setprio 1
	v_mfma_f32_16x16x32_bf16 v[148:151], v[64:67], v[180:183], v[148:151]
	v_mfma_f32_16x16x32_bf16 v[144:147], v[88:91], v[180:183], v[144:147]
	v_mfma_f32_16x16x32_bf16 v[132:135], v[64:67], v[198:201], v[132:135]
	v_mfma_f32_16x16x32_bf16 v[128:131], v[88:91], v[198:201], v[128:131]
	v_mfma_f32_16x16x32_bf16 v[116:119], v[64:67], v[210:213], v[116:119]
	v_mfma_f32_16x16x32_bf16 v[112:115], v[88:91], v[210:213], v[112:115]
	v_mfma_f32_16x16x32_bf16 v[100:103], v[64:67], v[218:221], v[100:103]
	v_mfma_f32_16x16x32_bf16 v[96:99], v[88:91], v[218:221], v[96:99]
	v_mfma_f32_16x16x32_bf16 v[148:151], v[68:71], v[184:187], v[148:151]
	v_mfma_f32_16x16x32_bf16 v[144:147], v[92:95], v[184:187], v[144:147]
	v_mfma_f32_16x16x32_bf16 v[132:135], v[68:71], v[202:205], v[132:135]
	v_mfma_f32_16x16x32_bf16 v[128:131], v[92:95], v[202:205], v[128:131]
	v_mfma_f32_16x16x32_bf16 v[116:119], v[68:71], v[214:217], v[116:119]
	v_mfma_f32_16x16x32_bf16 v[112:115], v[92:95], v[214:217], v[112:115]
	v_mfma_f32_16x16x32_bf16 v[100:103], v[68:71], v[228:231], v[100:103]
	v_mfma_f32_16x16x32_bf16 v[96:99], v[92:95], v[228:231], v[96:99]
	s_setprio 0
	s_barrier
	s_add_i32 s55, s55, s40
	v_lshl_add_u64 v[222:223], s[28:29], 0, v[164:165]
	s_mov_b32 m0, s55
	ds_read_b128 v[180:183], v209 offset:16384
	ds_read_b128 v[184:187], v209 offset:17408
	ds_read_b128 v[198:201], v209 offset:18432
	ds_read_b128 v[202:205], v209 offset:19456
	ds_read_b128 v[210:213], v209 offset:20480
	ds_read_b128 v[214:217], v209 offset:21504
	ds_read_b128 v[218:221], v209 offset:22528
	ds_read_b128 v[228:231], v209 offset:23552
	global_load_lds_dwordx4 v[222:223], off
	s_add_i32 m0, s55, 0x2000
	s_add_u32 s56, s28, 0x20000
	v_lshl_add_u64 v[240:241], s[28:29], 0, v[160:161]
	s_addc_u32 s57, s29, 0
	s_add_i32 s55, s58, s40
	global_load_lds_dwordx4 v[240:241], off
	v_lshl_add_u64 v[232:233], s[56:57], 0, v[164:165]
	s_mov_b32 m0, s55
	v_lshl_add_u64 v[242:243], s[30:31], 0, v[166:167]
	global_load_lds_dwordx4 v[232:233], off
	v_lshl_add_u64 v[232:233], s[56:57], 0, v[160:161]
	s_add_i32 m0, s55, 0x2000
	v_lshl_add_u64 v[244:245], s[30:31], 0, v[162:163]
	global_load_lds_dwordx4 v[232:233], off
	s_mov_b32 m0, s41
	s_nop 0
	global_load_lds_dwordx4 v[242:243], off
	s_mov_b32 m0, s42
	s_nop 0
	global_load_lds_dwordx4 v[244:245], off
	s_waitcnt vmcnt(8)
	s_waitcnt lgkmcnt(0)
	s_setprio 1
	s_waitcnt lgkmcnt(0)
	v_mfma_f32_16x16x32_bf16 v[84:87], v[48:51], v[180:183], v[84:87]
	v_mfma_f32_16x16x32_bf16 v[80:83], v[56:59], v[180:183], v[80:83]
	v_mfma_f32_16x16x32_bf16 v[44:47], v[48:51], v[198:201], v[44:47]
	v_mfma_f32_16x16x32_bf16 v[40:43], v[56:59], v[198:201], v[40:43]
	v_mfma_f32_16x16x32_bf16 v[28:31], v[48:51], v[210:213], v[28:31]
	v_mfma_f32_16x16x32_bf16 v[24:27], v[56:59], v[210:213], v[24:27]
	v_mfma_f32_16x16x32_bf16 v[12:15], v[48:51], v[218:221], v[12:15]
	v_mfma_f32_16x16x32_bf16 v[8:11], v[56:59], v[218:221], v[8:11]
	s_barrier
; #define PG8_STAGE(bufoff, gbase, voff) do { _Pragma("unroll") for (int _i = 0; _i < 2; ++_i) \
;         __builtin_amdgcn_global_load_lds((const unsigned*)((const char*)(gbase) + (voff)[_i]), (LAS unsigned*)(lds + (bufoff) + ldsw + _i * 8192), 16, 0, 0); } while (0)
; #define PG8_LDA(dst, b, h) do { _Pragma("unroll") for (int m = 0; m < 4; ++m) _Pragma("unroll") for (int k = 0; k < 2; ++k) dst[m][k] = *(const LAS bf16x8*)(lds + PG8_SA(b, h) + aoff + m * 2048 + k * 1024); } while (0)
; #define PG8_LDB(dst, b, h) do { _Pragma("unroll") for (int n = 0; n < 2; ++n) _Pragma("unroll") for (int k = 0; k < 2; ++k) dst[n][k] = *(const LAS bf16x8*)(lds + PG8_SB(b, h) + boff + n * 2048 + k * 1024); } while (0)
; #define PG8_MMA(ai, bj, At, Bt) do { __builtin_amdgcn_s_setprio(1); _Pragma("unroll") for (int m = 0; m < 4; ++m) _Pragma("unroll") for (int n = 0; n < 2; ++n) _Pragma("unroll") for (int k = 0; k < 2; ++k) \
;         acc[ai][bj][m][n] = __builtin_amdgcn_mfma_f32_16x16x32_bf16(Bt[n][k], At[m][k], acc[ai][bj][m][n], 0, 0, 0); __builtin_amdgcn_s_setprio(0); } while (0)
; #define PG8_WAIT_V(n) asm volatile("s_waitcnt vmcnt(" #n ")" ::: "memory")
; #define PG8_WAIT_L(n) asm volatile("s_waitcnt lgkmcnt(" #n ")" ::: "memory")
; #define PG8_BAR __builtin_amdgcn_s_barrier()
; #define PG8_SCHED __builtin_amdgcn_sched_barrier(0)
; template <class Epi, class Sched>
; __device__ __forceinline__ void gemm_phase(int wv, LAS unsigned char* lds, const Gemm g, const Sched& S, const Epi& E) {
;     ...
;             PG8_WAIT_V(8); PG8_WAIT_L(0); PG8_BAR; PG8_MMA(1, 0, At, B0); PG8_MMA(1, 1, At, B1); PG8_BAR; PG8_SCHED;
;             PG8_LDB(B0, 1, 0); PG8_LDB(B1, 1, 1); PG8_SCHED; PG8_LDA(At, 1, 0); PG8_STAGE(PG8_SA(0, 1), a2 + hstep, voffA);
;             PG8_WAIT_V(8); PG8_WAIT_L(0); PG8_BAR; PG8_MMA(0, 0, At, B0); PG8_MMA(0, 1, At, B1); PG8_BAR; PG8_SCHED;
	v_mfma_f32_16x16x32_bf16 v[84:87], v[52:55], v[184:187], v[84:87]
	v_mfma_f32_16x16x32_bf16 v[80:83], v[60:63], v[184:187], v[80:83]
	v_mfma_f32_16x16x32_bf16 v[44:47], v[52:55], v[202:205], v[44:47]
	v_mfma_f32_16x16x32_bf16 v[40:43], v[60:63], v[202:205], v[40:43]
	v_mfma_f32_16x16x32_bf16 v[28:31], v[52:55], v[214:217], v[28:31]
	v_mfma_f32_16x16x32_bf16 v[24:27], v[60:63], v[214:217], v[24:27]
	v_mfma_f32_16x16x32_bf16 v[12:15], v[52:55], v[228:231], v[12:15]
	v_mfma_f32_16x16x32_bf16 v[8:11], v[60:63], v[228:231], v[8:11]
	s_setprio 0
	s_setprio 1
	v_mfma_f32_16x16x32_bf16 v[36:39], v[64:67], v[198:201], v[36:39]
	v_mfma_f32_16x16x32_bf16 v[32:35], v[88:91], v[198:201], v[32:35]
	v_mfma_f32_16x16x32_bf16 v[20:23], v[64:67], v[210:213], v[20:23]
	v_mfma_f32_16x16x32_bf16 v[16:19], v[88:91], v[210:213], v[16:19]
	v_mfma_f32_16x16x32_bf16 v[4:7], v[64:67], v[218:221], v[4:7]
	v_mfma_f32_16x16x32_bf16 v[0:3], v[88:91], v[218:221], v[0:3]
	v_mfma_f32_16x16x32_bf16 v[48:51], v[64:67], v[180:183], v[76:79]
	v_mfma_f32_16x16x32_bf16 v[52:55], v[88:91], v[180:183], v[72:75]
	v_mfma_f32_16x16x32_bf16 v[36:39], v[68:71], v[202:205], v[36:39]
	v_mfma_f32_16x16x32_bf16 v[32:35], v[92:95], v[202:205], v[32:35]
	v_mfma_f32_16x16x32_bf16 v[20:23], v[68:71], v[214:217], v[20:23]
	v_mfma_f32_16x16x32_bf16 v[16:19], v[92:95], v[214:217], v[16:19]
	v_mfma_f32_16x16x32_bf16 v[4:7], v[68:71], v[228:231], v[4:7]
	v_mfma_f32_16x16x32_bf16 v[0:3], v[92:95], v[228:231], v[0:3]
	v_mfma_f32_16x16x32_bf16 v[48:51], v[68:71], v[184:187], v[48:51]
	v_mfma_f32_16x16x32_bf16 v[52:55], v[92:95], v[184:187], v[52:55]
	s_setprio 0
	s_barrier
	s_add_i32 s55, 0, 0x1c000
	v_add_u32_e32 v68, s95, v206
	v_add_u32_e32 v72, s55, v206
	ds_read_b128 v[56:59], v68
	ds_read_b128 v[60:63], v68 offset:1024
	ds_read_b128 v[64:67], v68 offset:2048
	ds_read_b128 v[68:71], v68 offset:3072
	ds_read_b128 v[88:91], v72
	ds_read_b128 v[92:95], v72 offset:1024
	ds_read_b128 v[180:183], v72 offset:2048
	ds_read_b128 v[184:187], v72 offset:3072
	s_add_u32 s30, s30, 0x40000
	s_addc_u32 s31, s31, 0
	s_mov_b32 m0, s43
	v_lshl_add_u64 v[232:233], s[30:31], 0, v[166:167]
	ds_read_b128 v[72:75], v209 offset:32768
	ds_read_b128 v[76:79], v209 offset:33792
	ds_read_b128 v[198:201], v209 offset:34816
	ds_read_b128 v[202:205], v209 offset:35840
	ds_read_b128 v[210:213], v209 offset:36864
	ds_read_b128 v[214:217], v209 offset:37888
	ds_read_b128 v[218:221], v209 offset:38912
	ds_read_b128 v[228:231], v209 offset:39936
	global_load_lds_dwordx4 v[232:233], off
	v_lshl_add_u64 v[232:233], s[30:31], 0, v[162:163]
	s_mov_b32 m0, s45
	s_nop 0
	global_load_lds_dwordx4 v[232:233], off
	s_waitcnt vmcnt(8)
	s_waitcnt lgkmcnt(0)
	s_setprio 1
	s_waitcnt lgkmcnt(0)
	v_mfma_f32_16x16x32_bf16 v[156:159], v[56:59], v[72:75], v[156:159]
	v_mfma_f32_16x16x32_bf16 v[152:155], v[64:67], v[72:75], v[152:155]
	v_mfma_f32_16x16x32_bf16 v[140:143], v[56:59], v[198:201], v[140:143]
	v_mfma_f32_16x16x32_bf16 v[136:139], v[64:67], v[198:201], v[136:139]
	v_mfma_f32_16x16x32_bf16 v[124:127], v[56:59], v[210:213], v[124:127]
	v_mfma_f32_16x16x32_bf16 v[120:123], v[64:67], v[210:213], v[120:123]
	v_mfma_f32_16x16x32_bf16 v[108:111], v[56:59], v[218:221], v[108:111]
	v_mfma_f32_16x16x32_bf16 v[104:107], v[64:67], v[218:221], v[104:107]
	s_barrier
	v_mfma_f32_16x16x32_bf16 v[156:159], v[60:63], v[76:79], v[156:159]
	v_mfma_f32_16x16x32_bf16 v[152:155], v[68:71], v[76:79], v[152:155]
	v_mfma_f32_16x16x32_bf16 v[140:143], v[60:63], v[202:205], v[140:143]
	v_mfma_f32_16x16x32_bf16 v[136:139], v[68:71], v[202:205], v[136:139]
	v_mfma_f32_16x16x32_bf16 v[124:127], v[60:63], v[214:217], v[124:127]
	v_mfma_f32_16x16x32_bf16 v[120:123], v[68:71], v[214:217], v[120:123]
	v_mfma_f32_16x16x32_bf16 v[108:111], v[60:63], v[228:231], v[108:111]
	v_mfma_f32_16x16x32_bf16 v[104:107], v[68:71], v[228:231], v[104:107]
	s_setprio 0
	s_setprio 1
	v_mfma_f32_16x16x32_bf16 v[148:151], v[88:91], v[72:75], v[148:151]
	v_mfma_f32_16x16x32_bf16 v[72:75], v[180:183], v[72:75], v[144:147]
	v_mfma_f32_16x16x32_bf16 v[144:147], v[184:187], v[76:79], v[72:75]
	v_mfma_f32_16x16x32_bf16 v[72:75], v[88:91], v[198:201], v[132:135]
	v_mfma_f32_16x16x32_bf16 v[132:135], v[92:95], v[202:205], v[72:75]
	v_mfma_f32_16x16x32_bf16 v[72:75], v[180:183], v[198:201], v[128:131]
	v_mfma_f32_16x16x32_bf16 v[128:131], v[184:187], v[202:205], v[72:75]
	v_mfma_f32_16x16x32_bf16 v[72:75], v[88:91], v[210:213], v[116:119]
	v_mfma_f32_16x16x32_bf16 v[116:119], v[92:95], v[214:217], v[72:75]
	v_mfma_f32_16x16x32_bf16 v[72:75], v[180:183], v[210:213], v[112:115]
	v_mfma_f32_16x16x32_bf16 v[112:115], v[184:187], v[214:217], v[72:75]
	v_mfma_f32_16x16x32_bf16 v[72:75], v[88:91], v[218:221], v[100:103]
	v_mfma_f32_16x16x32_bf16 v[100:103], v[92:95], v[228:231], v[72:75]
	v_mfma_f32_16x16x32_bf16 v[72:75], v[180:183], v[218:221], v[96:99]
	v_mfma_f32_16x16x32_bf16 v[148:151], v[92:95], v[76:79], v[148:151]
	v_mfma_f32_16x16x32_bf16 v[96:99], v[184:187], v[228:231], v[72:75]
	s_setprio 0
	s_barrier
; #define PG8_STAGE(bufoff, gbase, voff) do { _Pragma("unroll") for (int _i = 0; _i < 2; ++_i) \
;         __builtin_amdgcn_global_load_lds((const unsigned*)((const char*)(gbase) + (voff)[_i]), (LAS unsigned*)(lds + (bufoff) + ldsw + _i * 8192), 16, 0, 0); } while (0)
; #define PG8_LDA(dst, b, h) do { _Pragma("unroll") for (int m = 0; m < 4; ++m) _Pragma("unroll") for (int k = 0; k < 2; ++k) dst[m][k] = *(const LAS bf16x8*)(lds + PG8_SA(b, h) + aoff + m * 2048 + k * 1024); } while (0)
; #define PG8_MMA(ai, bj, At, Bt) do { __builtin_amdgcn_s_setprio(1); _Pragma("unroll") for (int m = 0; m < 4; ++m) _Pragma("unroll") for (int n = 0; n < 2; ++n) _Pragma("unroll") for (int k = 0; k < 2; ++k) \
;         acc[ai][bj][m][n] = __builtin_amdgcn_mfma_f32_16x16x32_bf16(Bt[n][k], At[m][k], acc[ai][bj][m][n], 0, 0, 0); __builtin_amdgcn_s_setprio(0); } while (0)
; #define PG8_WAIT_V(n) asm volatile("s_waitcnt vmcnt(" #n ")" ::: "memory")
; #define PG8_WAIT_L(n) asm volatile("s_waitcnt lgkmcnt(" #n ")" ::: "memory")
; #define PG8_BAR __builtin_amdgcn_s_barrier()
; #define PG8_SCHED __builtin_amdgcn_sched_barrier(0)
; template <class Epi, class Sched>
; __device__ __forceinline__ void gemm_phase(int wv, LAS unsigned char* lds, const Gemm g, const Sched& S, const Epi& E) {
;     ...
;             PG8_LDA(At, 1, 1); PG8_STAGE(PG8_SB(1, 0), b3, voffB); PG8_STAGE(PG8_SB(1, 1), b3 + hstepB, voffB); PG8_STAGE(PG8_SA(1, 0), a3, voffA);
;             PG8_WAIT_V(8); PG8_WAIT_L(0); PG8_BAR; PG8_MMA(1, 0, At, B0); PG8_MMA(1, 1, At, B1); PG8_BAR; PG8_SCHED;
;         }
;         if (wr == 0) PG8_BAR;
	s_add_i32 s30, s95, s40
	v_lshl_add_u64 v[76:77], v[222:223], 0, s[74:75]
	s_mov_b32 m0, s30
	s_nop 0
	ds_read_b128 v[72:75], v209 offset:49152
	ds_read_b128 v[198:201], v209 offset:50176
	ds_read_b128 v[202:205], v209 offset:51200
	ds_read_b128 v[210:213], v209 offset:52224
	ds_read_b128 v[214:217], v209 offset:53248
	ds_read_b128 v[218:221], v209 offset:54272
	ds_read_b128 v[228:231], v209 offset:55296
	ds_read_b128 v[232:235], v209 offset:56320
	global_load_lds_dwordx4 v[76:77], off
	s_add_i32 m0, s30, 0x2000
	s_add_u32 s28, s28, 0x20080
	v_lshl_add_u64 v[76:77], v[240:241], 0, s[74:75]
	s_addc_u32 s29, s29, 0
	s_add_i32 s30, s55, s40
	global_load_lds_dwordx4 v[76:77], off
	v_lshl_add_u64 v[76:77], s[28:29], 0, v[164:165]
	s_mov_b32 m0, s30
	s_nop 0
	global_load_lds_dwordx4 v[76:77], off
	v_lshl_add_u64 v[76:77], s[28:29], 0, v[160:161]
	s_add_i32 m0, s30, 0x2000
	s_nop 0
	global_load_lds_dwordx4 v[76:77], off
	v_lshl_add_u64 v[76:77], v[242:243], 0, s[74:75]
	s_mov_b32 m0, s48
	s_nop 0
	global_load_lds_dwordx4 v[76:77], off
	v_lshl_add_u64 v[76:77], v[244:245], 0, s[74:75]
	s_mov_b32 m0, s49
	s_nop 0
	global_load_lds_dwordx4 v[76:77], off
	s_waitcnt vmcnt(8)
	s_waitcnt lgkmcnt(0)
	s_setprio 1
	s_waitcnt lgkmcnt(0)
	v_mfma_f32_16x16x32_bf16 v[76:79], v[56:59], v[72:75], v[84:87]
	v_mfma_f32_16x16x32_bf16 v[84:87], v[60:63], v[198:201], v[76:79]
	v_mfma_f32_16x16x32_bf16 v[76:79], v[64:67], v[72:75], v[80:83]
	v_mfma_f32_16x16x32_bf16 v[44:47], v[56:59], v[202:205], v[44:47]
	v_mfma_f32_16x16x32_bf16 v[40:43], v[64:67], v[202:205], v[40:43]
	v_mfma_f32_16x16x32_bf16 v[28:31], v[56:59], v[214:217], v[28:31]
	v_mfma_f32_16x16x32_bf16 v[24:27], v[64:67], v[214:217], v[24:27]
	v_mfma_f32_16x16x32_bf16 v[12:15], v[56:59], v[228:231], v[12:15]
	s_barrier
	v_mfma_f32_16x16x32_bf16 v[8:11], v[64:67], v[228:231], v[8:11]
	v_mfma_f32_16x16x32_bf16 v[80:83], v[68:71], v[198:201], v[76:79]
	v_mfma_f32_16x16x32_bf16 v[44:47], v[60:63], v[210:213], v[44:47]
	v_mfma_f32_16x16x32_bf16 v[40:43], v[68:71], v[210:213], v[40:43]
	v_mfma_f32_16x16x32_bf16 v[28:31], v[60:63], v[218:221], v[28:31]
	v_mfma_f32_16x16x32_bf16 v[24:27], v[68:71], v[218:221], v[24:27]
	v_mfma_f32_16x16x32_bf16 v[12:15], v[60:63], v[232:235], v[12:15]
	v_mfma_f32_16x16x32_bf16 v[8:11], v[68:71], v[232:235], v[8:11]
	s_setprio 0
	s_setprio 1
	v_mfma_f32_16x16x32_bf16 v[48:51], v[88:91], v[72:75], v[48:51]
	v_mfma_f32_16x16x32_bf16 v[76:79], v[92:95], v[198:201], v[48:51]
	v_mfma_f32_16x16x32_bf16 v[48:51], v[180:183], v[72:75], v[52:55]
	v_mfma_f32_16x16x32_bf16 v[36:39], v[88:91], v[202:205], v[36:39]
	v_mfma_f32_16x16x32_bf16 v[32:35], v[180:183], v[202:205], v[32:35]
	v_mfma_f32_16x16x32_bf16 v[20:23], v[88:91], v[214:217], v[20:23]
	v_mfma_f32_16x16x32_bf16 v[16:19], v[180:183], v[214:217], v[16:19]
	v_mfma_f32_16x16x32_bf16 v[4:7], v[88:91], v[228:231], v[4:7]
	v_mfma_f32_16x16x32_bf16 v[0:3], v[180:183], v[228:231], v[0:3]
	v_mfma_f32_16x16x32_bf16 v[72:75], v[184:187], v[198:201], v[48:51]
	v_mfma_f32_16x16x32_bf16 v[36:39], v[92:95], v[210:213], v[36:39]
	v_mfma_f32_16x16x32_bf16 v[32:35], v[184:187], v[210:213], v[32:35]
	v_mfma_f32_16x16x32_bf16 v[20:23], v[92:95], v[218:221], v[20:23]
	v_mfma_f32_16x16x32_bf16 v[16:19], v[184:187], v[218:221], v[16:19]
	v_mfma_f32_16x16x32_bf16 v[4:7], v[92:95], v[232:235], v[4:7]
	v_mfma_f32_16x16x32_bf16 v[0:3], v[184:187], v[232:235], v[0:3]
	s_setprio 0
	s_barrier
	s_add_i32 s54, s54, 2
	s_add_u32 s4, s4, 0x100
	s_addc_u32 s5, s5, 0
	s_add_u32 s52, s52, 0x100
	s_addc_u32 s53, s53, 0
	s_cmp_gt_u32 s54, 13
	s_cbranch_scc0 .LBB0_542
	s_and_b64 vcc, exec, s[16:17]
	s_cbranch_vccz .LBB0_545
	s_barrier

; #define PG8_STAGE(bufoff, gbase, voff) do { _Pragma("unroll") for (int _i = 0; _i < 2; ++_i) \
;         __builtin_amdgcn_global_load_lds((const unsigned*)((const char*)(gbase) + (voff)[_i]), (LAS unsigned*)(lds + (bufoff) + ldsw + _i * 8192), 16, 0, 0); } while (0)
; #define PG8_LDA(dst, b, h) do { _Pragma("unroll") for (int m = 0; m < 4; ++m) _Pragma("unroll") for (int k = 0; k < 2; ++k) dst[m][k] = *(const LAS bf16x8*)(lds + PG8_SA(b, h) + aoff + m * 2048 + k * 1024); } while (0)
; #define PG8_LDB(dst, b, h) do { _Pragma("unroll") for (int n = 0; n < 2; ++n) _Pragma("unroll") for (int k = 0; k < 2; ++k) dst[n][k] = *(const LAS bf16x8*)(lds + PG8_SB(b, h) + boff + n * 2048 + k * 1024); } while (0)
; #define PG8_MMA(ai, bj, At, Bt) do { __builtin_amdgcn_s_setprio(1); _Pragma("unroll") for (int m = 0; m < 4; ++m) _Pragma("unroll") for (int n = 0; n < 2; ++n) _Pragma("unroll") for (int k = 0; k < 2; ++k) \
;         acc[ai][bj][m][n] = __builtin_amdgcn_mfma_f32_16x16x32_bf16(Bt[n][k], At[m][k], acc[ai][bj][m][n], 0, 0, 0); __builtin_amdgcn_s_setprio(0); } while (0)
; #define PG8_WAIT_V(n) asm volatile("s_waitcnt vmcnt(" #n ")" ::: "memory")
; #define PG8_WAIT_L(n) asm volatile("s_waitcnt lgkmcnt(" #n ")" ::: "memory")
; #define PG8_BAR __builtin_amdgcn_s_barrier()
; #define PG8_SCHED __builtin_amdgcn_sched_barrier(0)
; template <class Epi, class Sched>
; __device__ __forceinline__ void gemm_phase(int wv, LAS unsigned char* lds, const Gemm g, const Sched& S, const Epi& E) {
;     ...
;         for (int t = 0; t < nt; t += 2) {
;             const bool last = (t == nt - 2);
;             const char* a1 = cA + (size_t)(t + 1) * kstep;
;             const char* a2 = last ? nA : cA + (size_t)(t + 2) * kstep; const char* b2 = last ? nB : cB + (size_t)(t + 2) * kstep;
;             const char* a3 = a2 + kstep; const char* b3 = b2 + kstep;
;             PG8_LDB(B0, 0, 0); PG8_LDB(B1, 0, 1); PG8_SCHED; PG8_LDA(At, 0, 0); PG8_STAGE(PG8_SA(1, 1), a1 + hstep, voffA);
;             PG8_WAIT_V(8); PG8_WAIT_L(0); PG8_BAR; PG8_MMA(0, 0, At, B0); PG8_MMA(0, 1, At, B1); PG8_BAR; PG8_SCHED;
;             PG8_LDA(At, 0, 1); PG8_STAGE(PG8_SB(0, 0), b2, voffB); PG8_STAGE(PG8_SB(0, 1), b2 + hstepB, voffB); PG8_STAGE(PG8_SA(0, 0), a2, voffA);
;             PG8_WAIT_V(8); PG8_WAIT_L(0); PG8_BAR; PG8_MMA(1, 0, At, B0); PG8_MMA(1, 1, At, B1); PG8_BAR; PG8_SCHED;
.LBB0_781:
	s_add_u32 s22, s20, 0xfffc0080
	s_addc_u32 s23, s21, -1
	s_add_i32 s44, 0, 0x10000
	s_cmp_eq_u32 s43, 12
	s_cselect_b32 s25, s13, s23
	s_cselect_b32 s24, s39, s22
	s_cselect_b32 s23, s15, s42
	s_cselect_b32 s22, s40, s41
	s_add_i32 s46, 0, 0x14000
	v_add_u32_e32 v154, s44, v139
	v_add_u32_e32 v170, s46, v139
	ds_read_b128 v[142:145], v154
	ds_read_b128 v[146:149], v154 offset:1024
	ds_read_b128 v[150:153], v154 offset:2048
	ds_read_b128 v[154:157], v154 offset:3072
	ds_read_b128 v[158:161], v170
	ds_read_b128 v[162:165], v170 offset:1024
	ds_read_b128 v[166:169], v170 offset:2048
	ds_read_b128 v[170:173], v170 offset:3072
	v_lshl_add_u64 v[186:187], s[20:21], 0, v[134:135]
	s_add_i32 m0, s29, 0xc000
	ds_read_b128 v[174:177], v141
	ds_read_b128 v[178:181], v141 offset:1024
	ds_read_b128 v[182:185], v141 offset:2048
	ds_read_b128 v[198:201], v141 offset:3072
	ds_read_b128 v[202:205], v141 offset:4096
	ds_read_b128 v[206:209], v141 offset:5120
	ds_read_b128 v[210:213], v141 offset:6144
	ds_read_b128 v[214:217], v141 offset:7168
	global_load_lds_dwordx4 v[186:187], off
	v_lshl_add_u64 v[186:187], s[20:21], 0, v[136:137]
	s_add_i32 m0, s29, 0xe000
	s_nop 0
	global_load_lds_dwordx4 v[186:187], off
	s_waitcnt vmcnt(8)
	s_waitcnt lgkmcnt(0)
	s_setprio 1
	s_waitcnt lgkmcnt(0)
	v_mfma_f32_16x16x32_bf16 v[124:127], v[142:145], v[174:177], v[124:127]
	v_mfma_f32_16x16x32_bf16 v[120:123], v[150:153], v[174:177], v[120:123]
	v_mfma_f32_16x16x32_bf16 v[116:119], v[142:145], v[182:185], v[116:119]
	v_mfma_f32_16x16x32_bf16 v[108:111], v[150:153], v[182:185], v[108:111]
	v_mfma_f32_16x16x32_bf16 v[100:103], v[142:145], v[202:205], v[100:103]
	v_mfma_f32_16x16x32_bf16 v[96:99], v[150:153], v[202:205], v[96:99]
	v_mfma_f32_16x16x32_bf16 v[84:87], v[142:145], v[210:213], v[84:87]
	v_mfma_f32_16x16x32_bf16 v[80:83], v[150:153], v[210:213], v[80:83]
	s_barrier
	v_mfma_f32_16x16x32_bf16 v[124:127], v[146:149], v[178:181], v[124:127]
	v_mfma_f32_16x16x32_bf16 v[120:123], v[154:157], v[178:181], v[120:123]
	v_mfma_f32_16x16x32_bf16 v[116:119], v[146:149], v[198:201], v[116:119]
	v_mfma_f32_16x16x32_bf16 v[108:111], v[154:157], v[198:201], v[108:111]
	v_mfma_f32_16x16x32_bf16 v[100:103], v[146:149], v[206:209], v[100:103]
	v_mfma_f32_16x16x32_bf16 v[96:99], v[154:157], v[206:209], v[96:99]
	v_mfma_f32_16x16x32_bf16 v[84:87], v[146:149], v[214:217], v[84:87]
	v_mfma_f32_16x16x32_bf16 v[80:83], v[154:157], v[214:217], v[80:83]
	s_setprio 0
	s_setprio 1
	v_mfma_f32_16x16x32_bf16 v[112:115], v[158:161], v[174:177], v[112:115]
	v_mfma_f32_16x16x32_bf16 v[104:107], v[166:169], v[174:177], v[104:107]
	v_mfma_f32_16x16x32_bf16 v[92:95], v[158:161], v[182:185], v[92:95]
	v_mfma_f32_16x16x32_bf16 v[88:91], v[166:169], v[182:185], v[88:91]
	v_mfma_f32_16x16x32_bf16 v[76:79], v[158:161], v[202:205], v[76:79]
	v_mfma_f32_16x16x32_bf16 v[72:75], v[166:169], v[202:205], v[72:75]
	v_mfma_f32_16x16x32_bf16 v[68:71], v[158:161], v[210:213], v[68:71]
	v_mfma_f32_16x16x32_bf16 v[64:67], v[166:169], v[210:213], v[64:67]
	v_mfma_f32_16x16x32_bf16 v[112:115], v[162:165], v[178:181], v[112:115]
	v_mfma_f32_16x16x32_bf16 v[104:107], v[170:173], v[178:181], v[104:107]
	v_mfma_f32_16x16x32_bf16 v[92:95], v[162:165], v[198:201], v[92:95]
	v_mfma_f32_16x16x32_bf16 v[88:91], v[170:173], v[198:201], v[88:91]
	v_mfma_f32_16x16x32_bf16 v[76:79], v[162:165], v[206:209], v[76:79]
	v_mfma_f32_16x16x32_bf16 v[72:75], v[170:173], v[206:209], v[72:75]
	v_mfma_f32_16x16x32_bf16 v[68:71], v[162:165], v[214:217], v[68:71]
	v_mfma_f32_16x16x32_bf16 v[64:67], v[170:173], v[214:217], v[64:67]
	s_setprio 0
	s_barrier
	s_add_i32 s44, s44, s28
	v_lshl_add_u64 v[186:187], s[22:23], 0, v[188:189]
	s_mov_b32 m0, s44
	ds_read_b128 v[174:177], v141 offset:16384
	ds_read_b128 v[178:181], v141 offset:17408
	ds_read_b128 v[182:185], v141 offset:18432
	ds_read_b128 v[198:201], v141 offset:19456
	ds_read_b128 v[202:205], v141 offset:20480
	ds_read_b128 v[206:209], v141 offset:21504
	ds_read_b128 v[210:213], v141 offset:22528
	ds_read_b128 v[214:217], v141 offset:23552
	global_load_lds_dwordx4 v[186:187], off
	s_add_i32 m0, s44, 0x2000
	s_add_u32 s44, s22, 0x4000
	v_lshl_add_u64 v[218:219], s[22:23], 0, v[128:129]
	s_addc_u32 s45, s23, 0
	s_add_i32 s46, s46, s28
	global_load_lds_dwordx4 v[218:219], off
	v_lshl_add_u64 v[220:221], s[44:45], 0, v[188:189]
	s_mov_b32 m0, s46
	v_lshl_add_u64 v[222:223], s[24:25], 0, v[130:131]
	global_load_lds_dwordx4 v[220:221], off
	v_lshl_add_u64 v[220:221], s[44:45], 0, v[128:129]
	s_add_i32 m0, s46, 0x2000
	s_nop 0
	global_load_lds_dwordx4 v[220:221], off
	v_lshl_add_u64 v[220:221], s[24:25], 0, v[132:133]
	s_mov_b32 m0, s29
	s_nop 0
	global_load_lds_dwordx4 v[220:221], off
	s_mov_b32 m0, s30
	s_nop 0
	global_load_lds_dwordx4 v[222:223], off
	s_waitcnt vmcnt(8)
	s_waitcnt lgkmcnt(0)
	s_setprio 1
	s_waitcnt lgkmcnt(0)
	v_mfma_f32_16x16x32_bf16 v[60:63], v[142:145], v[174:177], v[60:63]
	v_mfma_f32_16x16x32_bf16 v[56:59], v[150:153], v[174:177], v[56:59]
	v_mfma_f32_16x16x32_bf16 v[52:55], v[142:145], v[182:185], v[52:55]
	v_mfma_f32_16x16x32_bf16 v[48:51], v[150:153], v[182:185], v[48:51]
	v_mfma_f32_16x16x32_bf16 v[36:39], v[142:145], v[202:205], v[36:39]
	v_mfma_f32_16x16x32_bf16 v[32:35], v[150:153], v[202:205], v[32:35]
	v_mfma_f32_16x16x32_bf16 v[20:23], v[142:145], v[210:213], v[20:23]
	v_mfma_f32_16x16x32_bf16 v[16:19], v[150:153], v[210:213], v[16:19]
	s_barrier
; #define PG8_STAGE(bufoff, gbase, voff) do { _Pragma("unroll") for (int _i = 0; _i < 2; ++_i) \
;         __builtin_amdgcn_global_load_lds((const unsigned*)((const char*)(gbase) + (voff)[_i]), (LAS unsigned*)(lds + (bufoff) + ldsw + _i * 8192), 16, 0, 0); } while (0)
; #define PG8_LDA(dst, b, h) do { _Pragma("unroll") for (int m = 0; m < 4; ++m) _Pragma("unroll") for (int k = 0; k < 2; ++k) dst[m][k] = *(const LAS bf16x8*)(lds + PG8_SA(b, h) + aoff + m * 2048 + k * 1024); } while (0)
; #define PG8_LDB(dst, b, h) do { _Pragma("unroll") for (int n = 0; n < 2; ++n) _Pragma("unroll") for (int k = 0; k < 2; ++k) dst[n][k] = *(const LAS bf16x8*)(lds + PG8_SB(b, h) + boff + n * 2048 + k * 1024); } while (0)
; #define PG8_MMA(ai, bj, At, Bt) do { __builtin_amdgcn_s_setprio(1); _Pragma("unroll") for (int m = 0; m < 4; ++m) _Pragma("unroll") for (int n = 0; n < 2; ++n) _Pragma("unroll") for (int k = 0; k < 2; ++k) \
;         acc[ai][bj][m][n] = __builtin_amdgcn_mfma_f32_16x16x32_bf16(Bt[n][k], At[m][k], acc[ai][bj][m][n], 0, 0, 0); __builtin_amdgcn_s_setprio(0); } while (0)
; #define PG8_WAIT_V(n) asm volatile("s_waitcnt vmcnt(" #n ")" ::: "memory")
; #define PG8_WAIT_L(n) asm volatile("s_waitcnt lgkmcnt(" #n ")" ::: "memory")
; #define PG8_BAR __builtin_amdgcn_s_barrier()
; #define PG8_SCHED __builtin_amdgcn_sched_barrier(0)
; template <class Epi, class Sched>
; __device__ __forceinline__ void gemm_phase(int wv, LAS unsigned char* lds, const Gemm g, const Sched& S, const Epi& E) {
;     ...
;             PG8_WAIT_V(8); PG8_WAIT_L(0); PG8_BAR; PG8_MMA(1, 0, At, B0); PG8_MMA(1, 1, At, B1); PG8_BAR; PG8_SCHED;
;             PG8_LDB(B0, 1, 0); PG8_LDB(B1, 1, 1); PG8_SCHED; PG8_LDA(At, 1, 0); PG8_STAGE(PG8_SA(0, 1), a2 + hstep, voffA);
;             PG8_WAIT_V(8); PG8_WAIT_L(0); PG8_BAR; PG8_MMA(0, 0, At, B0); PG8_MMA(0, 1, At, B1); PG8_BAR; PG8_SCHED;
	v_mfma_f32_16x16x32_bf16 v[60:63], v[146:149], v[178:181], v[60:63]
	v_mfma_f32_16x16x32_bf16 v[56:59], v[154:157], v[178:181], v[56:59]
	v_mfma_f32_16x16x32_bf16 v[52:55], v[146:149], v[198:201], v[52:55]
	v_mfma_f32_16x16x32_bf16 v[48:51], v[154:157], v[198:201], v[48:51]
	v_mfma_f32_16x16x32_bf16 v[36:39], v[146:149], v[206:209], v[36:39]
	v_mfma_f32_16x16x32_bf16 v[32:35], v[154:157], v[206:209], v[32:35]
	v_mfma_f32_16x16x32_bf16 v[20:23], v[146:149], v[214:217], v[20:23]
	v_mfma_f32_16x16x32_bf16 v[16:19], v[154:157], v[214:217], v[16:19]
	s_setprio 0
	s_setprio 1
	v_mfma_f32_16x16x32_bf16 v[44:47], v[158:161], v[174:177], v[44:47]
	v_mfma_f32_16x16x32_bf16 v[40:43], v[166:169], v[174:177], v[40:43]
	v_mfma_f32_16x16x32_bf16 v[28:31], v[158:161], v[182:185], v[28:31]
	v_mfma_f32_16x16x32_bf16 v[24:27], v[166:169], v[182:185], v[24:27]
	v_mfma_f32_16x16x32_bf16 v[12:15], v[158:161], v[202:205], v[12:15]
	v_mfma_f32_16x16x32_bf16 v[8:11], v[166:169], v[202:205], v[8:11]
	v_mfma_f32_16x16x32_bf16 v[4:7], v[158:161], v[210:213], v[4:7]
	v_mfma_f32_16x16x32_bf16 v[0:3], v[166:169], v[210:213], v[0:3]
	v_mfma_f32_16x16x32_bf16 v[44:47], v[162:165], v[178:181], v[44:47]
	v_mfma_f32_16x16x32_bf16 v[40:43], v[170:173], v[178:181], v[40:43]
	v_mfma_f32_16x16x32_bf16 v[28:31], v[162:165], v[198:201], v[28:31]
	v_mfma_f32_16x16x32_bf16 v[24:27], v[170:173], v[198:201], v[24:27]
	v_mfma_f32_16x16x32_bf16 v[12:15], v[162:165], v[206:209], v[12:15]
	v_mfma_f32_16x16x32_bf16 v[8:11], v[170:173], v[206:209], v[8:11]
	v_mfma_f32_16x16x32_bf16 v[4:7], v[162:165], v[214:217], v[4:7]
	v_mfma_f32_16x16x32_bf16 v[0:3], v[170:173], v[214:217], v[0:3]
	s_setprio 0
	s_barrier
	s_add_i32 s44, 0, 0x1c000
	v_add_u32_e32 v154, s95, v139
	v_add_u32_e32 v170, s44, v139
	ds_read_b128 v[142:145], v154
	ds_read_b128 v[146:149], v154 offset:1024
	ds_read_b128 v[150:153], v154 offset:2048
	ds_read_b128 v[154:157], v154 offset:3072
	ds_read_b128 v[158:161], v170
	ds_read_b128 v[162:165], v170 offset:1024
	ds_read_b128 v[166:169], v170 offset:2048
	ds_read_b128 v[170:173], v170 offset:3072
	s_add_u32 s24, s24, 0x40000
	s_addc_u32 s25, s25, 0
	s_mov_b32 m0, s31
	v_lshl_add_u64 v[228:229], s[24:25], 0, v[132:133]
	ds_read_b128 v[174:177], v141 offset:32768
	ds_read_b128 v[178:181], v141 offset:33792
	ds_read_b128 v[182:185], v141 offset:34816
	ds_read_b128 v[198:201], v141 offset:35840
	ds_read_b128 v[202:205], v141 offset:36864
	ds_read_b128 v[206:209], v141 offset:37888
	ds_read_b128 v[210:213], v141 offset:38912
	ds_read_b128 v[214:217], v141 offset:39936
	global_load_lds_dwordx4 v[228:229], off
	v_lshl_add_u64 v[228:229], s[24:25], 0, v[130:131]
	s_mov_b32 m0, s34
	s_nop 0
	global_load_lds_dwordx4 v[228:229], off
	s_waitcnt vmcnt(8)
	s_waitcnt lgkmcnt(0)
	s_setprio 1
	s_waitcnt lgkmcnt(0)
	v_mfma_f32_16x16x32_bf16 v[124:127], v[142:145], v[174:177], v[124:127]
	v_mfma_f32_16x16x32_bf16 v[120:123], v[150:153], v[174:177], v[120:123]
	v_mfma_f32_16x16x32_bf16 v[116:119], v[142:145], v[182:185], v[116:119]
	v_mfma_f32_16x16x32_bf16 v[108:111], v[150:153], v[182:185], v[108:111]
	v_mfma_f32_16x16x32_bf16 v[100:103], v[142:145], v[202:205], v[100:103]
	v_mfma_f32_16x16x32_bf16 v[96:99], v[150:153], v[202:205], v[96:99]
	v_mfma_f32_16x16x32_bf16 v[84:87], v[142:145], v[210:213], v[84:87]
	v_mfma_f32_16x16x32_bf16 v[80:83], v[150:153], v[210:213], v[80:83]
	s_barrier
	v_mfma_f32_16x16x32_bf16 v[124:127], v[146:149], v[178:181], v[124:127]
	v_mfma_f32_16x16x32_bf16 v[120:123], v[154:157], v[178:181], v[120:123]
	v_mfma_f32_16x16x32_bf16 v[116:119], v[146:149], v[198:201], v[116:119]
	v_mfma_f32_16x16x32_bf16 v[108:111], v[154:157], v[198:201], v[108:111]
	v_mfma_f32_16x16x32_bf16 v[100:103], v[146:149], v[206:209], v[100:103]
	v_mfma_f32_16x16x32_bf16 v[96:99], v[154:157], v[206:209], v[96:99]
	v_mfma_f32_16x16x32_bf16 v[84:87], v[146:149], v[214:217], v[84:87]
	v_mfma_f32_16x16x32_bf16 v[80:83], v[154:157], v[214:217], v[80:83]
	s_setprio 0
	s_setprio 1
	v_mfma_f32_16x16x32_bf16 v[112:115], v[158:161], v[174:177], v[112:115]
	v_mfma_f32_16x16x32_bf16 v[104:107], v[166:169], v[174:177], v[104:107]
	v_mfma_f32_16x16x32_bf16 v[92:95], v[158:161], v[182:185], v[92:95]
	v_mfma_f32_16x16x32_bf16 v[88:91], v[166:169], v[182:185], v[88:91]
	v_mfma_f32_16x16x32_bf16 v[76:79], v[158:161], v[202:205], v[76:79]
	v_mfma_f32_16x16x32_bf16 v[72:75], v[166:169], v[202:205], v[72:75]
	v_mfma_f32_16x16x32_bf16 v[68:71], v[158:161], v[210:213], v[68:71]
	v_mfma_f32_16x16x32_bf16 v[64:67], v[166:169], v[210:213], v[64:67]
	v_mfma_f32_16x16x32_bf16 v[112:115], v[162:165], v[178:181], v[112:115]
	v_mfma_f32_16x16x32_bf16 v[104:107], v[170:173], v[178:181], v[104:107]
	v_mfma_f32_16x16x32_bf16 v[92:95], v[162:165], v[198:201], v[92:95]
	v_mfma_f32_16x16x32_bf16 v[88:91], v[170:173], v[198:201], v[88:91]
	v_mfma_f32_16x16x32_bf16 v[76:79], v[162:165], v[206:209], v[76:79]
	v_mfma_f32_16x16x32_bf16 v[72:75], v[170:173], v[206:209], v[72:75]
	v_mfma_f32_16x16x32_bf16 v[68:71], v[162:165], v[214:217], v[68:71]
	v_mfma_f32_16x16x32_bf16 v[64:67], v[170:173], v[214:217], v[64:67]
	s_setprio 0
	s_barrier
; #define PG8_STAGE(bufoff, gbase, voff) do { _Pragma("unroll") for (int _i = 0; _i < 2; ++_i) \
;         __builtin_amdgcn_global_load_lds((const unsigned*)((const char*)(gbase) + (voff)[_i]), (LAS unsigned*)(lds + (bufoff) + ldsw + _i * 8192), 16, 0, 0); } while (0)
; #define PG8_LDA(dst, b, h) do { _Pragma("unroll") for (int m = 0; m < 4; ++m) _Pragma("unroll") for (int k = 0; k < 2; ++k) dst[m][k] = *(const LAS bf16x8*)(lds + PG8_SA(b, h) + aoff + m * 2048 + k * 1024); } while (0)
; #define PG8_MMA(ai, bj, At, Bt) do { __builtin_amdgcn_s_setprio(1); _Pragma("unroll") for (int m = 0; m < 4; ++m) _Pragma("unroll") for (int n = 0; n < 2; ++n) _Pragma("unroll") for (int k = 0; k < 2; ++k) \
;         acc[ai][bj][m][n] = __builtin_amdgcn_mfma_f32_16x16x32_bf16(Bt[n][k], At[m][k], acc[ai][bj][m][n], 0, 0, 0); __builtin_amdgcn_s_setprio(0); } while (0)
; #define PG8_WAIT_V(n) asm volatile("s_waitcnt vmcnt(" #n ")" ::: "memory")
; #define PG8_WAIT_L(n) asm volatile("s_waitcnt lgkmcnt(" #n ")" ::: "memory")
; #define PG8_BAR __builtin_amdgcn_s_barrier()
; #define PG8_SCHED __builtin_amdgcn_sched_barrier(0)
; template <class Epi, class Sched>
; __device__ __forceinline__ void gemm_phase(int wv, LAS unsigned char* lds, const Gemm g, const Sched& S, const Epi& E) {
;     ...
;             PG8_LDA(At, 1, 1); PG8_STAGE(PG8_SB(1, 0), b3, voffB); PG8_STAGE(PG8_SB(1, 1), b3 + hstepB, voffB); PG8_STAGE(PG8_SA(1, 0), a3, voffA);
;             PG8_WAIT_V(8); PG8_WAIT_L(0); PG8_BAR; PG8_MMA(1, 0, At, B0); PG8_MMA(1, 1, At, B1); PG8_BAR; PG8_SCHED;
;         }
;         if (wr == 0) PG8_BAR;
	s_add_i32 s24, s95, s28
	v_lshl_add_u64 v[186:187], v[186:187], 0, s[74:75]
	s_mov_b32 m0, s24
	ds_read_b128 v[174:177], v141 offset:49152
	ds_read_b128 v[178:181], v141 offset:50176
	ds_read_b128 v[182:185], v141 offset:51200
	ds_read_b128 v[198:201], v141 offset:52224
	ds_read_b128 v[202:205], v141 offset:53248
	ds_read_b128 v[206:209], v141 offset:54272
	ds_read_b128 v[210:213], v141 offset:55296
	ds_read_b128 v[214:217], v141 offset:56320
	global_load_lds_dwordx4 v[186:187], off
	s_add_i32 m0, s24, 0x2000
	s_add_u32 s22, s22, 0x4080
	v_lshl_add_u64 v[186:187], v[218:219], 0, s[74:75]
	s_addc_u32 s23, s23, 0
	s_add_i32 s24, s44, s28
	global_load_lds_dwordx4 v[186:187], off
	v_lshl_add_u64 v[186:187], s[22:23], 0, v[188:189]
	s_mov_b32 m0, s24
	s_nop 0
	global_load_lds_dwordx4 v[186:187], off
	v_lshl_add_u64 v[186:187], s[22:23], 0, v[128:129]
	s_add_i32 m0, s24, 0x2000
	s_nop 0
	global_load_lds_dwordx4 v[186:187], off
	v_lshl_add_u64 v[186:187], v[220:221], 0, s[74:75]
	s_mov_b32 m0, s35
	s_nop 0
	global_load_lds_dwordx4 v[186:187], off
	v_lshl_add_u64 v[186:187], v[222:223], 0, s[74:75]
	s_mov_b32 m0, s36
	s_nop 0
	global_load_lds_dwordx4 v[186:187], off
	s_waitcnt vmcnt(8)
	s_waitcnt lgkmcnt(0)
	s_setprio 1
	s_waitcnt lgkmcnt(0)
	v_mfma_f32_16x16x32_bf16 v[60:63], v[142:145], v[174:177], v[60:63]
	v_mfma_f32_16x16x32_bf16 v[56:59], v[150:153], v[174:177], v[56:59]
	v_mfma_f32_16x16x32_bf16 v[52:55], v[142:145], v[182:185], v[52:55]
	v_mfma_f32_16x16x32_bf16 v[48:51], v[150:153], v[182:185], v[48:51]
	v_mfma_f32_16x16x32_bf16 v[36:39], v[142:145], v[202:205], v[36:39]
	v_mfma_f32_16x16x32_bf16 v[32:35], v[150:153], v[202:205], v[32:35]
	v_mfma_f32_16x16x32_bf16 v[20:23], v[142:145], v[210:213], v[20:23]
	v_mfma_f32_16x16x32_bf16 v[16:19], v[150:153], v[210:213], v[16:19]
	s_barrier
	v_mfma_f32_16x16x32_bf16 v[60:63], v[146:149], v[178:181], v[60:63]
	v_mfma_f32_16x16x32_bf16 v[56:59], v[154:157], v[178:181], v[56:59]
	v_mfma_f32_16x16x32_bf16 v[52:55], v[146:149], v[198:201], v[52:55]
	v_mfma_f32_16x16x32_bf16 v[48:51], v[154:157], v[198:201], v[48:51]
	v_mfma_f32_16x16x32_bf16 v[36:39], v[146:149], v[206:209], v[36:39]
	v_mfma_f32_16x16x32_bf16 v[32:35], v[154:157], v[206:209], v[32:35]
	v_mfma_f32_16x16x32_bf16 v[20:23], v[146:149], v[214:217], v[20:23]
	v_mfma_f32_16x16x32_bf16 v[16:19], v[154:157], v[214:217], v[16:19]
	s_setprio 0
	s_setprio 1
	v_mfma_f32_16x16x32_bf16 v[44:47], v[158:161], v[174:177], v[44:47]
	v_mfma_f32_16x16x32_bf16 v[40:43], v[166:169], v[174:177], v[40:43]
	v_mfma_f32_16x16x32_bf16 v[28:31], v[158:161], v[182:185], v[28:31]
	v_mfma_f32_16x16x32_bf16 v[24:27], v[166:169], v[182:185], v[24:27]
	v_mfma_f32_16x16x32_bf16 v[12:15], v[158:161], v[202:205], v[12:15]
	v_mfma_f32_16x16x32_bf16 v[8:11], v[166:169], v[202:205], v[8:11]
	v_mfma_f32_16x16x32_bf16 v[4:7], v[158:161], v[210:213], v[4:7]
	v_mfma_f32_16x16x32_bf16 v[0:3], v[166:169], v[210:213], v[0:3]
	v_mfma_f32_16x16x32_bf16 v[44:47], v[162:165], v[178:181], v[44:47]
	v_mfma_f32_16x16x32_bf16 v[40:43], v[170:173], v[178:181], v[40:43]
	v_mfma_f32_16x16x32_bf16 v[28:31], v[162:165], v[198:201], v[28:31]
	v_mfma_f32_16x16x32_bf16 v[24:27], v[170:173], v[198:201], v[24:27]
	v_mfma_f32_16x16x32_bf16 v[12:15], v[162:165], v[206:209], v[12:15]
	v_mfma_f32_16x16x32_bf16 v[8:11], v[170:173], v[206:209], v[8:11]
	v_mfma_f32_16x16x32_bf16 v[4:7], v[162:165], v[214:217], v[4:7]
	v_mfma_f32_16x16x32_bf16 v[0:3], v[170:173], v[214:217], v[0:3]
	s_setprio 0
	s_barrier
	s_add_i32 s43, s43, 2
	s_add_u32 s20, s20, 0x100
	s_addc_u32 s21, s21, 0
	s_add_u32 s41, s41, 0x100
	s_addc_u32 s42, s42, 0
	s_cmp_gt_u32 s43, 13
	s_cbranch_scc0 .LBB0_781
	s_and_b64 vcc, exec, s[10:11]
	s_cbranch_vccz .LBB0_784
	s_barrier

; #define PG8_STAGE(bufoff, gbase, voff) do { _Pragma("unroll") for (int _i = 0; _i < 2; ++_i) \
;         __builtin_amdgcn_global_load_lds((const unsigned*)((const char*)(gbase) + (voff)[_i]), (LAS unsigned*)(lds + (bufoff) + ldsw + _i * 8192), 16, 0, 0); } while (0)
; #define PG8_LDA(dst, b, h) do { _Pragma("unroll") for (int m = 0; m < 4; ++m) _Pragma("unroll") for (int k = 0; k < 2; ++k) dst[m][k] = *(const LAS bf16x8*)(lds + PG8_SA(b, h) + aoff + m * 2048 + k * 1024); } while (0)
; #define PG8_LDB(dst, b, h) do { _Pragma("unroll") for (int n = 0; n < 2; ++n) _Pragma("unroll") for (int k = 0; k < 2; ++k) dst[n][k] = *(const LAS bf16x8*)(lds + PG8_SB(b, h) + boff + n * 2048 + k * 1024); } while (0)
; #define PG8_MMA(ai, bj, At, Bt) do { __builtin_amdgcn_s_setprio(1); _Pragma("unroll") for (int m = 0; m < 4; ++m) _Pragma("unroll") for (int n = 0; n < 2; ++n) _Pragma("unroll") for (int k = 0; k < 2; ++k) \
;         acc[ai][bj][m][n] = __builtin_amdgcn_mfma_f32_16x16x32_bf16(Bt[n][k], At[m][k], acc[ai][bj][m][n], 0, 0, 0); __builtin_amdgcn_s_setprio(0); } while (0)
; #define PG8_WAIT_V(n) asm volatile("s_waitcnt vmcnt(" #n ")" ::: "memory")
; #define PG8_WAIT_L(n) asm volatile("s_waitcnt lgkmcnt(" #n ")" ::: "memory")
; #define PG8_BAR __builtin_amdgcn_s_barrier()
; #define PG8_SCHED __builtin_amdgcn_sched_barrier(0)
; template <class Epi, class Sched>
; __device__ __forceinline__ void gemm_phase(int wv, LAS unsigned char* lds, const Gemm g, const Sched& S, const Epi& E) {
;     ...
;         for (int t = 0; t < nt; t += 2) {
;             const bool last = (t == nt - 2);
;             const char* a1 = cA + (size_t)(t + 1) * kstep;
;             const char* a2 = last ? nA : cA + (size_t)(t + 2) * kstep; const char* b2 = last ? nB : cB + (size_t)(t + 2) * kstep;
;             const char* a3 = a2 + kstep; const char* b3 = b2 + kstep;
;             PG8_LDB(B0, 0, 0); PG8_LDB(B1, 0, 1); PG8_SCHED; PG8_LDA(At, 0, 0); PG8_STAGE(PG8_SA(1, 1), a1 + hstep, voffA);
;             PG8_WAIT_V(8); PG8_WAIT_L(0); PG8_BAR; PG8_MMA(0, 0, At, B0); PG8_MMA(0, 1, At, B1); PG8_BAR; PG8_SCHED;
;             PG8_LDA(At, 0, 1); PG8_STAGE(PG8_SB(0, 0), b2, voffB); PG8_STAGE(PG8_SB(0, 1), b2 + hstepB, voffB); PG8_STAGE(PG8_SA(0, 0), a2, voffA);
;             PG8_WAIT_V(8); PG8_WAIT_L(0); PG8_BAR; PG8_MMA(1, 0, At, B0); PG8_MMA(1, 1, At, B1); PG8_BAR; PG8_SCHED;
.LBB0_801:
	s_add_u32 s20, s18, 0xfffe0080
	s_addc_u32 s21, s19, -1
	s_add_i32 s44, 0, 0x10000
	s_cmp_eq_u32 s43, 4
	s_cselect_b32 s23, s11, s21
	s_cselect_b32 s22, s39, s20
	s_cselect_b32 s21, s13, s42
	s_cselect_b32 s20, s40, s41
	s_add_i32 s46, 0, 0x14000
	v_add_u32_e32 v154, s44, v139
	v_add_u32_e32 v170, s46, v139
	ds_read_b128 v[142:145], v154
	ds_read_b128 v[146:149], v154 offset:1024
	ds_read_b128 v[150:153], v154 offset:2048
	ds_read_b128 v[154:157], v154 offset:3072
	ds_read_b128 v[158:161], v170
	ds_read_b128 v[162:165], v170 offset:1024
	ds_read_b128 v[166:169], v170 offset:2048
	ds_read_b128 v[170:173], v170 offset:3072
	v_lshl_add_u64 v[186:187], s[18:19], 0, v[134:135]
	s_add_i32 m0, s29, 0xc000
	ds_read_b128 v[174:177], v141
	ds_read_b128 v[178:181], v141 offset:1024
	ds_read_b128 v[182:185], v141 offset:2048
	ds_read_b128 v[198:201], v141 offset:3072
	ds_read_b128 v[202:205], v141 offset:4096
	ds_read_b128 v[206:209], v141 offset:5120
	ds_read_b128 v[210:213], v141 offset:6144
	ds_read_b128 v[214:217], v141 offset:7168
	global_load_lds_dwordx4 v[186:187], off
	v_lshl_add_u64 v[186:187], s[18:19], 0, v[136:137]
	s_add_i32 m0, s29, 0xe000
	s_nop 0
	global_load_lds_dwordx4 v[186:187], off
	s_waitcnt vmcnt(8)
	s_waitcnt lgkmcnt(0)
	s_setprio 1
	s_waitcnt lgkmcnt(0)
	v_mfma_f32_16x16x32_bf16 v[124:127], v[142:145], v[174:177], v[124:127]
	v_mfma_f32_16x16x32_bf16 v[120:123], v[150:153], v[174:177], v[120:123]
	v_mfma_f32_16x16x32_bf16 v[116:119], v[142:145], v[182:185], v[116:119]
	v_mfma_f32_16x16x32_bf16 v[108:111], v[150:153], v[182:185], v[108:111]
	v_mfma_f32_16x16x32_bf16 v[100:103], v[142:145], v[202:205], v[100:103]
	v_mfma_f32_16x16x32_bf16 v[96:99], v[150:153], v[202:205], v[96:99]
	v_mfma_f32_16x16x32_bf16 v[84:87], v[142:145], v[210:213], v[84:87]
	v_mfma_f32_16x16x32_bf16 v[80:83], v[150:153], v[210:213], v[80:83]
	s_barrier
	v_mfma_f32_16x16x32_bf16 v[124:127], v[146:149], v[178:181], v[124:127]
	v_mfma_f32_16x16x32_bf16 v[120:123], v[154:157], v[178:181], v[120:123]
	v_mfma_f32_16x16x32_bf16 v[116:119], v[146:149], v[198:201], v[116:119]
	v_mfma_f32_16x16x32_bf16 v[108:111], v[154:157], v[198:201], v[108:111]
	v_mfma_f32_16x16x32_bf16 v[100:103], v[146:149], v[206:209], v[100:103]
	v_mfma_f32_16x16x32_bf16 v[96:99], v[154:157], v[206:209], v[96:99]
	v_mfma_f32_16x16x32_bf16 v[84:87], v[146:149], v[214:217], v[84:87]
	v_mfma_f32_16x16x32_bf16 v[80:83], v[154:157], v[214:217], v[80:83]
	s_setprio 0
	s_setprio 1
	v_mfma_f32_16x16x32_bf16 v[112:115], v[158:161], v[174:177], v[112:115]
	v_mfma_f32_16x16x32_bf16 v[104:107], v[166:169], v[174:177], v[104:107]
	v_mfma_f32_16x16x32_bf16 v[92:95], v[158:161], v[182:185], v[92:95]
	v_mfma_f32_16x16x32_bf16 v[88:91], v[166:169], v[182:185], v[88:91]
	v_mfma_f32_16x16x32_bf16 v[76:79], v[158:161], v[202:205], v[76:79]
	v_mfma_f32_16x16x32_bf16 v[72:75], v[166:169], v[202:205], v[72:75]
	v_mfma_f32_16x16x32_bf16 v[68:71], v[158:161], v[210:213], v[68:71]
	v_mfma_f32_16x16x32_bf16 v[64:67], v[166:169], v[210:213], v[64:67]
	v_mfma_f32_16x16x32_bf16 v[112:115], v[162:165], v[178:181], v[112:115]
	v_mfma_f32_16x16x32_bf16 v[104:107], v[170:173], v[178:181], v[104:107]
	v_mfma_f32_16x16x32_bf16 v[92:95], v[162:165], v[198:201], v[92:95]
	v_mfma_f32_16x16x32_bf16 v[88:91], v[170:173], v[198:201], v[88:91]
	v_mfma_f32_16x16x32_bf16 v[76:79], v[162:165], v[206:209], v[76:79]
	v_mfma_f32_16x16x32_bf16 v[72:75], v[170:173], v[206:209], v[72:75]
	v_mfma_f32_16x16x32_bf16 v[68:71], v[162:165], v[214:217], v[68:71]
	v_mfma_f32_16x16x32_bf16 v[64:67], v[170:173], v[214:217], v[64:67]
	s_setprio 0
	s_barrier
	s_add_i32 s44, s44, s28
	v_lshl_add_u64 v[186:187], s[20:21], 0, v[188:189]
	s_mov_b32 m0, s44
	ds_read_b128 v[174:177], v141 offset:16384
	ds_read_b128 v[178:181], v141 offset:17408
	ds_read_b128 v[182:185], v141 offset:18432
	ds_read_b128 v[198:201], v141 offset:19456
	ds_read_b128 v[202:205], v141 offset:20480
	ds_read_b128 v[206:209], v141 offset:21504
	ds_read_b128 v[210:213], v141 offset:22528
	ds_read_b128 v[214:217], v141 offset:23552
	global_load_lds_dwordx4 v[186:187], off
	s_add_i32 m0, s44, 0x2000
	s_add_u32 s44, s20, 0x2000
	v_lshl_add_u64 v[218:219], s[20:21], 0, v[128:129]
	s_addc_u32 s45, s21, 0
	s_add_i32 s46, s46, s28
	global_load_lds_dwordx4 v[218:219], off
	v_lshl_add_u64 v[220:221], s[44:45], 0, v[188:189]
	s_mov_b32 m0, s46
	v_lshl_add_u64 v[222:223], s[22:23], 0, v[130:131]
	global_load_lds_dwordx4 v[220:221], off
	v_lshl_add_u64 v[220:221], s[44:45], 0, v[128:129]
	s_add_i32 m0, s46, 0x2000
	s_nop 0
	global_load_lds_dwordx4 v[220:221], off
	v_lshl_add_u64 v[220:221], s[22:23], 0, v[132:133]
	s_mov_b32 m0, s29
	s_nop 0
	global_load_lds_dwordx4 v[220:221], off
	s_mov_b32 m0, s30
	s_nop 0
	global_load_lds_dwordx4 v[222:223], off
	s_waitcnt vmcnt(8)
	s_waitcnt lgkmcnt(0)
	s_setprio 1
	s_waitcnt lgkmcnt(0)
	v_mfma_f32_16x16x32_bf16 v[60:63], v[142:145], v[174:177], v[60:63]
	v_mfma_f32_16x16x32_bf16 v[56:59], v[150:153], v[174:177], v[56:59]
	v_mfma_f32_16x16x32_bf16 v[52:55], v[142:145], v[182:185], v[52:55]
	v_mfma_f32_16x16x32_bf16 v[48:51], v[150:153], v[182:185], v[48:51]
	v_mfma_f32_16x16x32_bf16 v[36:39], v[142:145], v[202:205], v[36:39]
	v_mfma_f32_16x16x32_bf16 v[32:35], v[150:153], v[202:205], v[32:35]
	v_mfma_f32_16x16x32_bf16 v[20:23], v[142:145], v[210:213], v[20:23]
	v_mfma_f32_16x16x32_bf16 v[16:19], v[150:153], v[210:213], v[16:19]
	s_barrier
; #define PG8_STAGE(bufoff, gbase, voff) do { _Pragma("unroll") for (int _i = 0; _i < 2; ++_i) \
;         __builtin_amdgcn_global_load_lds((const unsigned*)((const char*)(gbase) + (voff)[_i]), (LAS unsigned*)(lds + (bufoff) + ldsw + _i * 8192), 16, 0, 0); } while (0)
; #define PG8_LDA(dst, b, h) do { _Pragma("unroll") for (int m = 0; m < 4; ++m) _Pragma("unroll") for (int k = 0; k < 2; ++k) dst[m][k] = *(const LAS bf16x8*)(lds + PG8_SA(b, h) + aoff + m * 2048 + k * 1024); } while (0)
; #define PG8_LDB(dst, b, h) do { _Pragma("unroll") for (int n = 0; n < 2; ++n) _Pragma("unroll") for (int k = 0; k < 2; ++k) dst[n][k] = *(const LAS bf16x8*)(lds + PG8_SB(b, h) + boff + n * 2048 + k * 1024); } while (0)
; #define PG8_MMA(ai, bj, At, Bt) do { __builtin_amdgcn_s_setprio(1); _Pragma("unroll") for (int m = 0; m < 4; ++m) _Pragma("unroll") for (int n = 0; n < 2; ++n) _Pragma("unroll") for (int k = 0; k < 2; ++k) \
;         acc[ai][bj][m][n] = __builtin_amdgcn_mfma_f32_16x16x32_bf16(Bt[n][k], At[m][k], acc[ai][bj][m][n], 0, 0, 0); __builtin_amdgcn_s_setprio(0); } while (0)
; #define PG8_WAIT_V(n) asm volatile("s_waitcnt vmcnt(" #n ")" ::: "memory")
; #define PG8_WAIT_L(n) asm volatile("s_waitcnt lgkmcnt(" #n ")" ::: "memory")
; #define PG8_BAR __builtin_amdgcn_s_barrier()
; #define PG8_SCHED __builtin_amdgcn_sched_barrier(0)
; template <class Epi, class Sched>
; __device__ __forceinline__ void gemm_phase(int wv, LAS unsigned char* lds, const Gemm g, const Sched& S, const Epi& E) {
;     ...
;             PG8_WAIT_V(8); PG8_WAIT_L(0); PG8_BAR; PG8_MMA(1, 0, At, B0); PG8_MMA(1, 1, At, B1); PG8_BAR; PG8_SCHED;
;             PG8_LDB(B0, 1, 0); PG8_LDB(B1, 1, 1); PG8_SCHED; PG8_LDA(At, 1, 0); PG8_STAGE(PG8_SA(0, 1), a2 + hstep, voffA);
;             PG8_WAIT_V(8); PG8_WAIT_L(0); PG8_BAR; PG8_MMA(0, 0, At, B0); PG8_MMA(0, 1, At, B1); PG8_BAR; PG8_SCHED;
	v_mfma_f32_16x16x32_bf16 v[60:63], v[146:149], v[178:181], v[60:63]
	v_mfma_f32_16x16x32_bf16 v[56:59], v[154:157], v[178:181], v[56:59]
	v_mfma_f32_16x16x32_bf16 v[52:55], v[146:149], v[198:201], v[52:55]
	v_mfma_f32_16x16x32_bf16 v[48:51], v[154:157], v[198:201], v[48:51]
	v_mfma_f32_16x16x32_bf16 v[36:39], v[146:149], v[206:209], v[36:39]
	v_mfma_f32_16x16x32_bf16 v[32:35], v[154:157], v[206:209], v[32:35]
	v_mfma_f32_16x16x32_bf16 v[20:23], v[146:149], v[214:217], v[20:23]
	v_mfma_f32_16x16x32_bf16 v[16:19], v[154:157], v[214:217], v[16:19]
	s_setprio 0
	s_setprio 1
	v_mfma_f32_16x16x32_bf16 v[44:47], v[158:161], v[174:177], v[44:47]
	v_mfma_f32_16x16x32_bf16 v[40:43], v[166:169], v[174:177], v[40:43]
	v_mfma_f32_16x16x32_bf16 v[28:31], v[158:161], v[182:185], v[28:31]
	v_mfma_f32_16x16x32_bf16 v[24:27], v[166:169], v[182:185], v[24:27]
	v_mfma_f32_16x16x32_bf16 v[12:15], v[158:161], v[202:205], v[12:15]
	v_mfma_f32_16x16x32_bf16 v[8:11], v[166:169], v[202:205], v[8:11]
	v_mfma_f32_16x16x32_bf16 v[4:7], v[158:161], v[210:213], v[4:7]
	v_mfma_f32_16x16x32_bf16 v[0:3], v[166:169], v[210:213], v[0:3]
	v_mfma_f32_16x16x32_bf16 v[44:47], v[162:165], v[178:181], v[44:47]
	v_mfma_f32_16x16x32_bf16 v[40:43], v[170:173], v[178:181], v[40:43]
	v_mfma_f32_16x16x32_bf16 v[28:31], v[162:165], v[198:201], v[28:31]
	v_mfma_f32_16x16x32_bf16 v[24:27], v[170:173], v[198:201], v[24:27]
	v_mfma_f32_16x16x32_bf16 v[12:15], v[162:165], v[206:209], v[12:15]
	v_mfma_f32_16x16x32_bf16 v[8:11], v[170:173], v[206:209], v[8:11]
	v_mfma_f32_16x16x32_bf16 v[4:7], v[162:165], v[214:217], v[4:7]
	v_mfma_f32_16x16x32_bf16 v[0:3], v[170:173], v[214:217], v[0:3]
	s_setprio 0
	s_barrier
	s_add_i32 s44, 0, 0x1c000
	v_add_u32_e32 v154, s95, v139
	v_add_u32_e32 v170, s44, v139
	ds_read_b128 v[142:145], v154
	ds_read_b128 v[146:149], v154 offset:1024
	ds_read_b128 v[150:153], v154 offset:2048
	ds_read_b128 v[154:157], v154 offset:3072
	ds_read_b128 v[158:161], v170
	ds_read_b128 v[162:165], v170 offset:1024
	ds_read_b128 v[166:169], v170 offset:2048
	ds_read_b128 v[170:173], v170 offset:3072
	s_add_u32 s22, s22, 0x20000
	s_addc_u32 s23, s23, 0
	s_mov_b32 m0, s31
	v_lshl_add_u64 v[228:229], s[22:23], 0, v[132:133]
	ds_read_b128 v[174:177], v141 offset:32768
	ds_read_b128 v[178:181], v141 offset:33792
	ds_read_b128 v[182:185], v141 offset:34816
	ds_read_b128 v[198:201], v141 offset:35840
	ds_read_b128 v[202:205], v141 offset:36864
	ds_read_b128 v[206:209], v141 offset:37888
	ds_read_b128 v[210:213], v141 offset:38912
	ds_read_b128 v[214:217], v141 offset:39936
	global_load_lds_dwordx4 v[228:229], off
	v_lshl_add_u64 v[228:229], s[22:23], 0, v[130:131]
	s_mov_b32 m0, s34
	s_nop 0
	global_load_lds_dwordx4 v[228:229], off
	s_waitcnt vmcnt(8)
	s_waitcnt lgkmcnt(0)
	s_setprio 1
	s_waitcnt lgkmcnt(0)
	v_mfma_f32_16x16x32_bf16 v[124:127], v[142:145], v[174:177], v[124:127]
	v_mfma_f32_16x16x32_bf16 v[120:123], v[150:153], v[174:177], v[120:123]
	v_mfma_f32_16x16x32_bf16 v[116:119], v[142:145], v[182:185], v[116:119]
	v_mfma_f32_16x16x32_bf16 v[108:111], v[150:153], v[182:185], v[108:111]
	v_mfma_f32_16x16x32_bf16 v[100:103], v[142:145], v[202:205], v[100:103]
	v_mfma_f32_16x16x32_bf16 v[96:99], v[150:153], v[202:205], v[96:99]
	v_mfma_f32_16x16x32_bf16 v[84:87], v[142:145], v[210:213], v[84:87]
	v_mfma_f32_16x16x32_bf16 v[80:83], v[150:153], v[210:213], v[80:83]
	s_barrier
	v_mfma_f32_16x16x32_bf16 v[124:127], v[146:149], v[178:181], v[124:127]
	v_mfma_f32_16x16x32_bf16 v[120:123], v[154:157], v[178:181], v[120:123]
	v_mfma_f32_16x16x32_bf16 v[116:119], v[146:149], v[198:201], v[116:119]
	v_mfma_f32_16x16x32_bf16 v[108:111], v[154:157], v[198:201], v[108:111]
	v_mfma_f32_16x16x32_bf16 v[100:103], v[146:149], v[206:209], v[100:103]
	v_mfma_f32_16x16x32_bf16 v[96:99], v[154:157], v[206:209], v[96:99]
	v_mfma_f32_16x16x32_bf16 v[84:87], v[146:149], v[214:217], v[84:87]
	v_mfma_f32_16x16x32_bf16 v[80:83], v[154:157], v[214:217], v[80:83]
	s_setprio 0
	s_setprio 1
	v_mfma_f32_16x16x32_bf16 v[112:115], v[158:161], v[174:177], v[112:115]
	v_mfma_f32_16x16x32_bf16 v[104:107], v[166:169], v[174:177], v[104:107]
	v_mfma_f32_16x16x32_bf16 v[92:95], v[158:161], v[182:185], v[92:95]
	v_mfma_f32_16x16x32_bf16 v[88:91], v[166:169], v[182:185], v[88:91]
	v_mfma_f32_16x16x32_bf16 v[76:79], v[158:161], v[202:205], v[76:79]
	v_mfma_f32_16x16x32_bf16 v[72:75], v[166:169], v[202:205], v[72:75]
	v_mfma_f32_16x16x32_bf16 v[68:71], v[158:161], v[210:213], v[68:71]
	v_mfma_f32_16x16x32_bf16 v[64:67], v[166:169], v[210:213], v[64:67]
	v_mfma_f32_16x16x32_bf16 v[112:115], v[162:165], v[178:181], v[112:115]
	v_mfma_f32_16x16x32_bf16 v[104:107], v[170:173], v[178:181], v[104:107]
	v_mfma_f32_16x16x32_bf16 v[92:95], v[162:165], v[198:201], v[92:95]
	v_mfma_f32_16x16x32_bf16 v[88:91], v[170:173], v[198:201], v[88:91]
	v_mfma_f32_16x16x32_bf16 v[76:79], v[162:165], v[206:209], v[76:79]
	v_mfma_f32_16x16x32_bf16 v[72:75], v[170:173], v[206:209], v[72:75]
	v_mfma_f32_16x16x32_bf16 v[68:71], v[162:165], v[214:217], v[68:71]
	v_mfma_f32_16x16x32_bf16 v[64:67], v[170:173], v[214:217], v[64:67]
	s_setprio 0
	s_barrier
; #define PG8_STAGE(bufoff, gbase, voff) do { _Pragma("unroll") for (int _i = 0; _i < 2; ++_i) \
;         __builtin_amdgcn_global_load_lds((const unsigned*)((const char*)(gbase) + (voff)[_i]), (LAS unsigned*)(lds + (bufoff) + ldsw + _i * 8192), 16, 0, 0); } while (0)
; #define PG8_LDA(dst, b, h) do { _Pragma("unroll") for (int m = 0; m < 4; ++m) _Pragma("unroll") for (int k = 0; k < 2; ++k) dst[m][k] = *(const LAS bf16x8*)(lds + PG8_SA(b, h) + aoff + m * 2048 + k * 1024); } while (0)
; #define PG8_MMA(ai, bj, At, Bt) do { __builtin_amdgcn_s_setprio(1); _Pragma("unroll") for (int m = 0; m < 4; ++m) _Pragma("unroll") for (int n = 0; n < 2; ++n) _Pragma("unroll") for (int k = 0; k < 2; ++k) \
;         acc[ai][bj][m][n] = __builtin_amdgcn_mfma_f32_16x16x32_bf16(Bt[n][k], At[m][k], acc[ai][bj][m][n], 0, 0, 0); __builtin_amdgcn_s_setprio(0); } while (0)
; #define PG8_WAIT_V(n) asm volatile("s_waitcnt vmcnt(" #n ")" ::: "memory")
; #define PG8_WAIT_L(n) asm volatile("s_waitcnt lgkmcnt(" #n ")" ::: "memory")
; #define PG8_BAR __builtin_amdgcn_s_barrier()
; #define PG8_SCHED __builtin_amdgcn_sched_barrier(0)
; template <class Epi, class Sched>
; __device__ __forceinline__ void gemm_phase(int wv, LAS unsigned char* lds, const Gemm g, const Sched& S, const Epi& E) {
;     ...
;             PG8_LDA(At, 1, 1); PG8_STAGE(PG8_SB(1, 0), b3, voffB); PG8_STAGE(PG8_SB(1, 1), b3 + hstepB, voffB); PG8_STAGE(PG8_SA(1, 0), a3, voffA);
;             PG8_WAIT_V(8); PG8_WAIT_L(0); PG8_BAR; PG8_MMA(1, 0, At, B0); PG8_MMA(1, 1, At, B1); PG8_BAR; PG8_SCHED;
;         }
;         if (wr == 0) PG8_BAR;
	s_add_i32 s22, s95, s28
	v_lshl_add_u64 v[186:187], v[186:187], 0, s[74:75]
	s_mov_b32 m0, s22
	ds_read_b128 v[174:177], v141 offset:49152
	ds_read_b128 v[178:181], v141 offset:50176
	ds_read_b128 v[182:185], v141 offset:51200
	ds_read_b128 v[198:201], v141 offset:52224
	ds_read_b128 v[202:205], v141 offset:53248
	ds_read_b128 v[206:209], v141 offset:54272
	ds_read_b128 v[210:213], v141 offset:55296
	ds_read_b128 v[214:217], v141 offset:56320
	global_load_lds_dwordx4 v[186:187], off
	s_add_i32 m0, s22, 0x2000
	s_add_u32 s20, s20, 0x2080
	v_lshl_add_u64 v[186:187], v[218:219], 0, s[74:75]
	s_addc_u32 s21, s21, 0
	s_add_i32 s22, s44, s28
	global_load_lds_dwordx4 v[186:187], off
	v_lshl_add_u64 v[186:187], s[20:21], 0, v[188:189]
	s_mov_b32 m0, s22
	s_nop 0
	global_load_lds_dwordx4 v[186:187], off
	v_lshl_add_u64 v[186:187], s[20:21], 0, v[128:129]
	s_add_i32 m0, s22, 0x2000
	s_nop 0
	global_load_lds_dwordx4 v[186:187], off
	v_lshl_add_u64 v[186:187], v[220:221], 0, s[74:75]
	s_mov_b32 m0, s35
	s_nop 0
	global_load_lds_dwordx4 v[186:187], off
	v_lshl_add_u64 v[186:187], v[222:223], 0, s[74:75]
	s_mov_b32 m0, s36
	s_nop 0
	global_load_lds_dwordx4 v[186:187], off
	s_waitcnt vmcnt(8)
	s_waitcnt lgkmcnt(0)
	s_setprio 1
	s_waitcnt lgkmcnt(0)
	v_mfma_f32_16x16x32_bf16 v[60:63], v[142:145], v[174:177], v[60:63]
	v_mfma_f32_16x16x32_bf16 v[56:59], v[150:153], v[174:177], v[56:59]
	v_mfma_f32_16x16x32_bf16 v[52:55], v[142:145], v[182:185], v[52:55]
	v_mfma_f32_16x16x32_bf16 v[48:51], v[150:153], v[182:185], v[48:51]
	v_mfma_f32_16x16x32_bf16 v[36:39], v[142:145], v[202:205], v[36:39]
	v_mfma_f32_16x16x32_bf16 v[32:35], v[150:153], v[202:205], v[32:35]
	v_mfma_f32_16x16x32_bf16 v[20:23], v[142:145], v[210:213], v[20:23]
	v_mfma_f32_16x16x32_bf16 v[16:19], v[150:153], v[210:213], v[16:19]
	s_barrier
	v_mfma_f32_16x16x32_bf16 v[60:63], v[146:149], v[178:181], v[60:63]
	v_mfma_f32_16x16x32_bf16 v[56:59], v[154:157], v[178:181], v[56:59]
	v_mfma_f32_16x16x32_bf16 v[52:55], v[146:149], v[198:201], v[52:55]
	v_mfma_f32_16x16x32_bf16 v[48:51], v[154:157], v[198:201], v[48:51]
	v_mfma_f32_16x16x32_bf16 v[36:39], v[146:149], v[206:209], v[36:39]
	v_mfma_f32_16x16x32_bf16 v[32:35], v[154:157], v[206:209], v[32:35]
	v_mfma_f32_16x16x32_bf16 v[20:23], v[146:149], v[214:217], v[20:23]
	v_mfma_f32_16x16x32_bf16 v[16:19], v[154:157], v[214:217], v[16:19]
	s_setprio 0
	s_setprio 1
	v_mfma_f32_16x16x32_bf16 v[44:47], v[158:161], v[174:177], v[44:47]
	v_mfma_f32_16x16x32_bf16 v[40:43], v[166:169], v[174:177], v[40:43]
	v_mfma_f32_16x16x32_bf16 v[28:31], v[158:161], v[182:185], v[28:31]
	v_mfma_f32_16x16x32_bf16 v[24:27], v[166:169], v[182:185], v[24:27]
	v_mfma_f32_16x16x32_bf16 v[12:15], v[158:161], v[202:205], v[12:15]
	v_mfma_f32_16x16x32_bf16 v[8:11], v[166:169], v[202:205], v[8:11]
	v_mfma_f32_16x16x32_bf16 v[4:7], v[158:161], v[210:213], v[4:7]
	v_mfma_f32_16x16x32_bf16 v[0:3], v[166:169], v[210:213], v[0:3]
	v_mfma_f32_16x16x32_bf16 v[44:47], v[162:165], v[178:181], v[44:47]
	v_mfma_f32_16x16x32_bf16 v[40:43], v[170:173], v[178:181], v[40:43]
	v_mfma_f32_16x16x32_bf16 v[28:31], v[162:165], v[198:201], v[28:31]
	v_mfma_f32_16x16x32_bf16 v[24:27], v[170:173], v[198:201], v[24:27]
	v_mfma_f32_16x16x32_bf16 v[12:15], v[162:165], v[206:209], v[12:15]
	v_mfma_f32_16x16x32_bf16 v[8:11], v[170:173], v[206:209], v[8:11]
	v_mfma_f32_16x16x32_bf16 v[4:7], v[162:165], v[214:217], v[4:7]
	v_mfma_f32_16x16x32_bf16 v[0:3], v[170:173], v[214:217], v[0:3]
	s_setprio 0
	s_barrier
	s_add_i32 s43, s43, 2
	s_add_u32 s18, s18, 0x100
	s_addc_u32 s19, s19, 0
	s_add_u32 s41, s41, 0x100
	s_addc_u32 s42, s42, 0
	s_cmp_gt_u32 s43, 5
	s_cbranch_scc0 .LBB0_801
	s_and_b64 vcc, exec, s[8:9]
	s_cbranch_vccz .LBB0_804
	s_barrier

; #define PG8_STAGE(bufoff, gbase, voff) do { _Pragma("unroll") for (int _i = 0; _i < 2; ++_i) \
;         __builtin_amdgcn_global_load_lds((const unsigned*)((const char*)(gbase) + (voff)[_i]), (LAS unsigned*)(lds + (bufoff) + ldsw + _i * 8192), 16, 0, 0); } while (0)
; #define PG8_LDA(dst, b, h) do { _Pragma("unroll") for (int m = 0; m < 4; ++m) _Pragma("unroll") for (int k = 0; k < 2; ++k) dst[m][k] = *(const LAS bf16x8*)(lds + PG8_SA(b, h) + aoff + m * 2048 + k * 1024); } while (0)
; #define PG8_LDB(dst, b, h) do { _Pragma("unroll") for (int n = 0; n < 2; ++n) _Pragma("unroll") for (int k = 0; k < 2; ++k) dst[n][k] = *(const LAS bf16x8*)(lds + PG8_SB(b, h) + boff + n * 2048 + k * 1024); } while (0)
; #define PG8_MMA(ai, bj, At, Bt) do { __builtin_amdgcn_s_setprio(1); _Pragma("unroll") for (int m = 0; m < 4; ++m) _Pragma("unroll") for (int n = 0; n < 2; ++n) _Pragma("unroll") for (int k = 0; k < 2; ++k) \
;         acc[ai][bj][m][n] = __builtin_amdgcn_mfma_f32_16x16x32_bf16(Bt[n][k], At[m][k], acc[ai][bj][m][n], 0, 0, 0); __builtin_amdgcn_s_setprio(0); } while (0)
; #define PG8_WAIT_V(n) asm volatile("s_waitcnt vmcnt(" #n ")" ::: "memory")
; #define PG8_WAIT_L(n) asm volatile("s_waitcnt lgkmcnt(" #n ")" ::: "memory")
; #define PG8_BAR __builtin_amdgcn_s_barrier()
; #define PG8_SCHED __builtin_amdgcn_sched_barrier(0)
; template <class Epi, class Sched>
; __device__ __forceinline__ void gemm_phase(int wv, LAS unsigned char* lds, const Gemm g, const Sched& S, const Epi& E) {
;     ...
;         for (int t = 0; t < nt; t += 2) {
;             const bool last = (t == nt - 2);
;             const char* a1 = cA + (size_t)(t + 1) * kstep;
;             const char* a2 = last ? nA : cA + (size_t)(t + 2) * kstep; const char* b2 = last ? nB : cB + (size_t)(t + 2) * kstep;
;             const char* a3 = a2 + kstep; const char* b3 = b2 + kstep;
;             PG8_LDB(B0, 0, 0); PG8_LDB(B1, 0, 1); PG8_SCHED; PG8_LDA(At, 0, 0); PG8_STAGE(PG8_SA(1, 1), a1 + hstep, voffA);
;             PG8_WAIT_V(8); PG8_WAIT_L(0); PG8_BAR; PG8_MMA(0, 0, At, B0); PG8_MMA(0, 1, At, B1); PG8_BAR; PG8_SCHED;
;             PG8_LDA(At, 0, 1); PG8_STAGE(PG8_SB(0, 0), b2, voffB); PG8_STAGE(PG8_SB(0, 1), b2 + hstepB, voffB); PG8_STAGE(PG8_SA(0, 0), a2, voffA);
;             PG8_WAIT_V(8); PG8_WAIT_L(0); PG8_BAR; PG8_MMA(1, 0, At, B0); PG8_MMA(1, 1, At, B1); PG8_BAR; PG8_SCHED;
.LBB0_821:
	s_add_u32 s22, s20, 0xfffc0080
	s_addc_u32 s23, s21, -1
	s_add_i32 s47, 0, 0x10000
	s_cmp_eq_u32 s46, 12
	s_cselect_b32 s25, s13, s23
	s_cselect_b32 s24, s42, s22
	s_cselect_b32 s23, s15, s45
	s_cselect_b32 s22, s43, s44
	s_add_i32 s50, 0, 0x14000
	v_add_u32_e32 v140, s47, v201
	v_add_u32_e32 v156, s50, v201
	ds_read_b128 v[120:123], v140
	ds_read_b128 v[124:127], v140 offset:1024
	ds_read_b128 v[136:139], v140 offset:2048
	ds_read_b128 v[140:143], v140 offset:3072
	ds_read_b128 v[144:147], v156
	ds_read_b128 v[148:151], v156 offset:1024
	ds_read_b128 v[152:155], v156 offset:2048
	ds_read_b128 v[156:159], v156 offset:3072
	v_lshl_add_u64 v[186:187], s[20:21], 0, v[174:175]
	s_add_i32 m0, s31, 0xc000
	ds_read_b128 v[160:163], v203
	ds_read_b128 v[164:167], v203 offset:1024
	ds_read_b128 v[178:181], v203 offset:2048
	ds_read_b128 v[182:185], v203 offset:3072
	ds_read_b128 v[204:207], v203 offset:4096
	ds_read_b128 v[208:211], v203 offset:5120
	ds_read_b128 v[212:215], v203 offset:6144
	ds_read_b128 v[216:219], v203 offset:7168
	global_load_lds_dwordx4 v[186:187], off
	v_lshl_add_u64 v[186:187], s[20:21], 0, v[176:177]
	s_add_i32 m0, s31, 0xe000
	s_nop 0
	global_load_lds_dwordx4 v[186:187], off
	s_waitcnt vmcnt(8)
	s_waitcnt lgkmcnt(0)
	s_setprio 1
	s_waitcnt lgkmcnt(0)
	v_mfma_f32_16x16x32_bf16 v[132:135], v[120:123], v[160:163], v[132:135]
	v_mfma_f32_16x16x32_bf16 v[116:119], v[136:139], v[160:163], v[116:119]
	v_mfma_f32_16x16x32_bf16 v[108:111], v[120:123], v[178:181], v[108:111]
	v_mfma_f32_16x16x32_bf16 v[100:103], v[136:139], v[178:181], v[100:103]
	v_mfma_f32_16x16x32_bf16 v[92:95], v[120:123], v[204:207], v[92:95]
	v_mfma_f32_16x16x32_bf16 v[84:87], v[136:139], v[204:207], v[84:87]
	v_mfma_f32_16x16x32_bf16 v[76:79], v[120:123], v[212:215], v[76:79]
	v_mfma_f32_16x16x32_bf16 v[68:71], v[136:139], v[212:215], v[68:71]
	s_barrier
	v_mfma_f32_16x16x32_bf16 v[132:135], v[124:127], v[164:167], v[132:135]
	v_mfma_f32_16x16x32_bf16 v[116:119], v[140:143], v[164:167], v[116:119]
	v_mfma_f32_16x16x32_bf16 v[108:111], v[124:127], v[182:185], v[108:111]
	v_mfma_f32_16x16x32_bf16 v[100:103], v[140:143], v[182:185], v[100:103]
	v_mfma_f32_16x16x32_bf16 v[92:95], v[124:127], v[208:211], v[92:95]
	v_mfma_f32_16x16x32_bf16 v[84:87], v[140:143], v[208:211], v[84:87]
	v_mfma_f32_16x16x32_bf16 v[76:79], v[124:127], v[216:219], v[76:79]
	v_mfma_f32_16x16x32_bf16 v[68:71], v[140:143], v[216:219], v[68:71]
	s_setprio 0
	s_setprio 1
	v_mfma_f32_16x16x32_bf16 v[128:131], v[144:147], v[160:163], v[128:131]
	v_mfma_f32_16x16x32_bf16 v[112:115], v[152:155], v[160:163], v[112:115]
	v_mfma_f32_16x16x32_bf16 v[104:107], v[144:147], v[178:181], v[104:107]
	v_mfma_f32_16x16x32_bf16 v[96:99], v[152:155], v[178:181], v[96:99]
	v_mfma_f32_16x16x32_bf16 v[88:91], v[144:147], v[204:207], v[88:91]
	v_mfma_f32_16x16x32_bf16 v[80:83], v[152:155], v[204:207], v[80:83]
	v_mfma_f32_16x16x32_bf16 v[72:75], v[144:147], v[212:215], v[72:75]
	v_mfma_f32_16x16x32_bf16 v[64:67], v[152:155], v[212:215], v[64:67]
	v_mfma_f32_16x16x32_bf16 v[128:131], v[148:151], v[164:167], v[128:131]
	v_mfma_f32_16x16x32_bf16 v[112:115], v[156:159], v[164:167], v[112:115]
	v_mfma_f32_16x16x32_bf16 v[104:107], v[148:151], v[182:185], v[104:107]
	v_mfma_f32_16x16x32_bf16 v[96:99], v[156:159], v[182:185], v[96:99]
	v_mfma_f32_16x16x32_bf16 v[88:91], v[148:151], v[208:211], v[88:91]
	v_mfma_f32_16x16x32_bf16 v[80:83], v[156:159], v[208:211], v[80:83]
	v_mfma_f32_16x16x32_bf16 v[72:75], v[148:151], v[216:219], v[72:75]
	v_mfma_f32_16x16x32_bf16 v[64:67], v[156:159], v[216:219], v[64:67]
	s_setprio 0
	s_barrier
	s_add_i32 s47, s47, s30
	v_lshl_add_u64 v[186:187], s[22:23], 0, v[188:189]
	s_mov_b32 m0, s47
	ds_read_b128 v[160:163], v203 offset:16384
	ds_read_b128 v[164:167], v203 offset:17408
	ds_read_b128 v[178:181], v203 offset:18432
	ds_read_b128 v[182:185], v203 offset:19456
	ds_read_b128 v[204:207], v203 offset:20480
	ds_read_b128 v[208:211], v203 offset:21504
	ds_read_b128 v[212:215], v203 offset:22528
	ds_read_b128 v[216:219], v203 offset:23552
	global_load_lds_dwordx4 v[186:187], off
	s_add_i32 m0, s47, 0x2000
	s_add_u32 s48, s22, 0x200000
	v_lshl_add_u64 v[198:199], s[22:23], 0, v[168:169]
	s_addc_u32 s49, s23, 0
	s_add_i32 s47, s50, s30
	global_load_lds_dwordx4 v[198:199], off
	v_lshl_add_u64 v[220:221], s[48:49], 0, v[188:189]
	s_mov_b32 m0, s47
	v_lshl_add_u64 v[222:223], s[24:25], 0, v[170:171]
	global_load_lds_dwordx4 v[220:221], off
	v_lshl_add_u64 v[220:221], s[48:49], 0, v[168:169]
	s_add_i32 m0, s47, 0x2000
	s_nop 0
	global_load_lds_dwordx4 v[220:221], off
	v_lshl_add_u64 v[220:221], s[24:25], 0, v[172:173]
	s_mov_b32 m0, s31
	s_nop 0
	global_load_lds_dwordx4 v[220:221], off
	s_mov_b32 m0, s34
	s_nop 0
	global_load_lds_dwordx4 v[222:223], off
	s_waitcnt vmcnt(8)
	s_waitcnt lgkmcnt(0)
	s_setprio 1
	s_waitcnt lgkmcnt(0)
	v_mfma_f32_16x16x32_bf16 v[60:63], v[120:123], v[160:163], v[60:63]
	v_mfma_f32_16x16x32_bf16 v[52:55], v[136:139], v[160:163], v[52:55]
	v_mfma_f32_16x16x32_bf16 v[44:47], v[120:123], v[178:181], v[44:47]
	v_mfma_f32_16x16x32_bf16 v[36:39], v[136:139], v[178:181], v[36:39]
	v_mfma_f32_16x16x32_bf16 v[28:31], v[120:123], v[204:207], v[28:31]
	v_mfma_f32_16x16x32_bf16 v[20:23], v[136:139], v[204:207], v[20:23]
	v_mfma_f32_16x16x32_bf16 v[12:15], v[120:123], v[212:215], v[12:15]
	v_mfma_f32_16x16x32_bf16 v[4:7], v[136:139], v[212:215], v[4:7]
	s_barrier
; #define PG8_STAGE(bufoff, gbase, voff) do { _Pragma("unroll") for (int _i = 0; _i < 2; ++_i) \
;         __builtin_amdgcn_global_load_lds((const unsigned*)((const char*)(gbase) + (voff)[_i]), (LAS unsigned*)(lds + (bufoff) + ldsw + _i * 8192), 16, 0, 0); } while (0)
; #define PG8_LDA(dst, b, h) do { _Pragma("unroll") for (int m = 0; m < 4; ++m) _Pragma("unroll") for (int k = 0; k < 2; ++k) dst[m][k] = *(const LAS bf16x8*)(lds + PG8_SA(b, h) + aoff + m * 2048 + k * 1024); } while (0)
; #define PG8_LDB(dst, b, h) do { _Pragma("unroll") for (int n = 0; n < 2; ++n) _Pragma("unroll") for (int k = 0; k < 2; ++k) dst[n][k] = *(const LAS bf16x8*)(lds + PG8_SB(b, h) + boff + n * 2048 + k * 1024); } while (0)
; #define PG8_MMA(ai, bj, At, Bt) do { __builtin_amdgcn_s_setprio(1); _Pragma("unroll") for (int m = 0; m < 4; ++m) _Pragma("unroll") for (int n = 0; n < 2; ++n) _Pragma("unroll") for (int k = 0; k < 2; ++k) \
;         acc[ai][bj][m][n] = __builtin_amdgcn_mfma_f32_16x16x32_bf16(Bt[n][k], At[m][k], acc[ai][bj][m][n], 0, 0, 0); __builtin_amdgcn_s_setprio(0); } while (0)
; #define PG8_WAIT_V(n) asm volatile("s_waitcnt vmcnt(" #n ")" ::: "memory")
; #define PG8_WAIT_L(n) asm volatile("s_waitcnt lgkmcnt(" #n ")" ::: "memory")
; #define PG8_BAR __builtin_amdgcn_s_barrier()
; #define PG8_SCHED __builtin_amdgcn_sched_barrier(0)
; template <class Epi, class Sched>
; __device__ __forceinline__ void gemm_phase(int wv, LAS unsigned char* lds, const Gemm g, const Sched& S, const Epi& E) {
;     ...
;             PG8_WAIT_V(8); PG8_WAIT_L(0); PG8_BAR; PG8_MMA(1, 0, At, B0); PG8_MMA(1, 1, At, B1); PG8_BAR; PG8_SCHED;
;             PG8_LDB(B0, 1, 0); PG8_LDB(B1, 1, 1); PG8_SCHED; PG8_LDA(At, 1, 0); PG8_STAGE(PG8_SA(0, 1), a2 + hstep, voffA);
;             PG8_WAIT_V(8); PG8_WAIT_L(0); PG8_BAR; PG8_MMA(0, 0, At, B0); PG8_MMA(0, 1, At, B1); PG8_BAR; PG8_SCHED;
	v_mfma_f32_16x16x32_bf16 v[60:63], v[124:127], v[164:167], v[60:63]
	v_mfma_f32_16x16x32_bf16 v[52:55], v[140:143], v[164:167], v[52:55]
	v_mfma_f32_16x16x32_bf16 v[44:47], v[124:127], v[182:185], v[44:47]
	v_mfma_f32_16x16x32_bf16 v[36:39], v[140:143], v[182:185], v[36:39]
	v_mfma_f32_16x16x32_bf16 v[28:31], v[124:127], v[208:211], v[28:31]
	v_mfma_f32_16x16x32_bf16 v[20:23], v[140:143], v[208:211], v[20:23]
	v_mfma_f32_16x16x32_bf16 v[12:15], v[124:127], v[216:219], v[12:15]
	v_mfma_f32_16x16x32_bf16 v[4:7], v[140:143], v[216:219], v[4:7]
	s_setprio 0
	s_setprio 1
	v_mfma_f32_16x16x32_bf16 v[56:59], v[144:147], v[160:163], v[56:59]
	v_mfma_f32_16x16x32_bf16 v[48:51], v[152:155], v[160:163], v[48:51]
	v_mfma_f32_16x16x32_bf16 v[40:43], v[144:147], v[178:181], v[40:43]
	v_mfma_f32_16x16x32_bf16 v[32:35], v[152:155], v[178:181], v[32:35]
	v_mfma_f32_16x16x32_bf16 v[24:27], v[144:147], v[204:207], v[24:27]
	v_mfma_f32_16x16x32_bf16 v[16:19], v[152:155], v[204:207], v[16:19]
	v_mfma_f32_16x16x32_bf16 v[8:11], v[144:147], v[212:215], v[8:11]
	v_mfma_f32_16x16x32_bf16 v[0:3], v[152:155], v[212:215], v[0:3]
	v_mfma_f32_16x16x32_bf16 v[56:59], v[148:151], v[164:167], v[56:59]
	v_mfma_f32_16x16x32_bf16 v[48:51], v[156:159], v[164:167], v[48:51]
	v_mfma_f32_16x16x32_bf16 v[40:43], v[148:151], v[182:185], v[40:43]
	v_mfma_f32_16x16x32_bf16 v[32:35], v[156:159], v[182:185], v[32:35]
	v_mfma_f32_16x16x32_bf16 v[24:27], v[148:151], v[208:211], v[24:27]
	v_mfma_f32_16x16x32_bf16 v[16:19], v[156:159], v[208:211], v[16:19]
	v_mfma_f32_16x16x32_bf16 v[8:11], v[148:151], v[216:219], v[8:11]
	v_mfma_f32_16x16x32_bf16 v[0:3], v[156:159], v[216:219], v[0:3]
	s_setprio 0
	s_barrier
	s_add_i32 s47, 0, 0x1c000
	v_add_u32_e32 v140, s95, v201
	v_add_u32_e32 v156, s47, v201
	ds_read_b128 v[120:123], v140
	ds_read_b128 v[124:127], v140 offset:1024
	ds_read_b128 v[136:139], v140 offset:2048
	ds_read_b128 v[140:143], v140 offset:3072
	ds_read_b128 v[144:147], v156
	ds_read_b128 v[148:151], v156 offset:1024
	ds_read_b128 v[152:155], v156 offset:2048
	ds_read_b128 v[156:159], v156 offset:3072
	s_add_u32 s24, s24, 0x40000
	s_addc_u32 s25, s25, 0
	s_mov_b32 m0, s35
	v_lshl_add_u64 v[228:229], s[24:25], 0, v[172:173]
	ds_read_b128 v[160:163], v203 offset:32768
	ds_read_b128 v[164:167], v203 offset:33792
	ds_read_b128 v[178:181], v203 offset:34816
	ds_read_b128 v[182:185], v203 offset:35840
	ds_read_b128 v[204:207], v203 offset:36864
	ds_read_b128 v[208:211], v203 offset:37888
	ds_read_b128 v[212:215], v203 offset:38912
	ds_read_b128 v[216:219], v203 offset:39936
	global_load_lds_dwordx4 v[228:229], off
	v_lshl_add_u64 v[228:229], s[24:25], 0, v[170:171]
	s_mov_b32 m0, s36
	s_nop 0
	global_load_lds_dwordx4 v[228:229], off
	s_waitcnt vmcnt(8)
	s_waitcnt lgkmcnt(0)
	s_setprio 1
	s_waitcnt lgkmcnt(0)
	v_mfma_f32_16x16x32_bf16 v[132:135], v[120:123], v[160:163], v[132:135]
	v_mfma_f32_16x16x32_bf16 v[116:119], v[136:139], v[160:163], v[116:119]
	v_mfma_f32_16x16x32_bf16 v[108:111], v[120:123], v[178:181], v[108:111]
	v_mfma_f32_16x16x32_bf16 v[100:103], v[136:139], v[178:181], v[100:103]
	v_mfma_f32_16x16x32_bf16 v[92:95], v[120:123], v[204:207], v[92:95]
	v_mfma_f32_16x16x32_bf16 v[84:87], v[136:139], v[204:207], v[84:87]
	v_mfma_f32_16x16x32_bf16 v[76:79], v[120:123], v[212:215], v[76:79]
	v_mfma_f32_16x16x32_bf16 v[68:71], v[136:139], v[212:215], v[68:71]
	s_barrier
	v_mfma_f32_16x16x32_bf16 v[132:135], v[124:127], v[164:167], v[132:135]
	v_mfma_f32_16x16x32_bf16 v[116:119], v[140:143], v[164:167], v[116:119]
	v_mfma_f32_16x16x32_bf16 v[108:111], v[124:127], v[182:185], v[108:111]
	v_mfma_f32_16x16x32_bf16 v[100:103], v[140:143], v[182:185], v[100:103]
	v_mfma_f32_16x16x32_bf16 v[92:95], v[124:127], v[208:211], v[92:95]
	v_mfma_f32_16x16x32_bf16 v[84:87], v[140:143], v[208:211], v[84:87]
	v_mfma_f32_16x16x32_bf16 v[76:79], v[124:127], v[216:219], v[76:79]
	v_mfma_f32_16x16x32_bf16 v[68:71], v[140:143], v[216:219], v[68:71]
	s_setprio 0
	s_setprio 1
	v_mfma_f32_16x16x32_bf16 v[128:131], v[144:147], v[160:163], v[128:131]
	v_mfma_f32_16x16x32_bf16 v[112:115], v[152:155], v[160:163], v[112:115]
	v_mfma_f32_16x16x32_bf16 v[104:107], v[144:147], v[178:181], v[104:107]
	v_mfma_f32_16x16x32_bf16 v[96:99], v[152:155], v[178:181], v[96:99]
	v_mfma_f32_16x16x32_bf16 v[88:91], v[144:147], v[204:207], v[88:91]
	v_mfma_f32_16x16x32_bf16 v[80:83], v[152:155], v[204:207], v[80:83]
	v_mfma_f32_16x16x32_bf16 v[72:75], v[144:147], v[212:215], v[72:75]
	v_mfma_f32_16x16x32_bf16 v[64:67], v[152:155], v[212:215], v[64:67]
	v_mfma_f32_16x16x32_bf16 v[128:131], v[148:151], v[164:167], v[128:131]
	v_mfma_f32_16x16x32_bf16 v[112:115], v[156:159], v[164:167], v[112:115]
	v_mfma_f32_16x16x32_bf16 v[104:107], v[148:151], v[182:185], v[104:107]
	v_mfma_f32_16x16x32_bf16 v[96:99], v[156:159], v[182:185], v[96:99]
	v_mfma_f32_16x16x32_bf16 v[88:91], v[148:151], v[208:211], v[88:91]
	v_mfma_f32_16x16x32_bf16 v[80:83], v[156:159], v[208:211], v[80:83]
	v_mfma_f32_16x16x32_bf16 v[72:75], v[148:151], v[216:219], v[72:75]
	v_mfma_f32_16x16x32_bf16 v[64:67], v[156:159], v[216:219], v[64:67]
	s_setprio 0
	s_barrier
; #define PG8_STAGE(bufoff, gbase, voff) do { _Pragma("unroll") for (int _i = 0; _i < 2; ++_i) \
;         __builtin_amdgcn_global_load_lds((const unsigned*)((const char*)(gbase) + (voff)[_i]), (LAS unsigned*)(lds + (bufoff) + ldsw + _i * 8192), 16, 0, 0); } while (0)
; #define PG8_LDA(dst, b, h) do { _Pragma("unroll") for (int m = 0; m < 4; ++m) _Pragma("unroll") for (int k = 0; k < 2; ++k) dst[m][k] = *(const LAS bf16x8*)(lds + PG8_SA(b, h) + aoff + m * 2048 + k * 1024); } while (0)
; #define PG8_MMA(ai, bj, At, Bt) do { __builtin_amdgcn_s_setprio(1); _Pragma("unroll") for (int m = 0; m < 4; ++m) _Pragma("unroll") for (int n = 0; n < 2; ++n) _Pragma("unroll") for (int k = 0; k < 2; ++k) \
;         acc[ai][bj][m][n] = __builtin_amdgcn_mfma_f32_16x16x32_bf16(Bt[n][k], At[m][k], acc[ai][bj][m][n], 0, 0, 0); __builtin_amdgcn_s_setprio(0); } while (0)
; #define PG8_WAIT_V(n) asm volatile("s_waitcnt vmcnt(" #n ")" ::: "memory")
; #define PG8_WAIT_L(n) asm volatile("s_waitcnt lgkmcnt(" #n ")" ::: "memory")
; #define PG8_BAR __builtin_amdgcn_s_barrier()
; #define PG8_SCHED __builtin_amdgcn_sched_barrier(0)
; template <class Epi, class Sched>
; __device__ __forceinline__ void gemm_phase(int wv, LAS unsigned char* lds, const Gemm g, const Sched& S, const Epi& E) {
;     ...
;             PG8_LDA(At, 1, 1); PG8_STAGE(PG8_SB(1, 0), b3, voffB); PG8_STAGE(PG8_SB(1, 1), b3 + hstepB, voffB); PG8_STAGE(PG8_SA(1, 0), a3, voffA);
;             PG8_WAIT_V(8); PG8_WAIT_L(0); PG8_BAR; PG8_MMA(1, 0, At, B0); PG8_MMA(1, 1, At, B1); PG8_BAR; PG8_SCHED;
;         }
;         if (wr == 0) PG8_BAR;
	s_add_i32 s24, s95, s30
	v_lshl_add_u64 v[186:187], v[186:187], 0, s[74:75]
	s_mov_b32 m0, s24
	ds_read_b128 v[160:163], v203 offset:49152
	ds_read_b128 v[164:167], v203 offset:50176
	ds_read_b128 v[178:181], v203 offset:51200
	ds_read_b128 v[182:185], v203 offset:52224
	ds_read_b128 v[204:207], v203 offset:53248
	ds_read_b128 v[208:211], v203 offset:54272
	ds_read_b128 v[212:215], v203 offset:55296
	ds_read_b128 v[216:219], v203 offset:56320
	global_load_lds_dwordx4 v[186:187], off
	s_add_i32 m0, s24, 0x2000
	s_add_u32 s22, s22, 0x200080
	v_lshl_add_u64 v[186:187], v[198:199], 0, s[74:75]
	s_addc_u32 s23, s23, 0
	s_add_i32 s24, s47, s30
	global_load_lds_dwordx4 v[186:187], off
	v_lshl_add_u64 v[186:187], s[22:23], 0, v[188:189]
	s_mov_b32 m0, s24
	s_nop 0
	global_load_lds_dwordx4 v[186:187], off
	v_lshl_add_u64 v[186:187], s[22:23], 0, v[168:169]
	s_add_i32 m0, s24, 0x2000
	s_nop 0
	global_load_lds_dwordx4 v[186:187], off
	v_lshl_add_u64 v[186:187], v[220:221], 0, s[74:75]
	s_mov_b32 m0, s37
	s_nop 0
	global_load_lds_dwordx4 v[186:187], off
	v_lshl_add_u64 v[186:187], v[222:223], 0, s[74:75]
	s_mov_b32 m0, s38
	s_nop 0
	global_load_lds_dwordx4 v[186:187], off
	s_waitcnt vmcnt(8)
	s_waitcnt lgkmcnt(0)
	s_setprio 1
	s_waitcnt lgkmcnt(0)
	v_mfma_f32_16x16x32_bf16 v[60:63], v[120:123], v[160:163], v[60:63]
	v_mfma_f32_16x16x32_bf16 v[52:55], v[136:139], v[160:163], v[52:55]
	v_mfma_f32_16x16x32_bf16 v[44:47], v[120:123], v[178:181], v[44:47]
	v_mfma_f32_16x16x32_bf16 v[36:39], v[136:139], v[178:181], v[36:39]
	v_mfma_f32_16x16x32_bf16 v[28:31], v[120:123], v[204:207], v[28:31]
	v_mfma_f32_16x16x32_bf16 v[20:23], v[136:139], v[204:207], v[20:23]
	v_mfma_f32_16x16x32_bf16 v[12:15], v[120:123], v[212:215], v[12:15]
	v_mfma_f32_16x16x32_bf16 v[4:7], v[136:139], v[212:215], v[4:7]
	s_barrier
	v_mfma_f32_16x16x32_bf16 v[60:63], v[124:127], v[164:167], v[60:63]
	v_mfma_f32_16x16x32_bf16 v[52:55], v[140:143], v[164:167], v[52:55]
	v_mfma_f32_16x16x32_bf16 v[44:47], v[124:127], v[182:185], v[44:47]
	v_mfma_f32_16x16x32_bf16 v[36:39], v[140:143], v[182:185], v[36:39]
	v_mfma_f32_16x16x32_bf16 v[28:31], v[124:127], v[208:211], v[28:31]
	v_mfma_f32_16x16x32_bf16 v[20:23], v[140:143], v[208:211], v[20:23]
	v_mfma_f32_16x16x32_bf16 v[12:15], v[124:127], v[216:219], v[12:15]
	v_mfma_f32_16x16x32_bf16 v[4:7], v[140:143], v[216:219], v[4:7]
	s_setprio 0
	s_setprio 1
	v_mfma_f32_16x16x32_bf16 v[56:59], v[144:147], v[160:163], v[56:59]
	v_mfma_f32_16x16x32_bf16 v[48:51], v[152:155], v[160:163], v[48:51]
	v_mfma_f32_16x16x32_bf16 v[40:43], v[144:147], v[178:181], v[40:43]
	v_mfma_f32_16x16x32_bf16 v[32:35], v[152:155], v[178:181], v[32:35]
	v_mfma_f32_16x16x32_bf16 v[24:27], v[144:147], v[204:207], v[24:27]
	v_mfma_f32_16x16x32_bf16 v[16:19], v[152:155], v[204:207], v[16:19]
	v_mfma_f32_16x16x32_bf16 v[8:11], v[144:147], v[212:215], v[8:11]
	v_mfma_f32_16x16x32_bf16 v[0:3], v[152:155], v[212:215], v[0:3]
	v_mfma_f32_16x16x32_bf16 v[56:59], v[148:151], v[164:167], v[56:59]
	v_mfma_f32_16x16x32_bf16 v[48:51], v[156:159], v[164:167], v[48:51]
	v_mfma_f32_16x16x32_bf16 v[40:43], v[148:151], v[182:185], v[40:43]
	v_mfma_f32_16x16x32_bf16 v[32:35], v[156:159], v[182:185], v[32:35]
	v_mfma_f32_16x16x32_bf16 v[24:27], v[148:151], v[208:211], v[24:27]
	v_mfma_f32_16x16x32_bf16 v[16:19], v[156:159], v[208:211], v[16:19]
	v_mfma_f32_16x16x32_bf16 v[8:11], v[148:151], v[216:219], v[8:11]
	v_mfma_f32_16x16x32_bf16 v[0:3], v[156:159], v[216:219], v[0:3]
	s_setprio 0
	s_barrier
	s_add_i32 s46, s46, 2
	s_add_u32 s20, s20, 0x100
	s_addc_u32 s21, s21, 0
	s_add_u32 s44, s44, 0x100
	s_addc_u32 s45, s45, 0
	s_cmp_gt_u32 s46, 13
	s_cbranch_scc0 .LBB0_821
	s_and_b64 vcc, exec, s[10:11]
	s_cbranch_vccz .LBB0_824
	s_barrier

; #define PG8_STAGE(bufoff, gbase, voff) do { _Pragma("unroll") for (int _i = 0; _i < 2; ++_i) \
;         __builtin_amdgcn_global_load_lds((const unsigned*)((const char*)(gbase) + (voff)[_i]), (LAS unsigned*)(lds + (bufoff) + ldsw + _i * 8192), 16, 0, 0); } while (0)
; #define PG8_LDA(dst, b, h) do { _Pragma("unroll") for (int m = 0; m < 4; ++m) _Pragma("unroll") for (int k = 0; k < 2; ++k) dst[m][k] = *(const LAS bf16x8*)(lds + PG8_SA(b, h) + aoff + m * 2048 + k * 1024); } while (0)
; #define PG8_LDB(dst, b, h) do { _Pragma("unroll") for (int n = 0; n < 2; ++n) _Pragma("unroll") for (int k = 0; k < 2; ++k) dst[n][k] = *(const LAS bf16x8*)(lds + PG8_SB(b, h) + boff + n * 2048 + k * 1024); } while (0)
; #define PG8_MMA(ai, bj, At, Bt) do { __builtin_amdgcn_s_setprio(1); _Pragma("unroll") for (int m = 0; m < 4; ++m) _Pragma("unroll") for (int n = 0; n < 2; ++n) _Pragma("unroll") for (int k = 0; k < 2; ++k) \
;         acc[ai][bj][m][n] = __builtin_amdgcn_mfma_f32_16x16x32_bf16(Bt[n][k], At[m][k], acc[ai][bj][m][n], 0, 0, 0); __builtin_amdgcn_s_setprio(0); } while (0)
; #define PG8_WAIT_V(n) asm volatile("s_waitcnt vmcnt(" #n ")" ::: "memory")
; #define PG8_WAIT_L(n) asm volatile("s_waitcnt lgkmcnt(" #n ")" ::: "memory")
; #define PG8_BAR __builtin_amdgcn_s_barrier()
; #define PG8_SCHED __builtin_amdgcn_sched_barrier(0)
; template <class Epi, class Sched>
; __device__ __forceinline__ void gemm_phase(int wv, LAS unsigned char* lds, const Gemm g, const Sched& S, const Epi& E) {
;     ...
;         for (int t = 0; t < nt; t += 2) {
;             const bool last = (t == nt - 2);
;             const char* a1 = cA + (size_t)(t + 1) * kstep;
;             const char* a2 = last ? nA : cA + (size_t)(t + 2) * kstep; const char* b2 = last ? nB : cB + (size_t)(t + 2) * kstep;
;             const char* a3 = a2 + kstep; const char* b3 = b2 + kstep;
;             PG8_LDB(B0, 0, 0); PG8_LDB(B1, 0, 1); PG8_SCHED; PG8_LDA(At, 0, 0); PG8_STAGE(PG8_SA(1, 1), a1 + hstep, voffA);
;             PG8_WAIT_V(8); PG8_WAIT_L(0); PG8_BAR; PG8_MMA(0, 0, At, B0); PG8_MMA(0, 1, At, B1); PG8_BAR; PG8_SCHED;
;             PG8_LDA(At, 0, 1); PG8_STAGE(PG8_SB(0, 0), b2, voffB); PG8_STAGE(PG8_SB(0, 1), b2 + hstepB, voffB); PG8_STAGE(PG8_SA(0, 0), a2, voffA);
;             PG8_WAIT_V(8); PG8_WAIT_L(0); PG8_BAR; PG8_MMA(1, 0, At, B0); PG8_MMA(1, 1, At, B1); PG8_BAR; PG8_SCHED;
.LBB0_893:
	s_add_u32 s26, s24, 0xfffc0080
	s_addc_u32 s27, s25, -1
	s_add_i32 s50, 0, 0x10000
	s_cmp_eq_u32 s49, 12
	s_cselect_b32 s29, s17, s27
	s_cselect_b32 s28, s45, s26
	s_cselect_b32 s27, s19, s48
	s_cselect_b32 s26, s46, s47
	s_add_i32 s52, 0, 0x14000
	v_add_u32_e32 v124, s50, v240
	v_add_u32_e32 v156, s52, v240
	ds_read_b128 v[112:115], v124
	ds_read_b128 v[116:119], v124 offset:1024
	ds_read_b128 v[120:123], v124 offset:2048
	ds_read_b128 v[124:127], v124 offset:3072
	ds_read_b128 v[128:131], v156
	ds_read_b128 v[140:143], v156 offset:1024
	ds_read_b128 v[152:155], v156 offset:2048
	ds_read_b128 v[156:159], v156 offset:3072
	v_lshl_add_u64 v[212:213], s[24:25], 0, v[204:205]
	s_add_i32 m0, s37, 0xc000
	ds_read_b128 v[160:163], v244
	ds_read_b128 v[164:167], v244 offset:1024
	ds_read_b128 v[168:171], v244 offset:2048
	ds_read_b128 v[172:175], v244 offset:3072
	ds_read_b128 v[176:179], v244 offset:4096
	ds_read_b128 v[180:183], v244 offset:5120
	ds_read_b128 v[184:187], v244 offset:6144
	ds_read_b128 v[208:211], v244 offset:7168
	global_load_lds_dwordx4 v[212:213], off
	v_lshl_add_u64 v[212:213], s[24:25], 0, v[206:207]
	s_add_i32 m0, s37, 0xe000
	s_nop 0
	global_load_lds_dwordx4 v[212:213], off
	s_waitcnt vmcnt(8)
	s_waitcnt lgkmcnt(0)
	s_setprio 1
	s_waitcnt lgkmcnt(0)
	v_mfma_f32_16x16x32_bf16 v[148:151], v[112:115], v[160:163], v[148:151]
	v_mfma_f32_16x16x32_bf16 v[144:147], v[120:123], v[160:163], v[144:147]
	v_mfma_f32_16x16x32_bf16 v[108:111], v[112:115], v[168:171], v[108:111]
	v_mfma_f32_16x16x32_bf16 v[104:107], v[120:123], v[168:171], v[104:107]
	v_mfma_f32_16x16x32_bf16 v[92:95], v[112:115], v[176:179], v[92:95]
	v_mfma_f32_16x16x32_bf16 v[88:91], v[120:123], v[176:179], v[88:91]
	v_mfma_f32_16x16x32_bf16 v[76:79], v[112:115], v[184:187], v[76:79]
	v_mfma_f32_16x16x32_bf16 v[72:75], v[120:123], v[184:187], v[72:75]
	s_barrier
	v_mfma_f32_16x16x32_bf16 v[148:151], v[116:119], v[164:167], v[148:151]
	v_mfma_f32_16x16x32_bf16 v[144:147], v[124:127], v[164:167], v[144:147]
	v_mfma_f32_16x16x32_bf16 v[108:111], v[116:119], v[172:175], v[108:111]
	v_mfma_f32_16x16x32_bf16 v[104:107], v[124:127], v[172:175], v[104:107]
	v_mfma_f32_16x16x32_bf16 v[92:95], v[116:119], v[180:183], v[92:95]
	v_mfma_f32_16x16x32_bf16 v[88:91], v[124:127], v[180:183], v[88:91]
	v_mfma_f32_16x16x32_bf16 v[76:79], v[116:119], v[208:211], v[76:79]
	v_mfma_f32_16x16x32_bf16 v[72:75], v[124:127], v[208:211], v[72:75]
	s_setprio 0
	s_setprio 1
	v_mfma_f32_16x16x32_bf16 v[136:139], v[128:131], v[160:163], v[136:139]
	v_mfma_f32_16x16x32_bf16 v[132:135], v[152:155], v[160:163], v[132:135]
	v_mfma_f32_16x16x32_bf16 v[100:103], v[128:131], v[168:171], v[100:103]
	v_mfma_f32_16x16x32_bf16 v[96:99], v[152:155], v[168:171], v[96:99]
	v_mfma_f32_16x16x32_bf16 v[84:87], v[128:131], v[176:179], v[84:87]
	v_mfma_f32_16x16x32_bf16 v[80:83], v[152:155], v[176:179], v[80:83]
	v_mfma_f32_16x16x32_bf16 v[68:71], v[128:131], v[184:187], v[68:71]
	v_mfma_f32_16x16x32_bf16 v[64:67], v[152:155], v[184:187], v[64:67]
	v_mfma_f32_16x16x32_bf16 v[136:139], v[140:143], v[164:167], v[136:139]
	v_mfma_f32_16x16x32_bf16 v[132:135], v[156:159], v[164:167], v[132:135]
	v_mfma_f32_16x16x32_bf16 v[100:103], v[140:143], v[172:175], v[100:103]
	v_mfma_f32_16x16x32_bf16 v[96:99], v[156:159], v[172:175], v[96:99]
	v_mfma_f32_16x16x32_bf16 v[84:87], v[140:143], v[180:183], v[84:87]
	v_mfma_f32_16x16x32_bf16 v[80:83], v[156:159], v[180:183], v[80:83]
	v_mfma_f32_16x16x32_bf16 v[68:71], v[140:143], v[208:211], v[68:71]
	v_mfma_f32_16x16x32_bf16 v[64:67], v[156:159], v[208:211], v[64:67]
	s_setprio 0
	s_barrier
	s_add_i32 s50, s50, s36
	v_lshl_add_u64 v[212:213], s[26:27], 0, v[188:189]
	s_mov_b32 m0, s50
	ds_read_b128 v[160:163], v244 offset:16384
	ds_read_b128 v[164:167], v244 offset:17408
	ds_read_b128 v[168:171], v244 offset:18432
	ds_read_b128 v[172:175], v244 offset:19456
	ds_read_b128 v[176:179], v244 offset:20480
	ds_read_b128 v[180:183], v244 offset:21504
	ds_read_b128 v[184:187], v244 offset:22528
	ds_read_b128 v[208:211], v244 offset:23552
	global_load_lds_dwordx4 v[212:213], off
	s_add_i32 m0, s50, 0x2000
	s_add_u32 s50, s26, 0x4000
	v_lshl_add_u64 v[214:215], s[26:27], 0, v[198:199]
	s_addc_u32 s51, s27, 0
	s_add_i32 s52, s52, s36
	global_load_lds_dwordx4 v[214:215], off
	v_lshl_add_u64 v[216:217], s[50:51], 0, v[188:189]
	s_mov_b32 m0, s52
	v_lshl_add_u64 v[218:219], s[28:29], 0, v[200:201]
	global_load_lds_dwordx4 v[216:217], off
	v_lshl_add_u64 v[216:217], s[50:51], 0, v[198:199]
	s_add_i32 m0, s52, 0x2000
	s_nop 0
	global_load_lds_dwordx4 v[216:217], off
	v_lshl_add_u64 v[216:217], s[28:29], 0, v[202:203]
	s_mov_b32 m0, s37
	s_nop 0
	global_load_lds_dwordx4 v[216:217], off
	s_mov_b32 m0, s38
	s_nop 0
	global_load_lds_dwordx4 v[218:219], off
	s_waitcnt vmcnt(8)
	s_waitcnt lgkmcnt(0)
	s_setprio 1
	s_waitcnt lgkmcnt(0)
	v_mfma_f32_16x16x32_bf16 v[60:63], v[112:115], v[160:163], v[60:63]
	v_mfma_f32_16x16x32_bf16 v[56:59], v[120:123], v[160:163], v[56:59]
	v_mfma_f32_16x16x32_bf16 v[44:47], v[112:115], v[168:171], v[44:47]
	v_mfma_f32_16x16x32_bf16 v[40:43], v[120:123], v[168:171], v[40:43]
	v_mfma_f32_16x16x32_bf16 v[28:31], v[112:115], v[176:179], v[28:31]
	v_mfma_f32_16x16x32_bf16 v[24:27], v[120:123], v[176:179], v[24:27]
	v_mfma_f32_16x16x32_bf16 v[12:15], v[112:115], v[184:187], v[12:15]
	v_mfma_f32_16x16x32_bf16 v[8:11], v[120:123], v[184:187], v[8:11]
	s_barrier
; #define PG8_STAGE(bufoff, gbase, voff) do { _Pragma("unroll") for (int _i = 0; _i < 2; ++_i) \
;         __builtin_amdgcn_global_load_lds((const unsigned*)((const char*)(gbase) + (voff)[_i]), (LAS unsigned*)(lds + (bufoff) + ldsw + _i * 8192), 16, 0, 0); } while (0)
; #define PG8_LDA(dst, b, h) do { _Pragma("unroll") for (int m = 0; m < 4; ++m) _Pragma("unroll") for (int k = 0; k < 2; ++k) dst[m][k] = *(const LAS bf16x8*)(lds + PG8_SA(b, h) + aoff + m * 2048 + k * 1024); } while (0)
; #define PG8_LDB(dst, b, h) do { _Pragma("unroll") for (int n = 0; n < 2; ++n) _Pragma("unroll") for (int k = 0; k < 2; ++k) dst[n][k] = *(const LAS bf16x8*)(lds + PG8_SB(b, h) + boff + n * 2048 + k * 1024); } while (0)
; #define PG8_MMA(ai, bj, At, Bt) do { __builtin_amdgcn_s_setprio(1); _Pragma("unroll") for (int m = 0; m < 4; ++m) _Pragma("unroll") for (int n = 0; n < 2; ++n) _Pragma("unroll") for (int k = 0; k < 2; ++k) \
;         acc[ai][bj][m][n] = __builtin_amdgcn_mfma_f32_16x16x32_bf16(Bt[n][k], At[m][k], acc[ai][bj][m][n], 0, 0, 0); __builtin_amdgcn_s_setprio(0); } while (0)
; #define PG8_WAIT_V(n) asm volatile("s_waitcnt vmcnt(" #n ")" ::: "memory")
; #define PG8_WAIT_L(n) asm volatile("s_waitcnt lgkmcnt(" #n ")" ::: "memory")
; #define PG8_BAR __builtin_amdgcn_s_barrier()
; #define PG8_SCHED __builtin_amdgcn_sched_barrier(0)
; template <class Epi, class Sched>
; __device__ __forceinline__ void gemm_phase(int wv, LAS unsigned char* lds, const Gemm g, const Sched& S, const Epi& E) {
;     ...
;             PG8_WAIT_V(8); PG8_WAIT_L(0); PG8_BAR; PG8_MMA(1, 0, At, B0); PG8_MMA(1, 1, At, B1); PG8_BAR; PG8_SCHED;
;             PG8_LDB(B0, 1, 0); PG8_LDB(B1, 1, 1); PG8_SCHED; PG8_LDA(At, 1, 0); PG8_STAGE(PG8_SA(0, 1), a2 + hstep, voffA);
;             PG8_WAIT_V(8); PG8_WAIT_L(0); PG8_BAR; PG8_MMA(0, 0, At, B0); PG8_MMA(0, 1, At, B1); PG8_BAR; PG8_SCHED;
	v_mfma_f32_16x16x32_bf16 v[60:63], v[116:119], v[164:167], v[60:63]
	v_mfma_f32_16x16x32_bf16 v[56:59], v[124:127], v[164:167], v[56:59]
	v_mfma_f32_16x16x32_bf16 v[44:47], v[116:119], v[172:175], v[44:47]
	v_mfma_f32_16x16x32_bf16 v[40:43], v[124:127], v[172:175], v[40:43]
	v_mfma_f32_16x16x32_bf16 v[28:31], v[116:119], v[180:183], v[28:31]
	v_mfma_f32_16x16x32_bf16 v[24:27], v[124:127], v[180:183], v[24:27]
	v_mfma_f32_16x16x32_bf16 v[12:15], v[116:119], v[208:211], v[12:15]
	v_mfma_f32_16x16x32_bf16 v[8:11], v[124:127], v[208:211], v[8:11]
	s_setprio 0
	s_setprio 1
	v_mfma_f32_16x16x32_bf16 v[52:55], v[128:131], v[160:163], v[52:55]
	v_mfma_f32_16x16x32_bf16 v[48:51], v[152:155], v[160:163], v[48:51]
	v_mfma_f32_16x16x32_bf16 v[36:39], v[128:131], v[168:171], v[36:39]
	v_mfma_f32_16x16x32_bf16 v[32:35], v[152:155], v[168:171], v[32:35]
	v_mfma_f32_16x16x32_bf16 v[20:23], v[128:131], v[176:179], v[20:23]
	v_mfma_f32_16x16x32_bf16 v[16:19], v[152:155], v[176:179], v[16:19]
	v_mfma_f32_16x16x32_bf16 v[4:7], v[128:131], v[184:187], v[4:7]
	v_mfma_f32_16x16x32_bf16 v[0:3], v[152:155], v[184:187], v[0:3]
	v_mfma_f32_16x16x32_bf16 v[52:55], v[140:143], v[164:167], v[52:55]
	v_mfma_f32_16x16x32_bf16 v[48:51], v[156:159], v[164:167], v[48:51]
	v_mfma_f32_16x16x32_bf16 v[36:39], v[140:143], v[172:175], v[36:39]
	v_mfma_f32_16x16x32_bf16 v[32:35], v[156:159], v[172:175], v[32:35]
	v_mfma_f32_16x16x32_bf16 v[20:23], v[140:143], v[180:183], v[20:23]
	v_mfma_f32_16x16x32_bf16 v[16:19], v[156:159], v[180:183], v[16:19]
	v_mfma_f32_16x16x32_bf16 v[4:7], v[140:143], v[208:211], v[4:7]
	v_mfma_f32_16x16x32_bf16 v[0:3], v[156:159], v[208:211], v[0:3]
	s_setprio 0
	s_barrier
	s_add_i32 s50, 0, 0x1c000
	v_add_u32_e32 v124, s95, v240
	v_add_u32_e32 v156, s50, v240
	ds_read_b128 v[112:115], v124
	ds_read_b128 v[116:119], v124 offset:1024
	ds_read_b128 v[120:123], v124 offset:2048
	ds_read_b128 v[124:127], v124 offset:3072
	ds_read_b128 v[128:131], v156
	ds_read_b128 v[140:143], v156 offset:1024
	ds_read_b128 v[152:155], v156 offset:2048
	ds_read_b128 v[156:159], v156 offset:3072
	s_add_u32 s28, s28, 0x40000
	s_addc_u32 s29, s29, 0
	s_mov_b32 m0, s39
	v_lshl_add_u64 v[220:221], s[28:29], 0, v[202:203]
	ds_read_b128 v[160:163], v244 offset:32768
	ds_read_b128 v[164:167], v244 offset:33792
	ds_read_b128 v[168:171], v244 offset:34816
	ds_read_b128 v[172:175], v244 offset:35840
	ds_read_b128 v[176:179], v244 offset:36864
	ds_read_b128 v[180:183], v244 offset:37888
	ds_read_b128 v[184:187], v244 offset:38912
	ds_read_b128 v[208:211], v244 offset:39936
	global_load_lds_dwordx4 v[220:221], off
	v_lshl_add_u64 v[220:221], s[28:29], 0, v[200:201]
	s_mov_b32 m0, s40
	s_nop 0
	global_load_lds_dwordx4 v[220:221], off
	s_waitcnt vmcnt(8)
	s_waitcnt lgkmcnt(0)
	s_setprio 1
	s_waitcnt lgkmcnt(0)
	v_mfma_f32_16x16x32_bf16 v[148:151], v[112:115], v[160:163], v[148:151]
	v_mfma_f32_16x16x32_bf16 v[144:147], v[120:123], v[160:163], v[144:147]
	v_mfma_f32_16x16x32_bf16 v[108:111], v[112:115], v[168:171], v[108:111]
	v_mfma_f32_16x16x32_bf16 v[104:107], v[120:123], v[168:171], v[104:107]
	v_mfma_f32_16x16x32_bf16 v[92:95], v[112:115], v[176:179], v[92:95]
	v_mfma_f32_16x16x32_bf16 v[88:91], v[120:123], v[176:179], v[88:91]
	v_mfma_f32_16x16x32_bf16 v[76:79], v[112:115], v[184:187], v[76:79]
	v_mfma_f32_16x16x32_bf16 v[72:75], v[120:123], v[184:187], v[72:75]
	s_barrier
	v_mfma_f32_16x16x32_bf16 v[148:151], v[116:119], v[164:167], v[148:151]
	v_mfma_f32_16x16x32_bf16 v[144:147], v[124:127], v[164:167], v[144:147]
	v_mfma_f32_16x16x32_bf16 v[108:111], v[116:119], v[172:175], v[108:111]
	v_mfma_f32_16x16x32_bf16 v[104:107], v[124:127], v[172:175], v[104:107]
	v_mfma_f32_16x16x32_bf16 v[92:95], v[116:119], v[180:183], v[92:95]
	v_mfma_f32_16x16x32_bf16 v[88:91], v[124:127], v[180:183], v[88:91]
	v_mfma_f32_16x16x32_bf16 v[76:79], v[116:119], v[208:211], v[76:79]
	v_mfma_f32_16x16x32_bf16 v[72:75], v[124:127], v[208:211], v[72:75]
	s_setprio 0
	s_setprio 1
	v_mfma_f32_16x16x32_bf16 v[136:139], v[128:131], v[160:163], v[136:139]
	v_mfma_f32_16x16x32_bf16 v[132:135], v[152:155], v[160:163], v[132:135]
	v_mfma_f32_16x16x32_bf16 v[100:103], v[128:131], v[168:171], v[100:103]
	v_mfma_f32_16x16x32_bf16 v[96:99], v[152:155], v[168:171], v[96:99]
	v_mfma_f32_16x16x32_bf16 v[84:87], v[128:131], v[176:179], v[84:87]
	v_mfma_f32_16x16x32_bf16 v[80:83], v[152:155], v[176:179], v[80:83]
	v_mfma_f32_16x16x32_bf16 v[68:71], v[128:131], v[184:187], v[68:71]
	v_mfma_f32_16x16x32_bf16 v[64:67], v[152:155], v[184:187], v[64:67]
	v_mfma_f32_16x16x32_bf16 v[136:139], v[140:143], v[164:167], v[136:139]
	v_mfma_f32_16x16x32_bf16 v[132:135], v[156:159], v[164:167], v[132:135]
	v_mfma_f32_16x16x32_bf16 v[100:103], v[140:143], v[172:175], v[100:103]
	v_mfma_f32_16x16x32_bf16 v[96:99], v[156:159], v[172:175], v[96:99]
	v_mfma_f32_16x16x32_bf16 v[84:87], v[140:143], v[180:183], v[84:87]
	v_mfma_f32_16x16x32_bf16 v[80:83], v[156:159], v[180:183], v[80:83]
	v_mfma_f32_16x16x32_bf16 v[68:71], v[140:143], v[208:211], v[68:71]
	v_mfma_f32_16x16x32_bf16 v[64:67], v[156:159], v[208:211], v[64:67]
	s_setprio 0
	s_barrier
; #define PG8_STAGE(bufoff, gbase, voff) do { _Pragma("unroll") for (int _i = 0; _i < 2; ++_i) \
;         __builtin_amdgcn_global_load_lds((const unsigned*)((const char*)(gbase) + (voff)[_i]), (LAS unsigned*)(lds + (bufoff) + ldsw + _i * 8192), 16, 0, 0); } while (0)
; #define PG8_LDA(dst, b, h) do { _Pragma("unroll") for (int m = 0; m < 4; ++m) _Pragma("unroll") for (int k = 0; k < 2; ++k) dst[m][k] = *(const LAS bf16x8*)(lds + PG8_SA(b, h) + aoff + m * 2048 + k * 1024); } while (0)
; #define PG8_MMA(ai, bj, At, Bt) do { __builtin_amdgcn_s_setprio(1); _Pragma("unroll") for (int m = 0; m < 4; ++m) _Pragma("unroll") for (int n = 0; n < 2; ++n) _Pragma("unroll") for (int k = 0; k < 2; ++k) \
;         acc[ai][bj][m][n] = __builtin_amdgcn_mfma_f32_16x16x32_bf16(Bt[n][k], At[m][k], acc[ai][bj][m][n], 0, 0, 0); __builtin_amdgcn_s_setprio(0); } while (0)
; #define PG8_WAIT_V(n) asm volatile("s_waitcnt vmcnt(" #n ")" ::: "memory")
; #define PG8_WAIT_L(n) asm volatile("s_waitcnt lgkmcnt(" #n ")" ::: "memory")
; #define PG8_BAR __builtin_amdgcn_s_barrier()
; #define PG8_SCHED __builtin_amdgcn_sched_barrier(0)
; template <class Epi, class Sched>
; __device__ __forceinline__ void gemm_phase(int wv, LAS unsigned char* lds, const Gemm g, const Sched& S, const Epi& E) {
;     ...
;             PG8_LDA(At, 1, 1); PG8_STAGE(PG8_SB(1, 0), b3, voffB); PG8_STAGE(PG8_SB(1, 1), b3 + hstepB, voffB); PG8_STAGE(PG8_SA(1, 0), a3, voffA);
;             PG8_WAIT_V(8); PG8_WAIT_L(0); PG8_BAR; PG8_MMA(1, 0, At, B0); PG8_MMA(1, 1, At, B1); PG8_BAR; PG8_SCHED;
;         }
;         if (wr == 0) PG8_BAR;
	s_add_i32 s28, s95, s36
	v_lshl_add_u64 v[212:213], v[212:213], 0, s[74:75]
	s_mov_b32 m0, s28
	ds_read_b128 v[160:163], v244 offset:49152
	ds_read_b128 v[164:167], v244 offset:50176
	ds_read_b128 v[168:171], v244 offset:51200
	ds_read_b128 v[172:175], v244 offset:52224
	ds_read_b128 v[176:179], v244 offset:53248
	ds_read_b128 v[180:183], v244 offset:54272
	ds_read_b128 v[184:187], v244 offset:55296
	ds_read_b128 v[208:211], v244 offset:56320
	global_load_lds_dwordx4 v[212:213], off
	s_add_i32 m0, s28, 0x2000
	s_add_u32 s26, s26, 0x4080
	v_lshl_add_u64 v[212:213], v[214:215], 0, s[74:75]
	s_addc_u32 s27, s27, 0
	s_add_i32 s28, s50, s36
	global_load_lds_dwordx4 v[212:213], off
	v_lshl_add_u64 v[212:213], s[26:27], 0, v[188:189]
	s_mov_b32 m0, s28
	s_nop 0
	global_load_lds_dwordx4 v[212:213], off
	v_lshl_add_u64 v[212:213], s[26:27], 0, v[198:199]
	s_add_i32 m0, s28, 0x2000
	s_nop 0
	global_load_lds_dwordx4 v[212:213], off
	v_lshl_add_u64 v[212:213], v[216:217], 0, s[74:75]
	s_mov_b32 m0, s41
	s_nop 0
	global_load_lds_dwordx4 v[212:213], off
	v_lshl_add_u64 v[212:213], v[218:219], 0, s[74:75]
	s_mov_b32 m0, s42
	s_nop 0
	global_load_lds_dwordx4 v[212:213], off
	s_waitcnt vmcnt(8)
	s_waitcnt lgkmcnt(0)
	s_setprio 1
	s_waitcnt lgkmcnt(0)
	v_mfma_f32_16x16x32_bf16 v[60:63], v[112:115], v[160:163], v[60:63]
	v_mfma_f32_16x16x32_bf16 v[56:59], v[120:123], v[160:163], v[56:59]
	v_mfma_f32_16x16x32_bf16 v[44:47], v[112:115], v[168:171], v[44:47]
	v_mfma_f32_16x16x32_bf16 v[40:43], v[120:123], v[168:171], v[40:43]
	v_mfma_f32_16x16x32_bf16 v[28:31], v[112:115], v[176:179], v[28:31]
	v_mfma_f32_16x16x32_bf16 v[24:27], v[120:123], v[176:179], v[24:27]
	v_mfma_f32_16x16x32_bf16 v[12:15], v[112:115], v[184:187], v[12:15]
	v_mfma_f32_16x16x32_bf16 v[8:11], v[120:123], v[184:187], v[8:11]
	s_barrier
	v_mfma_f32_16x16x32_bf16 v[60:63], v[116:119], v[164:167], v[60:63]
	v_mfma_f32_16x16x32_bf16 v[56:59], v[124:127], v[164:167], v[56:59]
	v_mfma_f32_16x16x32_bf16 v[44:47], v[116:119], v[172:175], v[44:47]
	v_mfma_f32_16x16x32_bf16 v[40:43], v[124:127], v[172:175], v[40:43]
	v_mfma_f32_16x16x32_bf16 v[28:31], v[116:119], v[180:183], v[28:31]
	v_mfma_f32_16x16x32_bf16 v[24:27], v[124:127], v[180:183], v[24:27]
	v_mfma_f32_16x16x32_bf16 v[12:15], v[116:119], v[208:211], v[12:15]
	v_mfma_f32_16x16x32_bf16 v[8:11], v[124:127], v[208:211], v[8:11]
	s_setprio 0
	s_setprio 1
	v_mfma_f32_16x16x32_bf16 v[52:55], v[128:131], v[160:163], v[52:55]
	v_mfma_f32_16x16x32_bf16 v[48:51], v[152:155], v[160:163], v[48:51]
	v_mfma_f32_16x16x32_bf16 v[36:39], v[128:131], v[168:171], v[36:39]
	v_mfma_f32_16x16x32_bf16 v[32:35], v[152:155], v[168:171], v[32:35]
	v_mfma_f32_16x16x32_bf16 v[20:23], v[128:131], v[176:179], v[20:23]
	v_mfma_f32_16x16x32_bf16 v[16:19], v[152:155], v[176:179], v[16:19]
	v_mfma_f32_16x16x32_bf16 v[4:7], v[128:131], v[184:187], v[4:7]
	v_mfma_f32_16x16x32_bf16 v[0:3], v[152:155], v[184:187], v[0:3]
	v_mfma_f32_16x16x32_bf16 v[52:55], v[140:143], v[164:167], v[52:55]
	v_mfma_f32_16x16x32_bf16 v[48:51], v[156:159], v[164:167], v[48:51]
	v_mfma_f32_16x16x32_bf16 v[36:39], v[140:143], v[172:175], v[36:39]
	v_mfma_f32_16x16x32_bf16 v[32:35], v[156:159], v[172:175], v[32:35]
	v_mfma_f32_16x16x32_bf16 v[20:23], v[140:143], v[180:183], v[20:23]
	v_mfma_f32_16x16x32_bf16 v[16:19], v[156:159], v[180:183], v[16:19]
	v_mfma_f32_16x16x32_bf16 v[4:7], v[140:143], v[208:211], v[4:7]
	v_mfma_f32_16x16x32_bf16 v[0:3], v[156:159], v[208:211], v[0:3]
	s_setprio 0
	s_barrier
	s_add_i32 s49, s49, 2
	s_add_u32 s24, s24, 0x100
	s_addc_u32 s25, s25, 0
	s_add_u32 s47, s47, 0x100
	s_addc_u32 s48, s48, 0
	s_cmp_gt_u32 s49, 13
	s_cbranch_scc0 .LBB0_893
	s_and_b64 vcc, exec, s[14:15]
	s_cbranch_vccz .LBB0_896
	s_barrier

; #define PG8_STAGE(bufoff, gbase, voff) do { _Pragma("unroll") for (int _i = 0; _i < 2; ++_i) \
;         __builtin_amdgcn_global_load_lds((const unsigned*)((const char*)(gbase) + (voff)[_i]), (LAS unsigned*)(lds + (bufoff) + ldsw + _i * 8192), 16, 0, 0); } while (0)
; #define PG8_LDA(dst, b, h) do { _Pragma("unroll") for (int m = 0; m < 4; ++m) _Pragma("unroll") for (int k = 0; k < 2; ++k) dst[m][k] = *(const LAS bf16x8*)(lds + PG8_SA(b, h) + aoff + m * 2048 + k * 1024); } while (0)
; #define PG8_LDB(dst, b, h) do { _Pragma("unroll") for (int n = 0; n < 2; ++n) _Pragma("unroll") for (int k = 0; k < 2; ++k) dst[n][k] = *(const LAS bf16x8*)(lds + PG8_SB(b, h) + boff + n * 2048 + k * 1024); } while (0)
; #define PG8_MMA(ai, bj, At, Bt) do { __builtin_amdgcn_s_setprio(1); _Pragma("unroll") for (int m = 0; m < 4; ++m) _Pragma("unroll") for (int n = 0; n < 2; ++n) _Pragma("unroll") for (int k = 0; k < 2; ++k) \
;         acc[ai][bj][m][n] = __builtin_amdgcn_mfma_f32_16x16x32_bf16(Bt[n][k], At[m][k], acc[ai][bj][m][n], 0, 0, 0); __builtin_amdgcn_s_setprio(0); } while (0)
; #define PG8_WAIT_V(n) asm volatile("s_waitcnt vmcnt(" #n ")" ::: "memory")
; #define PG8_WAIT_L(n) asm volatile("s_waitcnt lgkmcnt(" #n ")" ::: "memory")
; #define PG8_BAR __builtin_amdgcn_s_barrier()
; #define PG8_SCHED __builtin_amdgcn_sched_barrier(0)
; template <class Epi, class Sched>
; __device__ __forceinline__ void gemm_phase(int wv, LAS unsigned char* lds, const Gemm g, const Sched& S, const Epi& E) {
;     ...
;         for (int t = 0; t < nt; t += 2) {
;             const bool last = (t == nt - 2);
;             const char* a1 = cA + (size_t)(t + 1) * kstep;
;             const char* a2 = last ? nA : cA + (size_t)(t + 2) * kstep; const char* b2 = last ? nB : cB + (size_t)(t + 2) * kstep;
;             const char* a3 = a2 + kstep; const char* b3 = b2 + kstep;
;             PG8_LDB(B0, 0, 0); PG8_LDB(B1, 0, 1); PG8_SCHED; PG8_LDA(At, 0, 0); PG8_STAGE(PG8_SA(1, 1), a1 + hstep, voffA);
;             PG8_WAIT_V(8); PG8_WAIT_L(0); PG8_BAR; PG8_MMA(0, 0, At, B0); PG8_MMA(0, 1, At, B1); PG8_BAR; PG8_SCHED;
;             PG8_LDA(At, 0, 1); PG8_STAGE(PG8_SB(0, 0), b2, voffB); PG8_STAGE(PG8_SB(0, 1), b2 + hstepB, voffB); PG8_STAGE(PG8_SA(0, 0), a2, voffA);
;             PG8_WAIT_V(8); PG8_WAIT_L(0); PG8_BAR; PG8_MMA(1, 0, At, B0); PG8_MMA(1, 1, At, B1); PG8_BAR; PG8_SCHED;
.LBB0_978:
	s_add_u32 s20, s18, 0xfffc0080
	s_addc_u32 s21, s19, -1
	s_add_i32 s44, 0, 0x10000
	s_cmp_eq_u32 s43, 12
	s_cselect_b32 s23, s11, s21
	s_cselect_b32 s22, s39, s20
	s_cselect_b32 s21, s13, s42
	s_cselect_b32 s20, s40, s41
	s_add_i32 s46, 0, 0x14000
	v_add_u32_e32 v154, s44, v143
	v_add_u32_e32 v170, s46, v143
	ds_read_b128 v[138:141], v154
	ds_read_b128 v[146:149], v154 offset:1024
	ds_read_b128 v[150:153], v154 offset:2048
	ds_read_b128 v[154:157], v154 offset:3072
	ds_read_b128 v[158:161], v170
	ds_read_b128 v[162:165], v170 offset:1024
	ds_read_b128 v[166:169], v170 offset:2048
	ds_read_b128 v[170:173], v170 offset:3072
	v_lshl_add_u64 v[186:187], s[18:19], 0, v[134:135]
	s_add_i32 m0, s29, 0xc000
	ds_read_b128 v[174:177], v145
	ds_read_b128 v[178:181], v145 offset:1024
	ds_read_b128 v[182:185], v145 offset:2048
	ds_read_b128 v[198:201], v145 offset:3072
	ds_read_b128 v[202:205], v145 offset:4096
	ds_read_b128 v[206:209], v145 offset:5120
	ds_read_b128 v[210:213], v145 offset:6144
	ds_read_b128 v[214:217], v145 offset:7168
	global_load_lds_dwordx4 v[186:187], off
	v_lshl_add_u64 v[186:187], s[18:19], 0, v[136:137]
	s_add_i32 m0, s29, 0xe000
	s_nop 0
	global_load_lds_dwordx4 v[186:187], off
	s_waitcnt vmcnt(8)
	s_waitcnt lgkmcnt(0)
	s_setprio 1
	s_waitcnt lgkmcnt(0)
	v_mfma_f32_16x16x32_bf16 v[124:127], v[138:141], v[174:177], v[124:127]
	v_mfma_f32_16x16x32_bf16 v[120:123], v[150:153], v[174:177], v[120:123]
	v_mfma_f32_16x16x32_bf16 v[108:111], v[138:141], v[182:185], v[108:111]
	v_mfma_f32_16x16x32_bf16 v[100:103], v[150:153], v[182:185], v[100:103]
	v_mfma_f32_16x16x32_bf16 v[92:95], v[138:141], v[202:205], v[92:95]
	v_mfma_f32_16x16x32_bf16 v[84:87], v[150:153], v[202:205], v[84:87]
	v_mfma_f32_16x16x32_bf16 v[76:79], v[138:141], v[210:213], v[76:79]
	v_mfma_f32_16x16x32_bf16 v[68:71], v[150:153], v[210:213], v[68:71]
	s_barrier
	v_mfma_f32_16x16x32_bf16 v[124:127], v[146:149], v[178:181], v[124:127]
	v_mfma_f32_16x16x32_bf16 v[120:123], v[154:157], v[178:181], v[120:123]
	v_mfma_f32_16x16x32_bf16 v[108:111], v[146:149], v[198:201], v[108:111]
	v_mfma_f32_16x16x32_bf16 v[100:103], v[154:157], v[198:201], v[100:103]
	v_mfma_f32_16x16x32_bf16 v[92:95], v[146:149], v[206:209], v[92:95]
	v_mfma_f32_16x16x32_bf16 v[84:87], v[154:157], v[206:209], v[84:87]
	v_mfma_f32_16x16x32_bf16 v[76:79], v[146:149], v[214:217], v[76:79]
	v_mfma_f32_16x16x32_bf16 v[68:71], v[154:157], v[214:217], v[68:71]
	s_setprio 0
	s_setprio 1
	v_mfma_f32_16x16x32_bf16 v[116:119], v[158:161], v[174:177], v[116:119]
	v_mfma_f32_16x16x32_bf16 v[112:115], v[166:169], v[174:177], v[112:115]
	v_mfma_f32_16x16x32_bf16 v[104:107], v[158:161], v[182:185], v[104:107]
	v_mfma_f32_16x16x32_bf16 v[96:99], v[166:169], v[182:185], v[96:99]
	v_mfma_f32_16x16x32_bf16 v[88:91], v[158:161], v[202:205], v[88:91]
	v_mfma_f32_16x16x32_bf16 v[80:83], v[166:169], v[202:205], v[80:83]
	v_mfma_f32_16x16x32_bf16 v[72:75], v[158:161], v[210:213], v[72:75]
	v_mfma_f32_16x16x32_bf16 v[64:67], v[166:169], v[210:213], v[64:67]
	v_mfma_f32_16x16x32_bf16 v[116:119], v[162:165], v[178:181], v[116:119]
	v_mfma_f32_16x16x32_bf16 v[112:115], v[170:173], v[178:181], v[112:115]
	v_mfma_f32_16x16x32_bf16 v[104:107], v[162:165], v[198:201], v[104:107]
	v_mfma_f32_16x16x32_bf16 v[96:99], v[170:173], v[198:201], v[96:99]
	v_mfma_f32_16x16x32_bf16 v[88:91], v[162:165], v[206:209], v[88:91]
	v_mfma_f32_16x16x32_bf16 v[80:83], v[170:173], v[206:209], v[80:83]
	v_mfma_f32_16x16x32_bf16 v[72:75], v[162:165], v[214:217], v[72:75]
	v_mfma_f32_16x16x32_bf16 v[64:67], v[170:173], v[214:217], v[64:67]
	s_setprio 0
	s_barrier
	s_add_i32 s44, s44, s28
	v_lshl_add_u64 v[186:187], s[20:21], 0, v[188:189]
	s_mov_b32 m0, s44
	ds_read_b128 v[174:177], v145 offset:16384
	ds_read_b128 v[178:181], v145 offset:17408
	ds_read_b128 v[182:185], v145 offset:18432
	ds_read_b128 v[198:201], v145 offset:19456
	ds_read_b128 v[202:205], v145 offset:20480
	ds_read_b128 v[206:209], v145 offset:21504
	ds_read_b128 v[210:213], v145 offset:22528
	ds_read_b128 v[214:217], v145 offset:23552
	global_load_lds_dwordx4 v[186:187], off
	s_add_i32 m0, s44, 0x2000
	s_add_u32 s44, s20, 0x40000
	v_lshl_add_u64 v[218:219], s[20:21], 0, v[128:129]
	s_addc_u32 s45, s21, 0
	s_add_i32 s46, s46, s28
	global_load_lds_dwordx4 v[218:219], off
	v_lshl_add_u64 v[220:221], s[44:45], 0, v[188:189]
	s_mov_b32 m0, s46
	v_lshl_add_u64 v[222:223], s[22:23], 0, v[130:131]
	global_load_lds_dwordx4 v[220:221], off
	v_lshl_add_u64 v[220:221], s[44:45], 0, v[128:129]
	s_add_i32 m0, s46, 0x2000
	s_nop 0
	global_load_lds_dwordx4 v[220:221], off
	v_lshl_add_u64 v[220:221], s[22:23], 0, v[132:133]
	s_mov_b32 m0, s29
	s_nop 0
	global_load_lds_dwordx4 v[220:221], off
	s_mov_b32 m0, s30
	s_nop 0
	global_load_lds_dwordx4 v[222:223], off
	s_waitcnt vmcnt(8)
	s_waitcnt lgkmcnt(0)
	s_setprio 1
	s_waitcnt lgkmcnt(0)
	v_mfma_f32_16x16x32_bf16 v[60:63], v[138:141], v[174:177], v[60:63]
	v_mfma_f32_16x16x32_bf16 v[52:55], v[150:153], v[174:177], v[52:55]
	v_mfma_f32_16x16x32_bf16 v[44:47], v[138:141], v[182:185], v[44:47]
	v_mfma_f32_16x16x32_bf16 v[36:39], v[150:153], v[182:185], v[36:39]
	v_mfma_f32_16x16x32_bf16 v[28:31], v[138:141], v[202:205], v[28:31]
	v_mfma_f32_16x16x32_bf16 v[20:23], v[150:153], v[202:205], v[20:23]
	v_mfma_f32_16x16x32_bf16 v[12:15], v[138:141], v[210:213], v[12:15]
	v_mfma_f32_16x16x32_bf16 v[4:7], v[150:153], v[210:213], v[4:7]
	s_barrier
; #define PG8_STAGE(bufoff, gbase, voff) do { _Pragma("unroll") for (int _i = 0; _i < 2; ++_i) \
;         __builtin_amdgcn_global_load_lds((const unsigned*)((const char*)(gbase) + (voff)[_i]), (LAS unsigned*)(lds + (bufoff) + ldsw + _i * 8192), 16, 0, 0); } while (0)
; #define PG8_LDA(dst, b, h) do { _Pragma("unroll") for (int m = 0; m < 4; ++m) _Pragma("unroll") for (int k = 0; k < 2; ++k) dst[m][k] = *(const LAS bf16x8*)(lds + PG8_SA(b, h) + aoff + m * 2048 + k * 1024); } while (0)
; #define PG8_LDB(dst, b, h) do { _Pragma("unroll") for (int n = 0; n < 2; ++n) _Pragma("unroll") for (int k = 0; k < 2; ++k) dst[n][k] = *(const LAS bf16x8*)(lds + PG8_SB(b, h) + boff + n * 2048 + k * 1024); } while (0)
; #define PG8_MMA(ai, bj, At, Bt) do { __builtin_amdgcn_s_setprio(1); _Pragma("unroll") for (int m = 0; m < 4; ++m) _Pragma("unroll") for (int n = 0; n < 2; ++n) _Pragma("unroll") for (int k = 0; k < 2; ++k) \
;         acc[ai][bj][m][n] = __builtin_amdgcn_mfma_f32_16x16x32_bf16(Bt[n][k], At[m][k], acc[ai][bj][m][n], 0, 0, 0); __builtin_amdgcn_s_setprio(0); } while (0)
; #define PG8_WAIT_V(n) asm volatile("s_waitcnt vmcnt(" #n ")" ::: "memory")
; #define PG8_WAIT_L(n) asm volatile("s_waitcnt lgkmcnt(" #n ")" ::: "memory")
; #define PG8_BAR __builtin_amdgcn_s_barrier()
; #define PG8_SCHED __builtin_amdgcn_sched_barrier(0)
; template <class Epi, class Sched>
; __device__ __forceinline__ void gemm_phase(int wv, LAS unsigned char* lds, const Gemm g, const Sched& S, const Epi& E) {
;     ...
;             PG8_WAIT_V(8); PG8_WAIT_L(0); PG8_BAR; PG8_MMA(1, 0, At, B0); PG8_MMA(1, 1, At, B1); PG8_BAR; PG8_SCHED;
;             PG8_LDB(B0, 1, 0); PG8_LDB(B1, 1, 1); PG8_SCHED; PG8_LDA(At, 1, 0); PG8_STAGE(PG8_SA(0, 1), a2 + hstep, voffA);
;             PG8_WAIT_V(8); PG8_WAIT_L(0); PG8_BAR; PG8_MMA(0, 0, At, B0); PG8_MMA(0, 1, At, B1); PG8_BAR; PG8_SCHED;
	v_mfma_f32_16x16x32_bf16 v[60:63], v[146:149], v[178:181], v[60:63]
	v_mfma_f32_16x16x32_bf16 v[52:55], v[154:157], v[178:181], v[52:55]
	v_mfma_f32_16x16x32_bf16 v[44:47], v[146:149], v[198:201], v[44:47]
	v_mfma_f32_16x16x32_bf16 v[36:39], v[154:157], v[198:201], v[36:39]
	v_mfma_f32_16x16x32_bf16 v[28:31], v[146:149], v[206:209], v[28:31]
	v_mfma_f32_16x16x32_bf16 v[20:23], v[154:157], v[206:209], v[20:23]
	v_mfma_f32_16x16x32_bf16 v[12:15], v[146:149], v[214:217], v[12:15]
	v_mfma_f32_16x16x32_bf16 v[4:7], v[154:157], v[214:217], v[4:7]
	s_setprio 0
	s_setprio 1
	v_mfma_f32_16x16x32_bf16 v[56:59], v[158:161], v[174:177], v[56:59]
	v_mfma_f32_16x16x32_bf16 v[48:51], v[166:169], v[174:177], v[48:51]
	v_mfma_f32_16x16x32_bf16 v[40:43], v[158:161], v[182:185], v[40:43]
	v_mfma_f32_16x16x32_bf16 v[32:35], v[166:169], v[182:185], v[32:35]
	v_mfma_f32_16x16x32_bf16 v[24:27], v[158:161], v[202:205], v[24:27]
	v_mfma_f32_16x16x32_bf16 v[16:19], v[166:169], v[202:205], v[16:19]
	v_mfma_f32_16x16x32_bf16 v[8:11], v[158:161], v[210:213], v[8:11]
	v_mfma_f32_16x16x32_bf16 v[0:3], v[166:169], v[210:213], v[0:3]
	v_mfma_f32_16x16x32_bf16 v[56:59], v[162:165], v[178:181], v[56:59]
	v_mfma_f32_16x16x32_bf16 v[48:51], v[170:173], v[178:181], v[48:51]
	v_mfma_f32_16x16x32_bf16 v[40:43], v[162:165], v[198:201], v[40:43]
	v_mfma_f32_16x16x32_bf16 v[32:35], v[170:173], v[198:201], v[32:35]
	v_mfma_f32_16x16x32_bf16 v[24:27], v[162:165], v[206:209], v[24:27]
	v_mfma_f32_16x16x32_bf16 v[16:19], v[170:173], v[206:209], v[16:19]
	v_mfma_f32_16x16x32_bf16 v[8:11], v[162:165], v[214:217], v[8:11]
	v_mfma_f32_16x16x32_bf16 v[0:3], v[170:173], v[214:217], v[0:3]
	s_setprio 0
	s_barrier
	s_add_i32 s44, 0, 0x1c000
	v_add_u32_e32 v154, s95, v143
	v_add_u32_e32 v170, s44, v143
	ds_read_b128 v[138:141], v154
	ds_read_b128 v[146:149], v154 offset:1024
	ds_read_b128 v[150:153], v154 offset:2048
	ds_read_b128 v[154:157], v154 offset:3072
	ds_read_b128 v[158:161], v170
	ds_read_b128 v[162:165], v170 offset:1024
	ds_read_b128 v[166:169], v170 offset:2048
	ds_read_b128 v[170:173], v170 offset:3072
	s_add_u32 s22, s22, 0x40000
	s_addc_u32 s23, s23, 0
	s_mov_b32 m0, s31
	v_lshl_add_u64 v[228:229], s[22:23], 0, v[132:133]
	ds_read_b128 v[174:177], v145 offset:32768
	ds_read_b128 v[178:181], v145 offset:33792
	ds_read_b128 v[182:185], v145 offset:34816
	ds_read_b128 v[198:201], v145 offset:35840
	ds_read_b128 v[202:205], v145 offset:36864
	ds_read_b128 v[206:209], v145 offset:37888
	ds_read_b128 v[210:213], v145 offset:38912
	ds_read_b128 v[214:217], v145 offset:39936
	global_load_lds_dwordx4 v[228:229], off
	v_lshl_add_u64 v[228:229], s[22:23], 0, v[130:131]
	s_mov_b32 m0, s34
	s_nop 0
	global_load_lds_dwordx4 v[228:229], off
	s_waitcnt vmcnt(8)
	s_waitcnt lgkmcnt(0)
	s_setprio 1
	s_waitcnt lgkmcnt(0)
	v_mfma_f32_16x16x32_bf16 v[124:127], v[138:141], v[174:177], v[124:127]
	v_mfma_f32_16x16x32_bf16 v[120:123], v[150:153], v[174:177], v[120:123]
	v_mfma_f32_16x16x32_bf16 v[108:111], v[138:141], v[182:185], v[108:111]
	v_mfma_f32_16x16x32_bf16 v[100:103], v[150:153], v[182:185], v[100:103]
	v_mfma_f32_16x16x32_bf16 v[92:95], v[138:141], v[202:205], v[92:95]
	v_mfma_f32_16x16x32_bf16 v[84:87], v[150:153], v[202:205], v[84:87]
	v_mfma_f32_16x16x32_bf16 v[76:79], v[138:141], v[210:213], v[76:79]
	v_mfma_f32_16x16x32_bf16 v[68:71], v[150:153], v[210:213], v[68:71]
	s_barrier
	v_mfma_f32_16x16x32_bf16 v[124:127], v[146:149], v[178:181], v[124:127]
	v_mfma_f32_16x16x32_bf16 v[120:123], v[154:157], v[178:181], v[120:123]
	v_mfma_f32_16x16x32_bf16 v[108:111], v[146:149], v[198:201], v[108:111]
	v_mfma_f32_16x16x32_bf16 v[100:103], v[154:157], v[198:201], v[100:103]
	v_mfma_f32_16x16x32_bf16 v[92:95], v[146:149], v[206:209], v[92:95]
	v_mfma_f32_16x16x32_bf16 v[84:87], v[154:157], v[206:209], v[84:87]
	v_mfma_f32_16x16x32_bf16 v[76:79], v[146:149], v[214:217], v[76:79]
	v_mfma_f32_16x16x32_bf16 v[68:71], v[154:157], v[214:217], v[68:71]
	s_setprio 0
	s_setprio 1
	v_mfma_f32_16x16x32_bf16 v[116:119], v[158:161], v[174:177], v[116:119]
	v_mfma_f32_16x16x32_bf16 v[112:115], v[166:169], v[174:177], v[112:115]
	v_mfma_f32_16x16x32_bf16 v[104:107], v[158:161], v[182:185], v[104:107]
	v_mfma_f32_16x16x32_bf16 v[96:99], v[166:169], v[182:185], v[96:99]
	v_mfma_f32_16x16x32_bf16 v[88:91], v[158:161], v[202:205], v[88:91]
	v_mfma_f32_16x16x32_bf16 v[80:83], v[166:169], v[202:205], v[80:83]
	v_mfma_f32_16x16x32_bf16 v[72:75], v[158:161], v[210:213], v[72:75]
	v_mfma_f32_16x16x32_bf16 v[64:67], v[166:169], v[210:213], v[64:67]
	v_mfma_f32_16x16x32_bf16 v[116:119], v[162:165], v[178:181], v[116:119]
	v_mfma_f32_16x16x32_bf16 v[112:115], v[170:173], v[178:181], v[112:115]
	v_mfma_f32_16x16x32_bf16 v[104:107], v[162:165], v[198:201], v[104:107]
	v_mfma_f32_16x16x32_bf16 v[96:99], v[170:173], v[198:201], v[96:99]
	v_mfma_f32_16x16x32_bf16 v[88:91], v[162:165], v[206:209], v[88:91]
	v_mfma_f32_16x16x32_bf16 v[80:83], v[170:173], v[206:209], v[80:83]
	v_mfma_f32_16x16x32_bf16 v[72:75], v[162:165], v[214:217], v[72:75]
	v_mfma_f32_16x16x32_bf16 v[64:67], v[170:173], v[214:217], v[64:67]
	s_setprio 0
	s_barrier
; #define PG8_STAGE(bufoff, gbase, voff) do { _Pragma("unroll") for (int _i = 0; _i < 2; ++_i) \
;         __builtin_amdgcn_global_load_lds((const unsigned*)((const char*)(gbase) + (voff)[_i]), (LAS unsigned*)(lds + (bufoff) + ldsw + _i * 8192), 16, 0, 0); } while (0)
; #define PG8_LDA(dst, b, h) do { _Pragma("unroll") for (int m = 0; m < 4; ++m) _Pragma("unroll") for (int k = 0; k < 2; ++k) dst[m][k] = *(const LAS bf16x8*)(lds + PG8_SA(b, h) + aoff + m * 2048 + k * 1024); } while (0)
; #define PG8_MMA(ai, bj, At, Bt) do { __builtin_amdgcn_s_setprio(1); _Pragma("unroll") for (int m = 0; m < 4; ++m) _Pragma("unroll") for (int n = 0; n < 2; ++n) _Pragma("unroll") for (int k = 0; k < 2; ++k) \
;         acc[ai][bj][m][n] = __builtin_amdgcn_mfma_f32_16x16x32_bf16(Bt[n][k], At[m][k], acc[ai][bj][m][n], 0, 0, 0); __builtin_amdgcn_s_setprio(0); } while (0)
; #define PG8_WAIT_V(n) asm volatile("s_waitcnt vmcnt(" #n ")" ::: "memory")
; #define PG8_WAIT_L(n) asm volatile("s_waitcnt lgkmcnt(" #n ")" ::: "memory")
; #define PG8_BAR __builtin_amdgcn_s_barrier()
; #define PG8_SCHED __builtin_amdgcn_sched_barrier(0)
; template <class Epi, class Sched>
; __device__ __forceinline__ void gemm_phase(int wv, LAS unsigned char* lds, const Gemm g, const Sched& S, const Epi& E) {
;     ...
;             PG8_LDA(At, 1, 1); PG8_STAGE(PG8_SB(1, 0), b3, voffB); PG8_STAGE(PG8_SB(1, 1), b3 + hstepB, voffB); PG8_STAGE(PG8_SA(1, 0), a3, voffA);
;             PG8_WAIT_V(8); PG8_WAIT_L(0); PG8_BAR; PG8_MMA(1, 0, At, B0); PG8_MMA(1, 1, At, B1); PG8_BAR; PG8_SCHED;
;         }
;         if (wr == 0) PG8_BAR;
	s_add_i32 s22, s95, s28
	v_lshl_add_u64 v[186:187], v[186:187], 0, s[74:75]
	s_mov_b32 m0, s22
	ds_read_b128 v[174:177], v145 offset:49152
	ds_read_b128 v[178:181], v145 offset:50176
	ds_read_b128 v[182:185], v145 offset:51200
	ds_read_b128 v[198:201], v145 offset:52224
	ds_read_b128 v[202:205], v145 offset:53248
	ds_read_b128 v[206:209], v145 offset:54272
	ds_read_b128 v[210:213], v145 offset:55296
	ds_read_b128 v[214:217], v145 offset:56320
	global_load_lds_dwordx4 v[186:187], off
	s_add_i32 m0, s22, 0x2000
	s_add_u32 s20, s20, 0x40080
	v_lshl_add_u64 v[186:187], v[218:219], 0, s[74:75]
	s_addc_u32 s21, s21, 0
	s_add_i32 s22, s44, s28
	global_load_lds_dwordx4 v[186:187], off
	v_lshl_add_u64 v[186:187], s[20:21], 0, v[188:189]
	s_mov_b32 m0, s22
	s_nop 0
	global_load_lds_dwordx4 v[186:187], off
	v_lshl_add_u64 v[186:187], s[20:21], 0, v[128:129]
	s_add_i32 m0, s22, 0x2000
	s_nop 0
	global_load_lds_dwordx4 v[186:187], off
	v_lshl_add_u64 v[186:187], v[220:221], 0, s[74:75]
	s_mov_b32 m0, s35
	s_nop 0
	global_load_lds_dwordx4 v[186:187], off
	v_lshl_add_u64 v[186:187], v[222:223], 0, s[74:75]
	s_mov_b32 m0, s36
	s_nop 0
	global_load_lds_dwordx4 v[186:187], off
	s_waitcnt vmcnt(8)
	s_waitcnt lgkmcnt(0)
	s_setprio 1
	s_waitcnt lgkmcnt(0)
	v_mfma_f32_16x16x32_bf16 v[60:63], v[138:141], v[174:177], v[60:63]
	v_mfma_f32_16x16x32_bf16 v[52:55], v[150:153], v[174:177], v[52:55]
	v_mfma_f32_16x16x32_bf16 v[44:47], v[138:141], v[182:185], v[44:47]
	v_mfma_f32_16x16x32_bf16 v[36:39], v[150:153], v[182:185], v[36:39]
	v_mfma_f32_16x16x32_bf16 v[28:31], v[138:141], v[202:205], v[28:31]
	v_mfma_f32_16x16x32_bf16 v[20:23], v[150:153], v[202:205], v[20:23]
	v_mfma_f32_16x16x32_bf16 v[12:15], v[138:141], v[210:213], v[12:15]
	v_mfma_f32_16x16x32_bf16 v[4:7], v[150:153], v[210:213], v[4:7]
	s_barrier
	v_mfma_f32_16x16x32_bf16 v[60:63], v[146:149], v[178:181], v[60:63]
	v_mfma_f32_16x16x32_bf16 v[52:55], v[154:157], v[178:181], v[52:55]
	v_mfma_f32_16x16x32_bf16 v[44:47], v[146:149], v[198:201], v[44:47]
	v_mfma_f32_16x16x32_bf16 v[36:39], v[154:157], v[198:201], v[36:39]
	v_mfma_f32_16x16x32_bf16 v[28:31], v[146:149], v[206:209], v[28:31]
	v_mfma_f32_16x16x32_bf16 v[20:23], v[154:157], v[206:209], v[20:23]
	v_mfma_f32_16x16x32_bf16 v[12:15], v[146:149], v[214:217], v[12:15]
	v_mfma_f32_16x16x32_bf16 v[4:7], v[154:157], v[214:217], v[4:7]
	s_setprio 0
	s_setprio 1
	v_mfma_f32_16x16x32_bf16 v[56:59], v[158:161], v[174:177], v[56:59]
	v_mfma_f32_16x16x32_bf16 v[48:51], v[166:169], v[174:177], v[48:51]
	v_mfma_f32_16x16x32_bf16 v[40:43], v[158:161], v[182:185], v[40:43]
	v_mfma_f32_16x16x32_bf16 v[32:35], v[166:169], v[182:185], v[32:35]
	v_mfma_f32_16x16x32_bf16 v[24:27], v[158:161], v[202:205], v[24:27]
	v_mfma_f32_16x16x32_bf16 v[16:19], v[166:169], v[202:205], v[16:19]
	v_mfma_f32_16x16x32_bf16 v[8:11], v[158:161], v[210:213], v[8:11]
	v_mfma_f32_16x16x32_bf16 v[0:3], v[166:169], v[210:213], v[0:3]
	v_mfma_f32_16x16x32_bf16 v[56:59], v[162:165], v[178:181], v[56:59]
	v_mfma_f32_16x16x32_bf16 v[48:51], v[170:173], v[178:181], v[48:51]
	v_mfma_f32_16x16x32_bf16 v[40:43], v[162:165], v[198:201], v[40:43]
	v_mfma_f32_16x16x32_bf16 v[32:35], v[170:173], v[198:201], v[32:35]
	v_mfma_f32_16x16x32_bf16 v[24:27], v[162:165], v[206:209], v[24:27]
	v_mfma_f32_16x16x32_bf16 v[16:19], v[170:173], v[206:209], v[16:19]
	v_mfma_f32_16x16x32_bf16 v[8:11], v[162:165], v[214:217], v[8:11]
	v_mfma_f32_16x16x32_bf16 v[0:3], v[170:173], v[214:217], v[0:3]
	s_setprio 0
	s_barrier
	s_add_i32 s43, s43, 2
	s_add_u32 s18, s18, 0x100
	s_addc_u32 s19, s19, 0
	s_add_u32 s41, s41, 0x100
	s_addc_u32 s42, s42, 0
	s_cmp_gt_u32 s43, 13
	s_cbranch_scc0 .LBB0_978
	s_and_b64 vcc, exec, s[8:9]
	s_cbranch_vccz .LBB0_981
	s_barrier

; #define PG8_STAGE(bufoff, gbase, voff) do { _Pragma("unroll") for (int _i = 0; _i < 2; ++_i) \
;         __builtin_amdgcn_global_load_lds((const unsigned*)((const char*)(gbase) + (voff)[_i]), (LAS unsigned*)(lds + (bufoff) + ldsw + _i * 8192), 16, 0, 0); } while (0)
; #define PG8_LDA(dst, b, h) do { _Pragma("unroll") for (int m = 0; m < 4; ++m) _Pragma("unroll") for (int k = 0; k < 2; ++k) dst[m][k] = *(const LAS bf16x8*)(lds + PG8_SA(b, h) + aoff + m * 2048 + k * 1024); } while (0)
; #define PG8_LDB(dst, b, h) do { _Pragma("unroll") for (int n = 0; n < 2; ++n) _Pragma("unroll") for (int k = 0; k < 2; ++k) dst[n][k] = *(const LAS bf16x8*)(lds + PG8_SB(b, h) + boff + n * 2048 + k * 1024); } while (0)
; #define PG8_MMA(ai, bj, At, Bt) do { __builtin_amdgcn_s_setprio(1); _Pragma("unroll") for (int m = 0; m < 4; ++m) _Pragma("unroll") for (int n = 0; n < 2; ++n) _Pragma("unroll") for (int k = 0; k < 2; ++k) \
;         acc[ai][bj][m][n] = __builtin_amdgcn_mfma_f32_16x16x32_bf16(Bt[n][k], At[m][k], acc[ai][bj][m][n], 0, 0, 0); __builtin_amdgcn_s_setprio(0); } while (0)
; #define PG8_WAIT_V(n) asm volatile("s_waitcnt vmcnt(" #n ")" ::: "memory")
; #define PG8_WAIT_L(n) asm volatile("s_waitcnt lgkmcnt(" #n ")" ::: "memory")
; #define PG8_BAR __builtin_amdgcn_s_barrier()
; #define PG8_SCHED __builtin_amdgcn_sched_barrier(0)
; template <class Epi, class Sched>
; __device__ __forceinline__ void gemm_phase(int wv, LAS unsigned char* lds, const Gemm g, const Sched& S, const Epi& E) {
;     ...
;         for (int t = 0; t < nt; t += 2) {
;             const bool last = (t == nt - 2);
;             const char* a1 = cA + (size_t)(t + 1) * kstep;
;             const char* a2 = last ? nA : cA + (size_t)(t + 2) * kstep; const char* b2 = last ? nB : cB + (size_t)(t + 2) * kstep;
;             const char* a3 = a2 + kstep; const char* b3 = b2 + kstep;
;             PG8_LDB(B0, 0, 0); PG8_LDB(B1, 0, 1); PG8_SCHED; PG8_LDA(At, 0, 0); PG8_STAGE(PG8_SA(1, 1), a1 + hstep, voffA);
;             PG8_WAIT_V(8); PG8_WAIT_L(0); PG8_BAR; PG8_MMA(0, 0, At, B0); PG8_MMA(0, 1, At, B1); PG8_BAR; PG8_SCHED;
;             PG8_LDA(At, 0, 1); PG8_STAGE(PG8_SB(0, 0), b2, voffB); PG8_STAGE(PG8_SB(0, 1), b2 + hstepB, voffB); PG8_STAGE(PG8_SA(0, 0), a2, voffA);
;             PG8_WAIT_V(8); PG8_WAIT_L(0); PG8_BAR; PG8_MMA(1, 0, At, B0); PG8_MMA(1, 1, At, B1); PG8_BAR; PG8_SCHED;
.LBB0_1055:
	s_add_u32 s4, s22, 0x100
	s_addc_u32 s5, s23, 0
	s_add_i32 s48, 0, 0x10000
	s_cmp_eq_u32 s47, 40
	s_cselect_b32 s27, s19, s5
	s_cselect_b32 s26, s18, s4
	s_cselect_b32 s25, s21, s46
	s_cselect_b32 s24, s20, s45
	s_add_i32 s49, 0, 0x14000
	v_add_u32_e32 v136, s48, v213
	v_add_u32_e32 v156, s49, v213
	ds_read_b128 v[96:99], v136
	ds_read_b128 v[100:103], v136 offset:1024
	ds_read_b128 v[104:107], v136 offset:2048
	ds_read_b128 v[136:139], v136 offset:3072
	ds_read_b128 v[140:143], v156
	ds_read_b128 v[144:147], v156 offset:1024
	ds_read_b128 v[152:155], v156 offset:2048
	ds_read_b128 v[156:159], v156 offset:3072
	v_lshl_add_u64 v[186:187], s[22:23], 0, v[182:183]
	s_add_i32 m0, s35, 0xc000
	ds_read_b128 v[160:163], v217
	ds_read_b128 v[164:167], v217 offset:1024
	ds_read_b128 v[168:171], v217 offset:2048
	ds_read_b128 v[172:175], v217 offset:3072
	ds_read_b128 v[198:201], v217 offset:4096
	ds_read_b128 v[202:205], v217 offset:5120
	ds_read_b128 v[206:209], v217 offset:6144
	ds_read_b128 v[218:221], v217 offset:7168
	global_load_lds_dwordx4 v[186:187], off
	v_lshl_add_u64 v[186:187], s[22:23], 0, v[184:185]
	s_add_i32 m0, s35, 0xe000
	s_nop 0
	global_load_lds_dwordx4 v[186:187], off
	s_waitcnt vmcnt(8)
	s_waitcnt lgkmcnt(0)
	s_setprio 1
	s_waitcnt lgkmcnt(0)
	v_mfma_f32_16x16x32_bf16 v[148:151], v[96:99], v[160:163], v[148:151]
	v_mfma_f32_16x16x32_bf16 v[124:127], v[104:107], v[160:163], v[124:127]
	v_mfma_f32_16x16x32_bf16 v[132:135], v[96:99], v[168:171], v[132:135]
	v_mfma_f32_16x16x32_bf16 v[128:131], v[104:107], v[168:171], v[128:131]
	v_mfma_f32_16x16x32_bf16 v[92:95], v[96:99], v[198:201], v[92:95]
	v_mfma_f32_16x16x32_bf16 v[88:91], v[104:107], v[198:201], v[88:91]
	v_mfma_f32_16x16x32_bf16 v[76:79], v[96:99], v[206:209], v[76:79]
	v_mfma_f32_16x16x32_bf16 v[72:75], v[104:107], v[206:209], v[72:75]
	s_barrier
	v_mfma_f32_16x16x32_bf16 v[148:151], v[100:103], v[164:167], v[148:151]
	v_mfma_f32_16x16x32_bf16 v[124:127], v[136:139], v[164:167], v[124:127]
	v_mfma_f32_16x16x32_bf16 v[132:135], v[100:103], v[172:175], v[132:135]
	v_mfma_f32_16x16x32_bf16 v[128:131], v[136:139], v[172:175], v[128:131]
	v_mfma_f32_16x16x32_bf16 v[92:95], v[100:103], v[202:205], v[92:95]
	v_mfma_f32_16x16x32_bf16 v[88:91], v[136:139], v[202:205], v[88:91]
	v_mfma_f32_16x16x32_bf16 v[76:79], v[100:103], v[218:221], v[76:79]
	v_mfma_f32_16x16x32_bf16 v[72:75], v[136:139], v[218:221], v[72:75]
	s_setprio 0
	s_setprio 1
	v_mfma_f32_16x16x32_bf16 v[116:119], v[140:143], v[160:163], v[116:119]
	v_mfma_f32_16x16x32_bf16 v[108:111], v[152:155], v[160:163], v[108:111]
	v_mfma_f32_16x16x32_bf16 v[120:123], v[140:143], v[168:171], v[120:123]
	v_mfma_f32_16x16x32_bf16 v[112:115], v[152:155], v[168:171], v[112:115]
	v_mfma_f32_16x16x32_bf16 v[84:87], v[140:143], v[198:201], v[84:87]
	v_mfma_f32_16x16x32_bf16 v[80:83], v[152:155], v[198:201], v[80:83]
	v_mfma_f32_16x16x32_bf16 v[68:71], v[140:143], v[206:209], v[68:71]
	v_mfma_f32_16x16x32_bf16 v[64:67], v[152:155], v[206:209], v[64:67]
	v_mfma_f32_16x16x32_bf16 v[116:119], v[144:147], v[164:167], v[116:119]
	v_mfma_f32_16x16x32_bf16 v[108:111], v[156:159], v[164:167], v[108:111]
	v_mfma_f32_16x16x32_bf16 v[120:123], v[144:147], v[172:175], v[120:123]
	v_mfma_f32_16x16x32_bf16 v[112:115], v[156:159], v[172:175], v[112:115]
	v_mfma_f32_16x16x32_bf16 v[84:87], v[144:147], v[202:205], v[84:87]
	v_mfma_f32_16x16x32_bf16 v[80:83], v[156:159], v[202:205], v[80:83]
	v_mfma_f32_16x16x32_bf16 v[68:71], v[144:147], v[218:221], v[68:71]
	v_mfma_f32_16x16x32_bf16 v[64:67], v[156:159], v[218:221], v[64:67]
	s_setprio 0
	s_barrier
	s_add_i32 s22, s48, s34
	v_lshl_add_u64 v[186:187], s[24:25], 0, v[188:189]
	s_mov_b32 m0, s22
	ds_read_b128 v[160:163], v217 offset:16384
	ds_read_b128 v[164:167], v217 offset:17408
	ds_read_b128 v[168:171], v217 offset:18432
	ds_read_b128 v[172:175], v217 offset:19456
	ds_read_b128 v[198:201], v217 offset:20480
	ds_read_b128 v[202:205], v217 offset:21504
	ds_read_b128 v[206:209], v217 offset:22528
	ds_read_b128 v[218:221], v217 offset:23552
	global_load_lds_dwordx4 v[186:187], off
	s_add_i32 m0, s22, 0x2000
	s_add_u32 s22, s24, 0xb000
	v_lshl_add_u64 v[210:211], s[24:25], 0, v[176:177]
	s_addc_u32 s23, s25, 0
	s_add_i32 s48, s49, s34
	global_load_lds_dwordx4 v[210:211], off
	v_lshl_add_u64 v[222:223], s[22:23], 0, v[188:189]
	s_mov_b32 m0, s48
	v_lshl_add_u64 v[228:229], s[26:27], 0, v[178:179]
	global_load_lds_dwordx4 v[222:223], off
	v_lshl_add_u64 v[222:223], s[22:23], 0, v[176:177]
	s_add_i32 m0, s48, 0x2000
	s_nop 0
	global_load_lds_dwordx4 v[222:223], off
	v_lshl_add_u64 v[222:223], s[26:27], 0, v[180:181]
	s_mov_b32 m0, s35
	s_nop 0
	global_load_lds_dwordx4 v[222:223], off
	s_mov_b32 m0, s36
	s_nop 0
	global_load_lds_dwordx4 v[228:229], off
	s_waitcnt vmcnt(8)
	s_waitcnt lgkmcnt(0)
	s_setprio 1
	s_waitcnt lgkmcnt(0)
	v_mfma_f32_16x16x32_bf16 v[60:63], v[96:99], v[160:163], v[60:63]
	v_mfma_f32_16x16x32_bf16 v[56:59], v[104:107], v[160:163], v[56:59]
	v_mfma_f32_16x16x32_bf16 v[44:47], v[96:99], v[168:171], v[44:47]
	v_mfma_f32_16x16x32_bf16 v[40:43], v[104:107], v[168:171], v[40:43]
	v_mfma_f32_16x16x32_bf16 v[28:31], v[96:99], v[198:201], v[28:31]
	v_mfma_f32_16x16x32_bf16 v[24:27], v[104:107], v[198:201], v[24:27]
	v_mfma_f32_16x16x32_bf16 v[12:15], v[96:99], v[206:209], v[12:15]
	v_mfma_f32_16x16x32_bf16 v[8:11], v[104:107], v[206:209], v[8:11]
	s_barrier
; #define PG8_STAGE(bufoff, gbase, voff) do { _Pragma("unroll") for (int _i = 0; _i < 2; ++_i) \
;         __builtin_amdgcn_global_load_lds((const unsigned*)((const char*)(gbase) + (voff)[_i]), (LAS unsigned*)(lds + (bufoff) + ldsw + _i * 8192), 16, 0, 0); } while (0)
; #define PG8_LDA(dst, b, h) do { _Pragma("unroll") for (int m = 0; m < 4; ++m) _Pragma("unroll") for (int k = 0; k < 2; ++k) dst[m][k] = *(const LAS bf16x8*)(lds + PG8_SA(b, h) + aoff + m * 2048 + k * 1024); } while (0)
; #define PG8_LDB(dst, b, h) do { _Pragma("unroll") for (int n = 0; n < 2; ++n) _Pragma("unroll") for (int k = 0; k < 2; ++k) dst[n][k] = *(const LAS bf16x8*)(lds + PG8_SB(b, h) + boff + n * 2048 + k * 1024); } while (0)
; #define PG8_MMA(ai, bj, At, Bt) do { __builtin_amdgcn_s_setprio(1); _Pragma("unroll") for (int m = 0; m < 4; ++m) _Pragma("unroll") for (int n = 0; n < 2; ++n) _Pragma("unroll") for (int k = 0; k < 2; ++k) \
;         acc[ai][bj][m][n] = __builtin_amdgcn_mfma_f32_16x16x32_bf16(Bt[n][k], At[m][k], acc[ai][bj][m][n], 0, 0, 0); __builtin_amdgcn_s_setprio(0); } while (0)
; #define PG8_WAIT_V(n) asm volatile("s_waitcnt vmcnt(" #n ")" ::: "memory")
; #define PG8_WAIT_L(n) asm volatile("s_waitcnt lgkmcnt(" #n ")" ::: "memory")
; #define PG8_BAR __builtin_amdgcn_s_barrier()
; #define PG8_SCHED __builtin_amdgcn_sched_barrier(0)
; template <class Epi, class Sched>
; __device__ __forceinline__ void gemm_phase(int wv, LAS unsigned char* lds, const Gemm g, const Sched& S, const Epi& E) {
;     ...
;             PG8_WAIT_V(8); PG8_WAIT_L(0); PG8_BAR; PG8_MMA(1, 0, At, B0); PG8_MMA(1, 1, At, B1); PG8_BAR; PG8_SCHED;
;             PG8_LDB(B0, 1, 0); PG8_LDB(B1, 1, 1); PG8_SCHED; PG8_LDA(At, 1, 0); PG8_STAGE(PG8_SA(0, 1), a2 + hstep, voffA);
;             PG8_WAIT_V(8); PG8_WAIT_L(0); PG8_BAR; PG8_MMA(0, 0, At, B0); PG8_MMA(0, 1, At, B1); PG8_BAR; PG8_SCHED;
	v_mfma_f32_16x16x32_bf16 v[60:63], v[100:103], v[164:167], v[60:63]
	v_mfma_f32_16x16x32_bf16 v[56:59], v[136:139], v[164:167], v[56:59]
	v_mfma_f32_16x16x32_bf16 v[44:47], v[100:103], v[172:175], v[44:47]
	v_mfma_f32_16x16x32_bf16 v[40:43], v[136:139], v[172:175], v[40:43]
	v_mfma_f32_16x16x32_bf16 v[28:31], v[100:103], v[202:205], v[28:31]
	v_mfma_f32_16x16x32_bf16 v[24:27], v[136:139], v[202:205], v[24:27]
	v_mfma_f32_16x16x32_bf16 v[12:15], v[100:103], v[218:221], v[12:15]
	v_mfma_f32_16x16x32_bf16 v[8:11], v[136:139], v[218:221], v[8:11]
	s_setprio 0
	s_setprio 1
	v_mfma_f32_16x16x32_bf16 v[52:55], v[140:143], v[160:163], v[52:55]
	v_mfma_f32_16x16x32_bf16 v[48:51], v[152:155], v[160:163], v[48:51]
	v_mfma_f32_16x16x32_bf16 v[36:39], v[140:143], v[168:171], v[36:39]
	v_mfma_f32_16x16x32_bf16 v[32:35], v[152:155], v[168:171], v[32:35]
	v_mfma_f32_16x16x32_bf16 v[20:23], v[140:143], v[198:201], v[20:23]
	v_mfma_f32_16x16x32_bf16 v[16:19], v[152:155], v[198:201], v[16:19]
	v_mfma_f32_16x16x32_bf16 v[4:7], v[140:143], v[206:209], v[4:7]
	v_mfma_f32_16x16x32_bf16 v[0:3], v[152:155], v[206:209], v[0:3]
	v_mfma_f32_16x16x32_bf16 v[52:55], v[144:147], v[164:167], v[52:55]
	v_mfma_f32_16x16x32_bf16 v[48:51], v[156:159], v[164:167], v[48:51]
	v_mfma_f32_16x16x32_bf16 v[36:39], v[144:147], v[172:175], v[36:39]
	v_mfma_f32_16x16x32_bf16 v[32:35], v[156:159], v[172:175], v[32:35]
	v_mfma_f32_16x16x32_bf16 v[20:23], v[144:147], v[202:205], v[20:23]
	v_mfma_f32_16x16x32_bf16 v[16:19], v[156:159], v[202:205], v[16:19]
	v_mfma_f32_16x16x32_bf16 v[4:7], v[144:147], v[218:221], v[4:7]
	v_mfma_f32_16x16x32_bf16 v[0:3], v[156:159], v[218:221], v[0:3]
	s_setprio 0
	s_barrier
	s_add_i32 s48, 0, 0x1c000
	v_add_u32_e32 v136, s95, v213
	v_add_u32_e32 v156, s48, v213
	ds_read_b128 v[96:99], v136
	ds_read_b128 v[100:103], v136 offset:1024
	ds_read_b128 v[104:107], v136 offset:2048
	ds_read_b128 v[136:139], v136 offset:3072
	ds_read_b128 v[140:143], v156
	ds_read_b128 v[144:147], v156 offset:1024
	ds_read_b128 v[152:155], v156 offset:2048
	ds_read_b128 v[156:159], v156 offset:3072
	s_add_u32 s22, s26, 0xb0000
	s_addc_u32 s23, s27, 0
	s_mov_b32 m0, s37
	v_lshl_add_u64 v[230:231], s[22:23], 0, v[180:181]
	ds_read_b128 v[160:163], v217 offset:32768
	ds_read_b128 v[164:167], v217 offset:33792
	ds_read_b128 v[168:171], v217 offset:34816
	ds_read_b128 v[172:175], v217 offset:35840
	ds_read_b128 v[198:201], v217 offset:36864
	ds_read_b128 v[202:205], v217 offset:37888
	ds_read_b128 v[206:209], v217 offset:38912
	ds_read_b128 v[218:221], v217 offset:39936
	global_load_lds_dwordx4 v[230:231], off
	v_lshl_add_u64 v[230:231], s[22:23], 0, v[178:179]
	s_mov_b32 m0, s38
	s_nop 0
	global_load_lds_dwordx4 v[230:231], off
	s_waitcnt vmcnt(8)
	s_waitcnt lgkmcnt(0)
	s_setprio 1
	s_waitcnt lgkmcnt(0)
	v_mfma_f32_16x16x32_bf16 v[148:151], v[96:99], v[160:163], v[148:151]
	v_mfma_f32_16x16x32_bf16 v[124:127], v[104:107], v[160:163], v[124:127]
	v_mfma_f32_16x16x32_bf16 v[132:135], v[96:99], v[168:171], v[132:135]
	v_mfma_f32_16x16x32_bf16 v[128:131], v[104:107], v[168:171], v[128:131]
	v_mfma_f32_16x16x32_bf16 v[92:95], v[96:99], v[198:201], v[92:95]
	v_mfma_f32_16x16x32_bf16 v[88:91], v[104:107], v[198:201], v[88:91]
	v_mfma_f32_16x16x32_bf16 v[76:79], v[96:99], v[206:209], v[76:79]
	v_mfma_f32_16x16x32_bf16 v[72:75], v[104:107], v[206:209], v[72:75]
	s_barrier
	v_mfma_f32_16x16x32_bf16 v[148:151], v[100:103], v[164:167], v[148:151]
	v_mfma_f32_16x16x32_bf16 v[124:127], v[136:139], v[164:167], v[124:127]
	v_mfma_f32_16x16x32_bf16 v[132:135], v[100:103], v[172:175], v[132:135]
	v_mfma_f32_16x16x32_bf16 v[128:131], v[136:139], v[172:175], v[128:131]
	v_mfma_f32_16x16x32_bf16 v[92:95], v[100:103], v[202:205], v[92:95]
	v_mfma_f32_16x16x32_bf16 v[88:91], v[136:139], v[202:205], v[88:91]
	v_mfma_f32_16x16x32_bf16 v[76:79], v[100:103], v[218:221], v[76:79]
	v_mfma_f32_16x16x32_bf16 v[72:75], v[136:139], v[218:221], v[72:75]
	s_setprio 0
	s_setprio 1
	v_mfma_f32_16x16x32_bf16 v[116:119], v[140:143], v[160:163], v[116:119]
	v_mfma_f32_16x16x32_bf16 v[108:111], v[152:155], v[160:163], v[108:111]
	v_mfma_f32_16x16x32_bf16 v[120:123], v[140:143], v[168:171], v[120:123]
	v_mfma_f32_16x16x32_bf16 v[112:115], v[152:155], v[168:171], v[112:115]
	v_mfma_f32_16x16x32_bf16 v[84:87], v[140:143], v[198:201], v[84:87]
	v_mfma_f32_16x16x32_bf16 v[80:83], v[152:155], v[198:201], v[80:83]
	v_mfma_f32_16x16x32_bf16 v[68:71], v[140:143], v[206:209], v[68:71]
	v_mfma_f32_16x16x32_bf16 v[64:67], v[152:155], v[206:209], v[64:67]
	v_mfma_f32_16x16x32_bf16 v[116:119], v[144:147], v[164:167], v[116:119]
	v_mfma_f32_16x16x32_bf16 v[108:111], v[156:159], v[164:167], v[108:111]
	v_mfma_f32_16x16x32_bf16 v[120:123], v[144:147], v[172:175], v[120:123]
	v_mfma_f32_16x16x32_bf16 v[112:115], v[156:159], v[172:175], v[112:115]
	v_mfma_f32_16x16x32_bf16 v[84:87], v[144:147], v[202:205], v[84:87]
	v_mfma_f32_16x16x32_bf16 v[80:83], v[156:159], v[202:205], v[80:83]
	v_mfma_f32_16x16x32_bf16 v[68:71], v[144:147], v[218:221], v[68:71]
	v_mfma_f32_16x16x32_bf16 v[64:67], v[156:159], v[218:221], v[64:67]
	s_setprio 0
	s_barrier
; #define PG8_STAGE(bufoff, gbase, voff) do { _Pragma("unroll") for (int _i = 0; _i < 2; ++_i) \
;         __builtin_amdgcn_global_load_lds((const unsigned*)((const char*)(gbase) + (voff)[_i]), (LAS unsigned*)(lds + (bufoff) + ldsw + _i * 8192), 16, 0, 0); } while (0)
; #define PG8_LDA(dst, b, h) do { _Pragma("unroll") for (int m = 0; m < 4; ++m) _Pragma("unroll") for (int k = 0; k < 2; ++k) dst[m][k] = *(const LAS bf16x8*)(lds + PG8_SA(b, h) + aoff + m * 2048 + k * 1024); } while (0)
; #define PG8_MMA(ai, bj, At, Bt) do { __builtin_amdgcn_s_setprio(1); _Pragma("unroll") for (int m = 0; m < 4; ++m) _Pragma("unroll") for (int n = 0; n < 2; ++n) _Pragma("unroll") for (int k = 0; k < 2; ++k) \
;         acc[ai][bj][m][n] = __builtin_amdgcn_mfma_f32_16x16x32_bf16(Bt[n][k], At[m][k], acc[ai][bj][m][n], 0, 0, 0); __builtin_amdgcn_s_setprio(0); } while (0)
; #define PG8_WAIT_V(n) asm volatile("s_waitcnt vmcnt(" #n ")" ::: "memory")
; #define PG8_WAIT_L(n) asm volatile("s_waitcnt lgkmcnt(" #n ")" ::: "memory")
; #define PG8_BAR __builtin_amdgcn_s_barrier()
; #define PG8_SCHED __builtin_amdgcn_sched_barrier(0)
; template <class Epi, class Sched>
; __device__ __forceinline__ void gemm_phase(int wv, LAS unsigned char* lds, const Gemm g, const Sched& S, const Epi& E) {
;     ...
;             PG8_LDA(At, 1, 1); PG8_STAGE(PG8_SB(1, 0), b3, voffB); PG8_STAGE(PG8_SB(1, 1), b3 + hstepB, voffB); PG8_STAGE(PG8_SA(1, 0), a3, voffA);
;             PG8_WAIT_V(8); PG8_WAIT_L(0); PG8_BAR; PG8_MMA(1, 0, At, B0); PG8_MMA(1, 1, At, B1); PG8_BAR; PG8_SCHED;
;         }
;         if (wr == 0) PG8_BAR;
	s_add_i32 s22, s95, s34
	v_lshl_add_u64 v[186:187], v[186:187], 0, s[74:75]
	s_mov_b32 m0, s22
	ds_read_b128 v[160:163], v217 offset:49152
	ds_read_b128 v[164:167], v217 offset:50176
	ds_read_b128 v[168:171], v217 offset:51200
	ds_read_b128 v[172:175], v217 offset:52224
	ds_read_b128 v[198:201], v217 offset:53248
	ds_read_b128 v[202:205], v217 offset:54272
	ds_read_b128 v[206:209], v217 offset:55296
	ds_read_b128 v[218:221], v217 offset:56320
	global_load_lds_dwordx4 v[186:187], off
	s_add_i32 m0, s22, 0x2000
	s_add_u32 s22, s24, 0xb080
	v_lshl_add_u64 v[186:187], v[210:211], 0, s[74:75]
	s_addc_u32 s23, s25, 0
	s_add_i32 s24, s48, s34
	global_load_lds_dwordx4 v[186:187], off
	v_lshl_add_u64 v[186:187], s[22:23], 0, v[188:189]
	s_mov_b32 m0, s24
	s_nop 0
	global_load_lds_dwordx4 v[186:187], off
	v_lshl_add_u64 v[186:187], s[22:23], 0, v[176:177]
	s_add_i32 m0, s24, 0x2000
	s_nop 0
	global_load_lds_dwordx4 v[186:187], off
	v_lshl_add_u64 v[186:187], v[222:223], 0, s[74:75]
	s_mov_b32 m0, s39
	s_nop 0
	global_load_lds_dwordx4 v[186:187], off
	v_lshl_add_u64 v[186:187], v[228:229], 0, s[74:75]
	s_mov_b32 m0, s40
	s_nop 0
	global_load_lds_dwordx4 v[186:187], off
	s_waitcnt vmcnt(8)
	s_waitcnt lgkmcnt(0)
	s_setprio 1
	s_waitcnt lgkmcnt(0)
	v_mfma_f32_16x16x32_bf16 v[60:63], v[96:99], v[160:163], v[60:63]
	v_mfma_f32_16x16x32_bf16 v[56:59], v[104:107], v[160:163], v[56:59]
	v_mfma_f32_16x16x32_bf16 v[44:47], v[96:99], v[168:171], v[44:47]
	v_mfma_f32_16x16x32_bf16 v[40:43], v[104:107], v[168:171], v[40:43]
	v_mfma_f32_16x16x32_bf16 v[28:31], v[96:99], v[198:201], v[28:31]
	v_mfma_f32_16x16x32_bf16 v[24:27], v[104:107], v[198:201], v[24:27]
	v_mfma_f32_16x16x32_bf16 v[12:15], v[96:99], v[206:209], v[12:15]
	v_mfma_f32_16x16x32_bf16 v[8:11], v[104:107], v[206:209], v[8:11]
	s_barrier
	v_mfma_f32_16x16x32_bf16 v[60:63], v[100:103], v[164:167], v[60:63]
	v_mfma_f32_16x16x32_bf16 v[56:59], v[136:139], v[164:167], v[56:59]
	v_mfma_f32_16x16x32_bf16 v[44:47], v[100:103], v[172:175], v[44:47]
	v_mfma_f32_16x16x32_bf16 v[40:43], v[136:139], v[172:175], v[40:43]
	v_mfma_f32_16x16x32_bf16 v[28:31], v[100:103], v[202:205], v[28:31]
	v_mfma_f32_16x16x32_bf16 v[24:27], v[136:139], v[202:205], v[24:27]
	v_mfma_f32_16x16x32_bf16 v[12:15], v[100:103], v[218:221], v[12:15]
	v_mfma_f32_16x16x32_bf16 v[8:11], v[136:139], v[218:221], v[8:11]
	s_setprio 0
	s_setprio 1
	v_mfma_f32_16x16x32_bf16 v[52:55], v[140:143], v[160:163], v[52:55]
	v_mfma_f32_16x16x32_bf16 v[48:51], v[152:155], v[160:163], v[48:51]
	v_mfma_f32_16x16x32_bf16 v[36:39], v[140:143], v[168:171], v[36:39]
	v_mfma_f32_16x16x32_bf16 v[32:35], v[152:155], v[168:171], v[32:35]
	v_mfma_f32_16x16x32_bf16 v[20:23], v[140:143], v[198:201], v[20:23]
	v_mfma_f32_16x16x32_bf16 v[16:19], v[152:155], v[198:201], v[16:19]
	v_mfma_f32_16x16x32_bf16 v[4:7], v[140:143], v[206:209], v[4:7]
	v_mfma_f32_16x16x32_bf16 v[0:3], v[152:155], v[206:209], v[0:3]
	v_mfma_f32_16x16x32_bf16 v[52:55], v[144:147], v[164:167], v[52:55]
	v_mfma_f32_16x16x32_bf16 v[48:51], v[156:159], v[164:167], v[48:51]
	v_mfma_f32_16x16x32_bf16 v[36:39], v[144:147], v[172:175], v[36:39]
	v_mfma_f32_16x16x32_bf16 v[32:35], v[156:159], v[172:175], v[32:35]
	v_mfma_f32_16x16x32_bf16 v[20:23], v[144:147], v[202:205], v[20:23]
	v_mfma_f32_16x16x32_bf16 v[16:19], v[156:159], v[202:205], v[16:19]
	v_mfma_f32_16x16x32_bf16 v[4:7], v[144:147], v[218:221], v[4:7]
	v_mfma_f32_16x16x32_bf16 v[0:3], v[156:159], v[218:221], v[0:3]
	s_setprio 0
	s_barrier
	s_add_i32 s47, s47, 2
	s_add_u32 s45, s45, 0x100
	s_addc_u32 s46, s46, 0
	s_cmp_gt_u32 s47, 41
	s_mov_b64 s[22:23], s[4:5]
	s_cbranch_scc0 .LBB0_1055
	s_and_b64 vcc, exec, s[16:17]
	s_cbranch_vccz .LBB0_1058
	s_barrier
